# conversion items: LDS->bf16 output stage with up to 8 read pairs in flight instead of 16 serial read/wait steps; the eight conversion stores that sat in front of the tail loop headers are write-throug
# speedup vs baseline: 1.0038x; 1.0038x over previous
; #define LAS __attribute__((address_space(3)))
; __device__ __forceinline__ unsigned pk2(float lo, float hi) { return pg8::cvt_pk_bf16(lo, hi); }
; __device__ __forceinline__ void transpose_item(const float* W, int N, bf16* WT, int K, int k0, int n0, int drow0, const float* gk, LAS float* scr, int lane) {
;     ...
;     const int c = lane & 7;
; #pragma unroll
;     for (int j = 0; j < 4; ++j) { const int n = (lane >> 3) + 8 * j; const LAS float* s = scr + (8 * c) * 33 + n;
;         u32x4 o; o.x = pk2(s[0 * 33], s[1 * 33]); o.y = pk2(s[2 * 33], s[3 * 33]); o.z = pk2(s[4 * 33], s[5 * 33]); o.w = pk2(s[6 * 33], s[7 * 33]);
;         *(u32x4*)(WT + (size_t)(drow0 + n) * K + k0 + 8 * c) = o; }
.LBB0_8:
	s_lshl_b32 s4, s22, 6
	s_and_b32 s22, s4, 0xffffff00
	s_and_b64 s[4:5], s[24:25], exec
	s_cselect_b32 s24, 0x80, 0
	s_and_b32 s25, s28, 0x60
	s_or_b32 s22, s22, s24
	ds_write2_b32 v16, v14, v15 offset0:140 offset1:206
	s_lshl_b64 s[4:5], s[26:27], 1
	s_or_b32 s22, s22, s25
	s_waitcnt lgkmcnt(0)
	s_add_u32 s4, s84, s4
	v_or_b32_e32 v18, s22, v30
	s_waitcnt vmcnt(0)
	ds_read2_b32 v[12:13], v31 offset1:33
	ds_read2_b32 v[204:205], v31 offset0:66 offset1:99
	ds_read2_b32 v[206:207], v31 offset0:132 offset1:165
	ds_read2_b32 v[208:209], v31 offset0:198 offset1:231
	ds_read2_b32 v[210:211], v31 offset0:8 offset1:41
	ds_read2_b32 v[212:213], v31 offset0:74 offset1:107
	ds_read2_b32 v[214:215], v31 offset0:140 offset1:173
	ds_read2_b32 v[216:217], v31 offset0:206 offset1:239
	v_mov_b32_e32 v11, v7
	s_addc_u32 s5, s83, s5
	v_ashrrev_i32_e32 v19, 31, v18
	s_waitcnt lgkmcnt(7)
	v_cvt_pk_bf16_f32 v12, v12, v13
	ds_read2_b32 v[218:219], v31 offset0:16 offset1:49
	v_lshl_add_u64 v[20:21], s[4:5], 0, v[10:11]
	v_lshlrev_b64 v[18:19], 11, v[18:19]
	s_waitcnt lgkmcnt(7)
	v_cvt_pk_bf16_f32 v13, v204, v205
	ds_read2_b32 v[204:205], v31 offset0:82 offset1:115
	v_lshl_add_u64 v[18:19], v[20:21], 0, v[18:19]
	s_waitcnt lgkmcnt(7)
	v_cvt_pk_bf16_f32 v14, v206, v207
	ds_read2_b32 v[206:207], v31 offset0:148 offset1:181
	s_waitcnt lgkmcnt(7)
	v_cvt_pk_bf16_f32 v15, v208, v209
	ds_read2_b32 v[208:209], v31 offset0:214 offset1:247
	global_store_dwordx4 v[18:19], v[12:15], off sc1
	v_or_b32_e32 v18, s22, v32
	v_ashrrev_i32_e32 v19, 31, v18
	s_waitcnt lgkmcnt(7)
	v_cvt_pk_bf16_f32 v12, v210, v211
	ds_read2_b32 v[210:211], v31 offset0:24 offset1:57
	v_lshlrev_b64 v[18:19], 11, v[18:19]
	s_waitcnt lgkmcnt(7)
	v_cvt_pk_bf16_f32 v13, v212, v213
	ds_read2_b32 v[212:213], v31 offset0:90 offset1:123
	v_lshl_add_u64 v[18:19], v[20:21], 0, v[18:19]
	s_waitcnt lgkmcnt(7)
	v_cvt_pk_bf16_f32 v14, v214, v215
	ds_read2_b32 v[214:215], v31 offset0:156 offset1:189
	s_waitcnt lgkmcnt(7)
	v_cvt_pk_bf16_f32 v15, v216, v217
	ds_read2_b32 v[216:217], v31 offset0:222 offset1:255
	global_store_dwordx4 v[18:19], v[12:15], off sc1
	v_or_b32_e32 v18, s22, v33
	s_waitcnt lgkmcnt(7)
	v_cvt_pk_bf16_f32 v12, v218, v219
	v_ashrrev_i32_e32 v19, 31, v18
	s_waitcnt lgkmcnt(6)
	v_cvt_pk_bf16_f32 v13, v204, v205
	v_lshlrev_b64 v[18:19], 11, v[18:19]
	s_waitcnt lgkmcnt(5)
	v_cvt_pk_bf16_f32 v14, v206, v207
	s_waitcnt lgkmcnt(4)
	v_cvt_pk_bf16_f32 v15, v208, v209
	v_lshl_add_u64 v[18:19], v[20:21], 0, v[18:19]
	global_store_dwordx4 v[18:19], v[12:15], off sc1
	v_or_b32_e32 v18, s22, v34
	v_ashrrev_i32_e32 v19, 31, v18
	s_waitcnt lgkmcnt(3)
	v_cvt_pk_bf16_f32 v12, v210, v211
	s_waitcnt lgkmcnt(2)
	v_cvt_pk_bf16_f32 v13, v212, v213
	s_waitcnt lgkmcnt(1)
	v_cvt_pk_bf16_f32 v14, v214, v215
	v_lshlrev_b64 v[18:19], 11, v[18:19]
	s_waitcnt lgkmcnt(0)
	v_cvt_pk_bf16_f32 v15, v216, v217
	v_lshl_add_u64 v[16:17], v[20:21], 0, v[18:19]
	global_store_dwordx4 v[16:17], v[12:15], off sc1
	s_waitcnt lgkmcnt(0)

; #define LAS __attribute__((address_space(3)))
; __device__ __forceinline__ unsigned pk2(float lo, float hi) { return pg8::cvt_pk_bf16(lo, hi); }
; __device__ __forceinline__ void lds_wait() { asm volatile("s_waitcnt lgkmcnt(0)" ::: "memory"); }
; __device__ __forceinline__ void transpose_item(const float* W, int N, bf16* WT, int K, int k0, int n0, int drow0, const float* gk, LAS float* scr, int lane) {
;     float wv[32];
; #pragma unroll
;     for (int i = 0; i < 32; ++i) wv[i] = W[(size_t)(k0 + 2 * i + (lane >> 5)) * N + n0 + (lane & 31)];
; #pragma unroll
;     for (int i = 0; i < 32; ++i) { const int kk = 2 * i + (lane >> 5); float v = wv[i]; if (gk) v *= gk[kk]; scr[kk * 33 + (lane & 31)] = v; }
;     lds_wait();
;     const int c = lane & 7;
; #pragma unroll
;     for (int j = 0; j < 4; ++j) { const int n = (lane >> 3) + 8 * j; const LAS float* s = scr + (8 * c) * 33 + n;
;         u32x4 o; o.x = pk2(s[0 * 33], s[1 * 33]); o.y = pk2(s[2 * 33], s[3 * 33]); o.z = pk2(s[4 * 33], s[5 * 33]); o.w = pk2(s[6 * 33], s[7 * 33]);
;         *(u32x4*)(WT + (size_t)(drow0 + n) * K + k0 + 8 * c) = o; }
; __device__ __forceinline__ void p0_weight_item(const Args& a, int l, int r, LAS float* scr, int lane) {
;     ...
;     if (r < IT_OUT) {
;         const int kb = r / 32, nb = r % 32, k0 = 64 * kb;
;         const float* gk = (k0 < 256) ? a.in[17] + (size_t)l * 256 + k0 : (k0 < 768 ? a.in[18] + (size_t)l * 512 + (k0 - 256) : a.in[26] + (size_t)l * 256 + (k0 - 768));
;         transpose_item(a.in[27] + (size_t)l * DM * DM, DM, (bf16*)(wl + WL_WOUT), DM, k0, 32 * nb, 32 * nb, gk, scr, lane); return; }
;     r -= IT_OUT;
;     if (r < IT_GLU) { const int kb = r / 8, nb = r % 8; transpose_item(a.in[15] + (size_t)l * 65536, 256, (bf16*)(wl + WL_GLU), 256, 64 * kb, 32 * nb, 32 * nb, nullptr, scr, lane); return; }
;     r -= IT_GLU;
;     if (r < IT_LW) { const int blk = r >> 1, nb = r & 1; transpose_item(a.in[21] + (size_t)l * 16384 + blk * 4096, 64, (bf16*)(wl + WL_WA) + blk * 4096, 64, 0, 32 * nb, 32 * nb, nullptr, scr, lane); return; }
;     r -= IT_LW;
;     { const int blk = r >> 1, nb = r & 1; transpose_item(a.in[23] + (size_t)l * 16384 + blk * 4096, 64, (bf16*)(wl + WL_WX) + blk * 4096, 64, 0, 32 * nb, 32 * nb, nullptr, scr, lane); }
.LBB0_10:
	s_mul_hi_i32 s4, s82, 0x3255ba01
	s_lshr_b32 s5, s4, 31
	s_ashr_i32 s4, s4, 11
	s_add_i32 s26, s4, s5
	s_mul_i32 s4, s26, 0xffffd750
	s_add_i32 s88, s82, s4
	s_ashr_i32 s27, s26, 31
	s_mul_i32 s5, s26, 0x2b00000
	s_mul_hi_i32 s4, s26, 0x2b00000
	s_add_u32 s84, s33, s5
	s_addc_u32 s83, s42, s4
	s_lshl_b64 s[24:25], s[26:27], 12
	s_mul_i32 s87, s26, 0x28b0
	s_mul_hi_i32 s85, s26, 0xb00000
	s_mul_i32 s86, s26, 0xb00000
	s_cmpk_gt_i32 s88, 0xaff
	s_mov_b64 s[4:5], -1
	s_cbranch_scc0 .LBB0_122
	s_cmpk_gt_u32 s88, 0x107f
	s_cbranch_scc0 .LBB0_119
	s_cmpk_gt_u32 s88, 0x1b7f
	s_cbranch_scc0 .LBB0_92
	s_add_i32 s4, s88, 0xffffef80
	s_cmpk_lt_u32 s4, 0x1080
	s_mov_b64 s[4:5], -1
	s_cbranch_scc1 .LBB0_89
	s_add_i32 s34, s88, 0xffffdf00
	s_cmpk_gt_u32 s88, 0x267f
	s_cbranch_scc0 .LBB0_60
	s_cmpk_gt_u32 s34, 0x77f
	s_cbranch_scc0 .LBB0_25
	s_cmpk_gt_u32 s34, 0x79f
	s_cbranch_scc0 .LBB0_22
	s_mul_i32 s22, s26, 0xfeba8000
	s_add_i32 s31, s47, s22
	s_add_i32 s22, s43, 0xfffbe000
	s_lshl_b64 s[4:5], s[26:27], 16
	s_and_b32 s30, s22, 32
	s_cmpk_gt_u32 s34, 0x7a7
	s_mov_b64 s[28:29], -1
	v_or_b32_e32 v15, s30, v30
	v_or_b32_e32 v14, s30, v32
	v_or_b32_e32 v13, s30, v33
	v_or_b32_e32 v12, s30, v34
	s_cbranch_scc0 .LBB0_19
	v_readlane_b32 s52, v250, 43
	v_readlane_b32 s66, v250, 57
	v_readlane_b32 s67, v250, 58
	s_add_u32 s35, s66, s4
	s_addc_u32 s38, s67, s5
	s_and_b32 s22, s31, 0x7ffff000
	s_add_i32 s16, s22, 0xffc2c000
	s_lshl_b64 s[28:29], s[16:17], 2
	s_add_u32 s35, s35, s28
	s_addc_u32 s39, s38, s29
	s_lshl_b64 s[28:29], s[16:17], 1
	s_add_u32 s28, s84, s28
	s_addc_u32 s29, s83, s29
	s_lshl_b32 s22, s30, 2
	s_add_u32 s38, s35, s22
	s_addc_u32 s39, s39, 0
	v_lshl_add_u64 v[16:17], s[38:39], 0, v[6:7]
	v_mov_b32_e32 v9, v7
	v_lshl_add_u64 v[16:17], v[16:17], 0, v[8:9]
	v_add_co_u32_e32 v18, vcc, s14, v16
	global_load_dword v9, v[16:17], off nt
	global_load_dword v11, v[16:17], off offset:512 nt
	global_load_dword v22, v[16:17], off offset:1024 nt
	global_load_dword v23, v[16:17], off offset:1536 nt
	global_load_dword v24, v[16:17], off offset:2048 nt
	global_load_dword v25, v[16:17], off offset:2560 nt
	global_load_dword v26, v[16:17], off offset:3072 nt
	global_load_dword v27, v[16:17], off offset:3584 nt
	v_addc_co_u32_e32 v19, vcc, 0, v17, vcc
	v_add_co_u32_e32 v20, vcc, s91, v16
	v_readlane_b32 s53, v250, 44
	s_nop 0
	v_addc_co_u32_e32 v21, vcc, 0, v17, vcc
	v_add_co_u32_e32 v16, vcc, s92, v16
	global_load_dword v28, v[20:21], off offset:-4096 nt
	global_load_dword v29, v[20:21], off nt
	global_load_dword v55, v[20:21], off offset:512 nt
	global_load_dword v56, v[20:21], off offset:1024 nt
	global_load_dword v57, v[20:21], off offset:1536 nt
	global_load_dword v58, v[20:21], off offset:2048 nt
	global_load_dword v59, v[20:21], off offset:2560 nt
	global_load_dword v60, v[20:21], off offset:3072 nt
	s_nop 0
	global_load_dword v20, v[20:21], off offset:3584 nt
	v_addc_co_u32_e32 v17, vcc, 0, v17, vcc
	global_load_dword v21, v[18:19], off offset:512 nt
	global_load_dword v61, v[18:19], off offset:1024 nt
	global_load_dword v62, v[18:19], off offset:1536 nt
	global_load_dword v63, v[18:19], off offset:2048 nt
	global_load_dword v64, v[18:19], off offset:2560 nt
	global_load_dword v65, v[18:19], off offset:3072 nt
	s_nop 0
	global_load_dword v18, v[18:19], off offset:3584 nt
	s_nop 0
	global_load_dword v19, v[16:17], off nt
	global_load_dword v66, v[16:17], off offset:512 nt
	global_load_dword v67, v[16:17], off offset:1024 nt
	global_load_dword v68, v[16:17], off offset:1536 nt
	global_load_dword v69, v[16:17], off offset:2048 nt
	global_load_dword v70, v[16:17], off offset:2560 nt
	global_load_dword v71, v[16:17], off offset:3072 nt
	s_nop 0
	global_load_dword v16, v[16:17], off offset:3584 nt
	v_readlane_b32 s54, v250, 45
	v_readlane_b32 s55, v250, 46
	v_readlane_b32 s56, v250, 47
	v_readlane_b32 s57, v250, 48
	v_readlane_b32 s58, v250, 49
	v_readlane_b32 s59, v250, 50
	v_readlane_b32 s60, v250, 51
	v_readlane_b32 s61, v250, 52
	v_readlane_b32 s62, v250, 53
	v_readlane_b32 s63, v250, 54
	v_readlane_b32 s64, v250, 55
	v_readlane_b32 s65, v250, 56
	s_waitcnt vmcnt(30)
	ds_write2_b32 v5, v9, v11 offset1:66
	s_waitcnt vmcnt(28)
	ds_write2_b32 v5, v22, v23 offset0:132 offset1:198
	s_waitcnt vmcnt(26)
	ds_write2_b32 v48, v24, v25 offset0:8 offset1:74
	s_waitcnt vmcnt(24)
	ds_write2_b32 v48, v26, v27 offset0:140 offset1:206
	s_waitcnt vmcnt(14)
	ds_write2_b32 v49, v28, v21 offset0:16 offset1:82
	s_waitcnt vmcnt(12)
	ds_write2_b32 v49, v61, v62 offset0:148 offset1:214
	s_waitcnt vmcnt(10)
	ds_write2_b32 v50, v63, v64 offset0:24 offset1:90
	s_waitcnt vmcnt(8)
	ds_write2_b32 v50, v65, v18 offset0:156 offset1:222
	ds_write2_b32 v51, v29, v55 offset0:32 offset1:98
	ds_write2_b32 v51, v56, v57 offset0:164 offset1:230
	ds_write2_b32 v52, v58, v59 offset0:40 offset1:106
	ds_write2_b32 v52, v60, v20 offset0:172 offset1:238
	s_waitcnt vmcnt(6)
	ds_write2_b32 v53, v19, v66 offset0:48 offset1:114
	s_waitcnt vmcnt(4)
	ds_write2_b32 v53, v67, v68 offset0:180 offset1:246
	s_waitcnt vmcnt(2)
	ds_write2_b32 v54, v69, v70 offset0:56 offset1:122
	s_waitcnt vmcnt(0)
	ds_write2_b32 v54, v71, v16 offset0:188 offset1:254
	s_waitcnt lgkmcnt(0)
	ds_read2_b32 v[16:17], v31 offset1:33
	ds_read2_b32 v[204:205], v31 offset0:66 offset1:99
	ds_read2_b32 v[206:207], v31 offset0:132 offset1:165
	ds_read2_b32 v[208:209], v31 offset0:198 offset1:231
	ds_read2_b32 v[210:211], v31 offset0:8 offset1:41
	ds_read2_b32 v[212:213], v31 offset0:74 offset1:107
	ds_read2_b32 v[214:215], v31 offset0:140 offset1:173
	ds_read2_b32 v[216:217], v31 offset0:206 offset1:239
	v_mov_b32_e32 v11, v7
	s_waitcnt lgkmcnt(7)
; #define LAS __attribute__((address_space(3)))
; __device__ __forceinline__ unsigned pk2(float lo, float hi) { return pg8::cvt_pk_bf16(lo, hi); }
; __device__ __forceinline__ void transpose_item(const float* W, int N, bf16* WT, int K, int k0, int n0, int drow0, const float* gk, LAS float* scr, int lane) {
;     ...
;     for (int j = 0; j < 4; ++j) { const int n = (lane >> 3) + 8 * j; const LAS float* s = scr + (8 * c) * 33 + n;
;         u32x4 o; o.x = pk2(s[0 * 33], s[1 * 33]); o.y = pk2(s[2 * 33], s[3 * 33]); o.z = pk2(s[4 * 33], s[5 * 33]); o.w = pk2(s[6 * 33], s[7 * 33]);
;         *(u32x4*)(WT + (size_t)(drow0 + n) * K + k0 + 8 * c) = o; }
	v_cvt_pk_bf16_f32 v16, v16, v17
	ds_read2_b32 v[218:219], v31 offset0:16 offset1:49
	v_lshl_add_u64 v[24:25], s[28:29], 0, v[10:11]
	s_mov_b64 s[28:29], 0x28a8000
	s_waitcnt lgkmcnt(7)
	v_cvt_pk_bf16_f32 v17, v204, v205
	ds_read2_b32 v[204:205], v31 offset0:82 offset1:115
	v_lshlrev_b32_e32 v22, 7, v15
	v_mov_b32_e32 v23, v7
	v_lshl_add_u64 v[24:25], v[24:25], 0, s[28:29]
	s_waitcnt lgkmcnt(7)
	v_cvt_pk_bf16_f32 v18, v206, v207
	ds_read2_b32 v[206:207], v31 offset0:148 offset1:181
	s_waitcnt lgkmcnt(7)
	v_cvt_pk_bf16_f32 v19, v208, v209
	ds_read2_b32 v[208:209], v31 offset0:214 offset1:247
	v_lshl_add_u64 v[22:23], v[24:25], 0, v[22:23]
	global_store_dwordx4 v[22:23], v[16:19], off sc1
	v_lshlrev_b32_e32 v22, 7, v14
	v_mov_b32_e32 v23, v7
	s_waitcnt lgkmcnt(7)
	v_cvt_pk_bf16_f32 v16, v210, v211
	ds_read2_b32 v[210:211], v31 offset0:24 offset1:57
	s_waitcnt lgkmcnt(7)
	v_cvt_pk_bf16_f32 v17, v212, v213
	ds_read2_b32 v[212:213], v31 offset0:90 offset1:123
	s_waitcnt lgkmcnt(7)
	v_cvt_pk_bf16_f32 v18, v214, v215
	ds_read2_b32 v[214:215], v31 offset0:156 offset1:189
	s_waitcnt lgkmcnt(7)
	v_cvt_pk_bf16_f32 v19, v216, v217
	ds_read2_b32 v[216:217], v31 offset0:222 offset1:255
	v_lshl_add_u64 v[22:23], v[24:25], 0, v[22:23]
	global_store_dwordx4 v[22:23], v[16:19], off sc1
	v_lshlrev_b32_e32 v22, 7, v13
	v_mov_b32_e32 v23, v7
	s_waitcnt lgkmcnt(7)
	v_cvt_pk_bf16_f32 v16, v218, v219
	s_waitcnt lgkmcnt(6)
	v_cvt_pk_bf16_f32 v17, v204, v205
	s_waitcnt lgkmcnt(5)
	v_cvt_pk_bf16_f32 v18, v206, v207
	s_waitcnt lgkmcnt(4)
	v_cvt_pk_bf16_f32 v19, v208, v209
	v_lshl_add_u64 v[22:23], v[24:25], 0, v[22:23]
	global_store_dwordx4 v[22:23], v[16:19], off sc1
	v_lshlrev_b32_e32 v22, 7, v12
	v_mov_b32_e32 v23, v7
	s_waitcnt lgkmcnt(3)
	v_cvt_pk_bf16_f32 v16, v210, v211
	s_waitcnt lgkmcnt(2)
	v_cvt_pk_bf16_f32 v17, v212, v213
	s_waitcnt lgkmcnt(1)
	v_cvt_pk_bf16_f32 v18, v214, v215
	s_waitcnt lgkmcnt(0)
	v_cvt_pk_bf16_f32 v19, v216, v217
	v_lshl_add_u64 v[20:21], v[24:25], 0, v[22:23]
	global_store_dwordx4 v[20:21], v[16:19], off sc1
	s_waitcnt lgkmcnt(0)
	s_mov_b64 s[28:29], 0
; #define LAS __attribute__((address_space(3)))
; __device__ __forceinline__ unsigned pk2(float lo, float hi) { return pg8::cvt_pk_bf16(lo, hi); }
; __device__ __forceinline__ void lds_wait() { asm volatile("s_waitcnt lgkmcnt(0)" ::: "memory"); }
; __device__ __forceinline__ void transpose_item(const float* W, int N, bf16* WT, int K, int k0, int n0, int drow0, const float* gk, LAS float* scr, int lane) {
;     float wv[32];
; #pragma unroll
;     for (int i = 0; i < 32; ++i) wv[i] = W[(size_t)(k0 + 2 * i + (lane >> 5)) * N + n0 + (lane & 31)];
; #pragma unroll
;     for (int i = 0; i < 32; ++i) { const int kk = 2 * i + (lane >> 5); float v = wv[i]; if (gk) v *= gk[kk]; scr[kk * 33 + (lane & 31)] = v; }
;     lds_wait();
;     const int c = lane & 7;
; #pragma unroll
;     for (int j = 0; j < 4; ++j) { const int n = (lane >> 3) + 8 * j; const LAS float* s = scr + (8 * c) * 33 + n;
;         u32x4 o; o.x = pk2(s[0 * 33], s[1 * 33]); o.y = pk2(s[2 * 33], s[3 * 33]); o.z = pk2(s[4 * 33], s[5 * 33]); o.w = pk2(s[6 * 33], s[7 * 33]);
;         *(u32x4*)(WT + (size_t)(drow0 + n) * K + k0 + 8 * c) = o; }
; __device__ __forceinline__ void p0_weight_item(const Args& a, int l, int r, LAS float* scr, int lane) {
;     ...
;     if (r < IT_LW) { const int blk = r >> 1, nb = r & 1; transpose_item(a.in[21] + (size_t)l * 16384 + blk * 4096, 64, (bf16*)(wl + WL_WA) + blk * 4096, 64, 0, 32 * nb, 32 * nb, nullptr, scr, lane); return; }
;     r -= IT_LW;
;     { const int blk = r >> 1, nb = r & 1; transpose_item(a.in[23] + (size_t)l * 16384 + blk * 4096, 64, (bf16*)(wl + WL_WX) + blk * 4096, 64, 0, 32 * nb, 32 * nb, nullptr, scr, lane); }
.LBB0_19:
	s_andn2_b64 vcc, exec, s[28:29]
	s_cbranch_vccnz .LBB0_21
	v_readlane_b32 s52, v250, 43
	v_readlane_b32 s62, v250, 53
	v_readlane_b32 s63, v250, 54
	s_add_u32 s28, s62, s4
	s_addc_u32 s29, s63, s5
	s_and_b32 s4, s31, 0x3ff000
	s_add_i32 s16, s4, 0xffc30000
	s_lshl_b64 s[4:5], s[16:17], 2
	s_add_u32 s28, s28, s4
	s_addc_u32 s29, s29, s5
	s_lshl_b64 s[4:5], s[16:17], 1
	s_add_u32 s4, s84, s4
	s_addc_u32 s5, s83, s5
	s_lshl_b32 s22, s30, 2
	s_add_u32 s28, s28, s22
	s_addc_u32 s29, s29, 0
	v_lshl_add_u64 v[16:17], s[28:29], 0, v[6:7]
	v_mov_b32_e32 v9, v7
	v_lshl_add_u64 v[16:17], v[16:17], 0, v[8:9]
	v_add_co_u32_e32 v18, vcc, s14, v16
	global_load_dword v9, v[16:17], off nt
	global_load_dword v11, v[16:17], off offset:512 nt
	global_load_dword v22, v[16:17], off offset:1024 nt
	global_load_dword v23, v[16:17], off offset:1536 nt
	global_load_dword v24, v[16:17], off offset:2048 nt
	global_load_dword v25, v[16:17], off offset:2560 nt
	global_load_dword v26, v[16:17], off offset:3072 nt
	global_load_dword v27, v[16:17], off offset:3584 nt
	v_addc_co_u32_e32 v19, vcc, 0, v17, vcc
	v_add_co_u32_e32 v20, vcc, s91, v16
	v_lshlrev_b32_e32 v14, 7, v14
	s_nop 0
	v_addc_co_u32_e32 v21, vcc, 0, v17, vcc
	v_add_co_u32_e32 v16, vcc, s92, v16
	global_load_dword v28, v[20:21], off offset:-4096 nt
	global_load_dword v29, v[20:21], off nt
	global_load_dword v55, v[20:21], off offset:512 nt
	global_load_dword v56, v[20:21], off offset:1024 nt
	global_load_dword v57, v[20:21], off offset:1536 nt
	global_load_dword v58, v[20:21], off offset:2048 nt
	global_load_dword v59, v[20:21], off offset:2560 nt
	global_load_dword v60, v[20:21], off offset:3072 nt
	s_nop 0
	global_load_dword v20, v[20:21], off offset:3584 nt
	v_addc_co_u32_e32 v17, vcc, 0, v17, vcc
	global_load_dword v21, v[18:19], off offset:512 nt
	global_load_dword v61, v[18:19], off offset:1024 nt
	global_load_dword v62, v[18:19], off offset:1536 nt
	global_load_dword v63, v[18:19], off offset:2048 nt
	global_load_dword v64, v[18:19], off offset:2560 nt
	global_load_dword v65, v[18:19], off offset:3072 nt
	s_nop 0
	global_load_dword v18, v[18:19], off offset:3584 nt
	s_nop 0
	global_load_dword v19, v[16:17], off nt
	global_load_dword v66, v[16:17], off offset:512 nt
	global_load_dword v67, v[16:17], off offset:1024 nt
	global_load_dword v68, v[16:17], off offset:1536 nt
	global_load_dword v69, v[16:17], off offset:2048 nt
	global_load_dword v70, v[16:17], off offset:2560 nt
	global_load_dword v71, v[16:17], off offset:3072 nt
	s_nop 0
	global_load_dword v16, v[16:17], off offset:3584 nt
	v_lshlrev_b32_e32 v12, 7, v12
	v_readlane_b32 s53, v250, 44
	v_readlane_b32 s54, v250, 45
	v_readlane_b32 s55, v250, 46
	v_readlane_b32 s56, v250, 47
	v_readlane_b32 s57, v250, 48
	v_readlane_b32 s58, v250, 49
	v_readlane_b32 s59, v250, 50
	v_readlane_b32 s60, v250, 51
	v_readlane_b32 s61, v250, 52
	v_readlane_b32 s64, v250, 55
	v_readlane_b32 s65, v250, 56
	v_readlane_b32 s66, v250, 57
	v_readlane_b32 s67, v250, 58
	s_waitcnt vmcnt(30)
	ds_write2_b32 v5, v9, v11 offset1:66
	s_waitcnt vmcnt(28)
	ds_write2_b32 v5, v22, v23 offset0:132 offset1:198
	s_waitcnt vmcnt(26)
	ds_write2_b32 v48, v24, v25 offset0:8 offset1:74
	s_waitcnt vmcnt(24)
	ds_write2_b32 v48, v26, v27 offset0:140 offset1:206
	s_waitcnt vmcnt(14)
	ds_write2_b32 v49, v28, v21 offset0:16 offset1:82
	s_waitcnt vmcnt(12)
	ds_write2_b32 v49, v61, v62 offset0:148 offset1:214
	s_waitcnt vmcnt(10)
	ds_write2_b32 v50, v63, v64 offset0:24 offset1:90
	s_waitcnt vmcnt(8)
	ds_write2_b32 v50, v65, v18 offset0:156 offset1:222
	ds_write2_b32 v51, v29, v55 offset0:32 offset1:98
	ds_write2_b32 v51, v56, v57 offset0:164 offset1:230
	ds_write2_b32 v52, v58, v59 offset0:40 offset1:106
	ds_write2_b32 v52, v60, v20 offset0:172 offset1:238
	s_waitcnt vmcnt(6)
	ds_write2_b32 v53, v19, v66 offset0:48 offset1:114
	s_waitcnt vmcnt(4)
	ds_write2_b32 v53, v67, v68 offset0:180 offset1:246
	s_waitcnt vmcnt(2)
	ds_write2_b32 v54, v69, v70 offset0:56 offset1:122
	s_waitcnt vmcnt(0)
	ds_write2_b32 v54, v71, v16 offset0:188 offset1:254
	s_waitcnt lgkmcnt(0)
	ds_read2_b32 v[16:17], v31 offset1:33
	ds_read2_b32 v[204:205], v31 offset0:66 offset1:99
	ds_read2_b32 v[206:207], v31 offset0:132 offset1:165
	ds_read2_b32 v[208:209], v31 offset0:198 offset1:231
	ds_read2_b32 v[210:211], v31 offset0:8 offset1:41
	ds_read2_b32 v[212:213], v31 offset0:74 offset1:107
	ds_read2_b32 v[214:215], v31 offset0:140 offset1:173
	ds_read2_b32 v[216:217], v31 offset0:206 offset1:239
	v_mov_b32_e32 v11, v7
	s_waitcnt lgkmcnt(7)
	v_cvt_pk_bf16_f32 v16, v16, v17
	ds_read2_b32 v[218:219], v31 offset0:16 offset1:49
	v_lshl_add_u64 v[24:25], s[4:5], 0, v[10:11]
	s_mov_b64 s[4:5], 0x28a0000
	s_waitcnt lgkmcnt(7)
	v_cvt_pk_bf16_f32 v17, v204, v205
	ds_read2_b32 v[204:205], v31 offset0:82 offset1:115
	v_lshlrev_b32_e32 v22, 7, v15
	v_mov_b32_e32 v23, v7
	v_lshl_add_u64 v[24:25], v[24:25], 0, s[4:5]
	s_waitcnt lgkmcnt(7)
	v_cvt_pk_bf16_f32 v18, v206, v207
	ds_read2_b32 v[206:207], v31 offset0:148 offset1:181
	s_waitcnt lgkmcnt(7)
	v_cvt_pk_bf16_f32 v19, v208, v209
	ds_read2_b32 v[208:209], v31 offset0:214 offset1:247
	v_lshl_add_u64 v[22:23], v[24:25], 0, v[22:23]
	global_store_dwordx4 v[22:23], v[16:19], off sc1
	v_mov_b32_e32 v15, v7
	v_lshl_add_u64 v[14:15], v[24:25], 0, v[14:15]
	s_waitcnt lgkmcnt(7)
	v_cvt_pk_bf16_f32 v16, v210, v211
	ds_read2_b32 v[210:211], v31 offset0:24 offset1:57
	s_waitcnt lgkmcnt(7)
	v_cvt_pk_bf16_f32 v17, v212, v213
	ds_read2_b32 v[212:213], v31 offset0:90 offset1:123
	s_waitcnt lgkmcnt(7)
	v_cvt_pk_bf16_f32 v18, v214, v215
	ds_read2_b32 v[214:215], v31 offset0:156 offset1:189
	s_waitcnt lgkmcnt(7)
	v_cvt_pk_bf16_f32 v19, v216, v217
	global_store_dwordx4 v[14:15], v[16:19], off sc1
	s_waitcnt lgkmcnt(6)
	v_cvt_pk_bf16_f32 v14, v218, v219
	s_waitcnt lgkmcnt(5)
	v_cvt_pk_bf16_f32 v15, v204, v205
	v_lshlrev_b32_e32 v20, 7, v13
	v_mov_b32_e32 v21, v7
	s_waitcnt lgkmcnt(4)
	v_cvt_pk_bf16_f32 v16, v206, v207
	s_waitcnt lgkmcnt(3)
	v_cvt_pk_bf16_f32 v17, v208, v209
	v_lshl_add_u64 v[20:21], v[24:25], 0, v[20:21]
	global_store_dwordx4 v[20:21], v[14:17], off sc1
	v_mov_b32_e32 v13, v7
	v_lshl_add_u64 v[12:13], v[24:25], 0, v[12:13]
	s_waitcnt lgkmcnt(2)
	v_cvt_pk_bf16_f32 v14, v210, v211
	ds_read2_b32 v[18:19], v31 offset0:222 offset1:255
	s_waitcnt lgkmcnt(2)
	v_cvt_pk_bf16_f32 v15, v212, v213
	s_waitcnt lgkmcnt(1)
	v_cvt_pk_bf16_f32 v16, v214, v215
	s_waitcnt lgkmcnt(0)
	v_cvt_pk_bf16_f32 v17, v18, v19
	global_store_dwordx4 v[12:13], v[14:17], off sc1
	s_waitcnt lgkmcnt(0)

; #define LAS __attribute__((address_space(3)))
; __device__ __forceinline__ void transpose_item(const float* W, int N, bf16* WT, int K, int k0, int n0, int drow0, const float* gk, LAS float* scr, int lane) {
;     float wv[32];
; #pragma unroll
;     for (int i = 0; i < 32; ++i) wv[i] = W[(size_t)(k0 + 2 * i + (lane >> 5)) * N + n0 + (lane & 31)];
; #pragma unroll
;     for (int i = 0; i < 32; ++i) { const int kk = 2 * i + (lane >> 5); float v = wv[i]; if (gk) v *= gk[kk]; scr[kk * 33 + (lane & 31)] = v; }
; __device__ __forceinline__ void p0_weight_item(const Args& a, int l, int r, LAS float* scr, int lane) {
;     ...
;     if (r < IT_GLU) { const int kb = r / 8, nb = r % 8; transpose_item(a.in[15] + (size_t)l * 65536, 256, (bf16*)(wl + WL_GLU), 256, 64 * kb, 32 * nb, 32 * nb, nullptr, scr, lane); return; }
.LBB0_22:
	s_andn2_b64 vcc, exec, s[4:5]
	s_cbranch_vccnz .LBB0_24
	v_readlane_b32 s52, v250, 27
	s_lshl_b64 s[4:5], s[26:27], 18
	v_readlane_b32 s66, v250, 41
	v_readlane_b32 s67, v250, 42
	s_add_u32 s28, s66, s4
	s_mul_i32 s4, s26, 0xfffeba80
	s_addc_u32 s5, s67, s5
	s_add_i32 s4, s49, s4
	s_and_b32 s4, s4, 0x3fc0
	s_add_i32 s16, s4, 0xffffc400
	s_add_i32 s4, s43, 0xfffbe000
	s_and_b32 s4, s4, 0xe0
	s_lshl_b32 s29, s4, 2
	v_or_b32_e32 v12, s16, v4
	s_add_u32 s28, s28, s29
	s_addc_u32 s29, s5, 0
	v_mov_b32_e32 v13, v7
	v_or_b32_e32 v18, 2, v12
	v_mov_b32_e32 v19, v7
	v_or_b32_e32 v20, 4, v12
	v_mov_b32_e32 v21, v7
	v_or_b32_e32 v22, 6, v12
	v_mov_b32_e32 v23, v7
	v_or_b32_e32 v24, 8, v12
	v_mov_b32_e32 v25, v7
	v_or_b32_e32 v26, 10, v12
	v_mov_b32_e32 v27, v7
	v_or_b32_e32 v28, 12, v12
	v_mov_b32_e32 v29, v7
	v_or_b32_e32 v56, 14, v12
	v_mov_b32_e32 v57, v7
	v_lshl_add_u64 v[14:15], s[28:29], 0, v[6:7]
	v_lshlrev_b64 v[16:17], 10, v[12:13]
	v_lshlrev_b64 v[18:19], 10, v[18:19]
	v_lshlrev_b64 v[20:21], 10, v[20:21]
	v_lshlrev_b64 v[22:23], 10, v[22:23]
	v_lshlrev_b64 v[24:25], 10, v[24:25]
	v_lshlrev_b64 v[26:27], 10, v[26:27]
	v_lshlrev_b64 v[28:29], 10, v[28:29]
	v_lshlrev_b64 v[56:57], 10, v[56:57]
	v_lshl_add_u64 v[16:17], v[14:15], 0, v[16:17]
	v_lshl_add_u64 v[18:19], v[14:15], 0, v[18:19]
	v_lshl_add_u64 v[20:21], v[14:15], 0, v[20:21]
	v_lshl_add_u64 v[22:23], v[14:15], 0, v[22:23]
	v_lshl_add_u64 v[24:25], v[14:15], 0, v[24:25]
	v_lshl_add_u64 v[26:27], v[14:15], 0, v[26:27]
	v_lshl_add_u64 v[28:29], v[14:15], 0, v[28:29]
	v_lshl_add_u64 v[56:57], v[14:15], 0, v[56:57]
	global_load_dword v9, v[16:17], off nt
	global_load_dword v11, v[18:19], off nt
	global_load_dword v55, v[20:21], off nt
	global_load_dword v58, v[22:23], off nt
	global_load_dword v59, v[24:25], off nt
	global_load_dword v60, v[26:27], off nt
	global_load_dword v61, v[28:29], off nt
	global_load_dword v62, v[56:57], off nt
	v_or_b32_e32 v16, 16, v12
	v_mov_b32_e32 v17, v7
	v_or_b32_e32 v18, 18, v12
	v_mov_b32_e32 v19, v7
	v_or_b32_e32 v20, 20, v12
	v_mov_b32_e32 v21, v7
	v_or_b32_e32 v22, 22, v12
	v_mov_b32_e32 v23, v7
	v_or_b32_e32 v24, 24, v12
	v_mov_b32_e32 v25, v7
	v_or_b32_e32 v26, 26, v12
	v_mov_b32_e32 v27, v7
	v_or_b32_e32 v28, 28, v12
	v_mov_b32_e32 v29, v7
	v_or_b32_e32 v56, 30, v12
	v_mov_b32_e32 v57, v7
	v_lshlrev_b64 v[16:17], 10, v[16:17]
	v_lshlrev_b64 v[18:19], 10, v[18:19]
	v_lshlrev_b64 v[20:21], 10, v[20:21]
	v_lshlrev_b64 v[22:23], 10, v[22:23]
	v_lshlrev_b64 v[24:25], 10, v[24:25]
	v_lshlrev_b64 v[26:27], 10, v[26:27]
	v_lshlrev_b64 v[28:29], 10, v[28:29]
	v_lshlrev_b64 v[56:57], 10, v[56:57]
	v_lshl_add_u64 v[16:17], v[14:15], 0, v[16:17]
	v_lshl_add_u64 v[18:19], v[14:15], 0, v[18:19]
	v_lshl_add_u64 v[20:21], v[14:15], 0, v[20:21]
	v_lshl_add_u64 v[22:23], v[14:15], 0, v[22:23]
	v_lshl_add_u64 v[24:25], v[14:15], 0, v[24:25]
	v_lshl_add_u64 v[26:27], v[14:15], 0, v[26:27]
	v_lshl_add_u64 v[28:29], v[14:15], 0, v[28:29]
	v_lshl_add_u64 v[56:57], v[14:15], 0, v[56:57]
	global_load_dword v63, v[16:17], off nt
	global_load_dword v64, v[18:19], off nt
	global_load_dword v65, v[20:21], off nt
	global_load_dword v66, v[22:23], off nt
	global_load_dword v67, v[24:25], off nt
	global_load_dword v68, v[26:27], off nt
	global_load_dword v69, v[28:29], off nt
	global_load_dword v70, v[56:57], off nt
	v_or_b32_e32 v16, 32, v12
	v_mov_b32_e32 v17, v7
	v_or_b32_e32 v18, 34, v12
	v_mov_b32_e32 v19, v7
	v_or_b32_e32 v20, 36, v12
	v_mov_b32_e32 v21, v7
	v_or_b32_e32 v22, 38, v12
	v_mov_b32_e32 v23, v7
	v_or_b32_e32 v24, 40, v12
	v_mov_b32_e32 v25, v7
	v_or_b32_e32 v26, 42, v12
	v_mov_b32_e32 v27, v7
	v_or_b32_e32 v28, 44, v12
	v_mov_b32_e32 v29, v7
	v_or_b32_e32 v56, 46, v12
	v_mov_b32_e32 v57, v7
	v_lshlrev_b64 v[16:17], 10, v[16:17]
	v_lshlrev_b64 v[18:19], 10, v[18:19]
	v_lshlrev_b64 v[20:21], 10, v[20:21]
	v_lshlrev_b64 v[22:23], 10, v[22:23]
	v_lshlrev_b64 v[24:25], 10, v[24:25]
	v_lshlrev_b64 v[26:27], 10, v[26:27]
	v_lshlrev_b64 v[28:29], 10, v[28:29]
	v_lshlrev_b64 v[56:57], 10, v[56:57]
	v_lshl_add_u64 v[16:17], v[14:15], 0, v[16:17]
	v_lshl_add_u64 v[18:19], v[14:15], 0, v[18:19]
	v_lshl_add_u64 v[20:21], v[14:15], 0, v[20:21]
	v_lshl_add_u64 v[22:23], v[14:15], 0, v[22:23]
	v_lshl_add_u64 v[24:25], v[14:15], 0, v[24:25]
	v_lshl_add_u64 v[26:27], v[14:15], 0, v[26:27]
	v_lshl_add_u64 v[28:29], v[14:15], 0, v[28:29]
	v_lshl_add_u64 v[56:57], v[14:15], 0, v[56:57]
	global_load_dword v71, v[16:17], off nt
	global_load_dword v72, v[18:19], off nt
	global_load_dword v73, v[20:21], off nt
	global_load_dword v74, v[22:23], off nt
	global_load_dword v75, v[24:25], off nt
	global_load_dword v76, v[26:27], off nt
	global_load_dword v77, v[28:29], off nt
	s_nop 0
	global_load_dword v56, v[56:57], off nt
	v_or_b32_e32 v16, 48, v12
	v_mov_b32_e32 v17, v7
	v_or_b32_e32 v18, 50, v12
	v_mov_b32_e32 v19, v7
	v_or_b32_e32 v20, 52, v12
	v_mov_b32_e32 v21, v7
	v_or_b32_e32 v22, 54, v12
	v_or_b32_e32 v24, 56, v12
	v_or_b32_e32 v26, 58, v12
	v_or_b32_e32 v28, 60, v12
	v_or_b32_e32 v12, 62, v12
	v_lshlrev_b64 v[16:17], 10, v[16:17]
	v_lshlrev_b64 v[18:19], 10, v[18:19]
	v_lshlrev_b64 v[20:21], 10, v[20:21]
	v_mov_b32_e32 v23, v7
	v_mov_b32_e32 v25, v7
	v_mov_b32_e32 v27, v7
	v_mov_b32_e32 v29, v7
	v_lshlrev_b64 v[12:13], 10, v[12:13]
	v_lshl_add_u64 v[16:17], v[14:15], 0, v[16:17]
	v_lshl_add_u64 v[18:19], v[14:15], 0, v[18:19]
	v_lshl_add_u64 v[20:21], v[14:15], 0, v[20:21]
	v_lshlrev_b64 v[22:23], 10, v[22:23]
	v_lshlrev_b64 v[24:25], 10, v[24:25]
	v_lshlrev_b64 v[26:27], 10, v[26:27]
	v_lshlrev_b64 v[28:29], 10, v[28:29]
	v_lshl_add_u64 v[12:13], v[14:15], 0, v[12:13]
	v_lshl_add_u64 v[22:23], v[14:15], 0, v[22:23]
	v_lshl_add_u64 v[24:25], v[14:15], 0, v[24:25]
	v_lshl_add_u64 v[26:27], v[14:15], 0, v[26:27]
	v_lshl_add_u64 v[28:29], v[14:15], 0, v[28:29]
	global_load_dword v14, v[16:17], off nt
	global_load_dword v15, v[18:19], off nt
	s_nop 0
	global_load_dword v16, v[20:21], off nt
	global_load_dword v17, v[22:23], off nt
	global_load_dword v18, v[24:25], off nt
	global_load_dword v19, v[26:27], off nt
	s_nop 0
	global_load_dword v20, v[28:29], off nt
	s_nop 0
	global_load_dword v12, v[12:13], off nt
	s_waitcnt vmcnt(30)
; #define LAS __attribute__((address_space(3)))
; __device__ __forceinline__ unsigned pk2(float lo, float hi) { return pg8::cvt_pk_bf16(lo, hi); }
; __device__ __forceinline__ void lds_wait() { asm volatile("s_waitcnt lgkmcnt(0)" ::: "memory"); }
; __device__ __forceinline__ void transpose_item(const float* W, int N, bf16* WT, int K, int k0, int n0, int drow0, const float* gk, LAS float* scr, int lane) {
;     ...
;     for (int i = 0; i < 32; ++i) { const int kk = 2 * i + (lane >> 5); float v = wv[i]; if (gk) v *= gk[kk]; scr[kk * 33 + (lane & 31)] = v; }
;     lds_wait();
;     const int c = lane & 7;
; #pragma unroll
;     for (int j = 0; j < 4; ++j) { const int n = (lane >> 3) + 8 * j; const LAS float* s = scr + (8 * c) * 33 + n;
;         u32x4 o; o.x = pk2(s[0 * 33], s[1 * 33]); o.y = pk2(s[2 * 33], s[3 * 33]); o.z = pk2(s[4 * 33], s[5 * 33]); o.w = pk2(s[6 * 33], s[7 * 33]);
;         *(u32x4*)(WT + (size_t)(drow0 + n) * K + k0 + 8 * c) = o; }
;     lds_wait();
; __device__ __forceinline__ void p0_weight_item(const Args& a, int l, int r, LAS float* scr, int lane) {
;     ...
;     if (r < IT_GLU) { const int kb = r / 8, nb = r % 8; transpose_item(a.in[15] + (size_t)l * 65536, 256, (bf16*)(wl + WL_GLU), 256, 64 * kb, 32 * nb, 32 * nb, nullptr, scr, lane); return; }
	ds_write2_b32 v5, v9, v11 offset1:66
	s_waitcnt vmcnt(28)
	ds_write2_b32 v5, v55, v58 offset0:132 offset1:198
	s_waitcnt vmcnt(26)
	ds_write2_b32 v48, v59, v60 offset0:8 offset1:74
	s_waitcnt vmcnt(24)
	ds_write2_b32 v48, v61, v62 offset0:140 offset1:206
	s_waitcnt vmcnt(22)
	ds_write2_b32 v49, v63, v64 offset0:16 offset1:82
	s_waitcnt vmcnt(20)
	ds_write2_b32 v49, v65, v66 offset0:148 offset1:214
	s_waitcnt vmcnt(18)
	ds_write2_b32 v50, v67, v68 offset0:24 offset1:90
	s_waitcnt vmcnt(16)
	ds_write2_b32 v50, v69, v70 offset0:156 offset1:222
	s_waitcnt vmcnt(14)
	ds_write2_b32 v51, v71, v72 offset0:32 offset1:98
	s_waitcnt vmcnt(12)
	ds_write2_b32 v51, v73, v74 offset0:164 offset1:230
	s_waitcnt vmcnt(10)
	ds_write2_b32 v52, v75, v76 offset0:40 offset1:106
	s_waitcnt vmcnt(8)
	ds_write2_b32 v52, v77, v56 offset0:172 offset1:238
	s_waitcnt vmcnt(6)
	ds_write2_b32 v53, v14, v15 offset0:48 offset1:114
	s_waitcnt vmcnt(4)
	ds_write2_b32 v53, v16, v17 offset0:180 offset1:246
	s_waitcnt vmcnt(2)
	ds_write2_b32 v54, v18, v19 offset0:56 offset1:122
	s_waitcnt vmcnt(0)
	ds_write2_b32 v54, v20, v12 offset0:188 offset1:254
	s_lshl_b64 s[28:29], s[16:17], 1
	s_waitcnt lgkmcnt(0)
	s_add_u32 s28, s84, s28
	ds_read2_b32 v[12:13], v31 offset1:33
	ds_read2_b32 v[204:205], v31 offset0:66 offset1:99
	ds_read2_b32 v[206:207], v31 offset0:132 offset1:165
	ds_read2_b32 v[208:209], v31 offset0:198 offset1:231
	ds_read2_b32 v[210:211], v31 offset0:8 offset1:41
	ds_read2_b32 v[212:213], v31 offset0:74 offset1:107
	ds_read2_b32 v[214:215], v31 offset0:140 offset1:173
	ds_read2_b32 v[216:217], v31 offset0:206 offset1:239
	s_addc_u32 s29, s83, s29
	v_mov_b32_e32 v11, v7
	s_waitcnt lgkmcnt(7)
	v_cvt_pk_bf16_f32 v12, v12, v13
	ds_read2_b32 v[218:219], v31 offset0:16 offset1:49
	v_lshl_add_u64 v[18:19], s[28:29], 0, v[10:11]
	s_mov_b64 s[28:29], 0x2880000
	v_or_b32_e32 v9, s4, v30
	s_waitcnt lgkmcnt(7)
	v_cvt_pk_bf16_f32 v13, v204, v205
	ds_read2_b32 v[204:205], v31 offset0:82 offset1:115
	v_lshl_add_u64 v[18:19], v[18:19], 0, s[28:29]
	v_lshlrev_b32_e32 v20, 9, v9
	v_mov_b32_e32 v21, v7
	s_waitcnt lgkmcnt(7)
	v_cvt_pk_bf16_f32 v14, v206, v207
	ds_read2_b32 v[206:207], v31 offset0:148 offset1:181
	s_waitcnt lgkmcnt(7)
	v_cvt_pk_bf16_f32 v15, v208, v209
	ds_read2_b32 v[208:209], v31 offset0:214 offset1:247
	v_lshl_add_u64 v[20:21], v[18:19], 0, v[20:21]
	global_store_dwordx4 v[20:21], v[12:15], off sc1
	v_or_b32_e32 v9, s4, v32
	v_lshlrev_b32_e32 v20, 9, v9
	s_waitcnt lgkmcnt(7)
	v_cvt_pk_bf16_f32 v12, v210, v211
	ds_read2_b32 v[210:211], v31 offset0:24 offset1:57
	s_waitcnt lgkmcnt(7)
	v_cvt_pk_bf16_f32 v13, v212, v213
	ds_read2_b32 v[212:213], v31 offset0:90 offset1:123
	v_mov_b32_e32 v21, v7
	s_waitcnt lgkmcnt(7)
	v_cvt_pk_bf16_f32 v14, v214, v215
	ds_read2_b32 v[214:215], v31 offset0:156 offset1:189
	s_waitcnt lgkmcnt(7)
	v_cvt_pk_bf16_f32 v15, v216, v217
	ds_read2_b32 v[216:217], v31 offset0:222 offset1:255
	v_lshl_add_u64 v[20:21], v[18:19], 0, v[20:21]
	global_store_dwordx4 v[20:21], v[12:15], off sc1
	v_or_b32_e32 v9, s4, v33
	v_lshlrev_b32_e32 v20, 9, v9
	s_waitcnt lgkmcnt(7)
	v_cvt_pk_bf16_f32 v12, v218, v219
	s_waitcnt lgkmcnt(6)
	v_cvt_pk_bf16_f32 v13, v204, v205
	v_mov_b32_e32 v21, v7
	s_waitcnt lgkmcnt(5)
	v_cvt_pk_bf16_f32 v14, v206, v207
	s_waitcnt lgkmcnt(4)
	v_cvt_pk_bf16_f32 v15, v208, v209
	v_lshl_add_u64 v[20:21], v[18:19], 0, v[20:21]
	global_store_dwordx4 v[20:21], v[12:15], off sc1
	v_or_b32_e32 v9, s4, v34
	v_readlane_b32 s53, v250, 28
	s_waitcnt lgkmcnt(3)
	v_cvt_pk_bf16_f32 v12, v210, v211
	s_waitcnt lgkmcnt(2)
	v_cvt_pk_bf16_f32 v13, v212, v213
	s_waitcnt lgkmcnt(1)
	v_cvt_pk_bf16_f32 v14, v214, v215
	s_waitcnt lgkmcnt(0)
	v_cvt_pk_bf16_f32 v15, v216, v217
	v_lshlrev_b32_e32 v16, 9, v9
	v_mov_b32_e32 v17, v7
	v_lshl_add_u64 v[16:17], v[18:19], 0, v[16:17]
	global_store_dwordx4 v[16:17], v[12:15], off sc1
	s_waitcnt lgkmcnt(0)
	v_readlane_b32 s54, v250, 29
	v_readlane_b32 s55, v250, 30
	v_readlane_b32 s56, v250, 31
	v_readlane_b32 s57, v250, 32
	v_readlane_b32 s58, v250, 33
	v_readlane_b32 s59, v250, 34
	v_readlane_b32 s60, v250, 35
	v_readlane_b32 s61, v250, 36
	v_readlane_b32 s62, v250, 37
	v_readlane_b32 s63, v250, 38
	v_readlane_b32 s64, v250, 39
	v_readlane_b32 s65, v250, 40

; #define LAS __attribute__((address_space(3)))
; __device__ __forceinline__ unsigned pk2(float lo, float hi) { return pg8::cvt_pk_bf16(lo, hi); }
; __device__ __forceinline__ void lds_wait() { asm volatile("s_waitcnt lgkmcnt(0)" ::: "memory"); }
; __device__ __forceinline__ void transpose_item(const float* W, int N, bf16* WT, int K, int k0, int n0, int drow0, const float* gk, LAS float* scr, int lane) {
;     ...
;     for (int i = 0; i < 32; ++i) { const int kk = 2 * i + (lane >> 5); float v = wv[i]; if (gk) v *= gk[kk]; scr[kk * 33 + (lane & 31)] = v; }
;     lds_wait();
;     const int c = lane & 7;
; #pragma unroll
;     for (int j = 0; j < 4; ++j) { const int n = (lane >> 3) + 8 * j; const LAS float* s = scr + (8 * c) * 33 + n;
;         u32x4 o; o.x = pk2(s[0 * 33], s[1 * 33]); o.y = pk2(s[2 * 33], s[3 * 33]); o.z = pk2(s[4 * 33], s[5 * 33]); o.w = pk2(s[6 * 33], s[7 * 33]);
;         *(u32x4*)(WT + (size_t)(drow0 + n) * K + k0 + 8 * c) = o; }
;     lds_wait();
; __device__ __forceinline__ void p0_weight_item(const Args& a, int l, int r, LAS float* scr, int lane) {
;     ...
;     if (r < IT_OUT) {
;         const int kb = r / 32, nb = r % 32, k0 = 64 * kb;
;         const float* gk = (k0 < 256) ? a.in[17] + (size_t)l * 256 + k0 : (k0 < 768 ? a.in[18] + (size_t)l * 512 + (k0 - 256) : a.in[26] + (size_t)l * 256 + (k0 - 768));
;         transpose_item(a.in[27] + (size_t)l * DM * DM, DM, (bf16*)(wl + WL_WOUT), DM, k0, 32 * nb, 32 * nb, gk, scr, lane); return; }
.LBB0_58:
	s_waitcnt vmcnt(4)
	ds_write2_b32 v16, v14, v15 offset0:140 offset1:206
	s_lshl_b64 s[4:5], s[16:17], 1
	s_waitcnt lgkmcnt(0)
	s_add_u32 s4, s84, s4
	s_waitcnt vmcnt(0)
	ds_read2_b32 v[12:13], v31 offset1:33
	ds_read2_b32 v[204:205], v31 offset0:66 offset1:99
	ds_read2_b32 v[206:207], v31 offset0:132 offset1:165
	ds_read2_b32 v[208:209], v31 offset0:198 offset1:231
	ds_read2_b32 v[210:211], v31 offset0:8 offset1:41
	ds_read2_b32 v[212:213], v31 offset0:74 offset1:107
	ds_read2_b32 v[214:215], v31 offset0:140 offset1:173
	ds_read2_b32 v[216:217], v31 offset0:206 offset1:239
	v_mov_b32_e32 v11, v7
	s_addc_u32 s5, s83, s5
	s_waitcnt lgkmcnt(7)
	v_cvt_pk_bf16_f32 v12, v12, v13
	ds_read2_b32 v[218:219], v31 offset0:16 offset1:49
	v_or_b32_e32 v9, s27, v30
	v_lshl_add_u64 v[20:21], s[4:5], 0, v[10:11]
	s_mov_b64 s[4:5], 0x1600000
	s_waitcnt lgkmcnt(7)
	v_cvt_pk_bf16_f32 v13, v204, v205
	ds_read2_b32 v[204:205], v31 offset0:82 offset1:115
	v_mov_b32_e32 v19, v7
	v_lshlrev_b32_e32 v18, 11, v9
	v_lshl_add_u64 v[20:21], v[20:21], 0, s[4:5]
	s_waitcnt lgkmcnt(7)
	v_cvt_pk_bf16_f32 v14, v206, v207
	ds_read2_b32 v[206:207], v31 offset0:148 offset1:181
	s_waitcnt lgkmcnt(7)
	v_cvt_pk_bf16_f32 v15, v208, v209
	ds_read2_b32 v[208:209], v31 offset0:214 offset1:247
	v_lshl_add_u64 v[18:19], v[20:21], 0, v[18:19]
	global_store_dwordx4 v[18:19], v[12:15], off sc1
	v_or_b32_e32 v9, s27, v32
	v_mov_b32_e32 v19, v7
	s_waitcnt lgkmcnt(7)
	v_cvt_pk_bf16_f32 v12, v210, v211
	ds_read2_b32 v[210:211], v31 offset0:24 offset1:57
	s_waitcnt lgkmcnt(7)
	v_cvt_pk_bf16_f32 v13, v212, v213
	ds_read2_b32 v[212:213], v31 offset0:90 offset1:123
	v_lshlrev_b32_e32 v18, 11, v9
	s_waitcnt lgkmcnt(7)
	v_cvt_pk_bf16_f32 v14, v214, v215
	ds_read2_b32 v[214:215], v31 offset0:156 offset1:189
	s_waitcnt lgkmcnt(7)
	v_cvt_pk_bf16_f32 v15, v216, v217
	ds_read2_b32 v[216:217], v31 offset0:222 offset1:255
	v_lshl_add_u64 v[18:19], v[20:21], 0, v[18:19]
	global_store_dwordx4 v[18:19], v[12:15], off sc1
	v_or_b32_e32 v9, s27, v33
	v_mov_b32_e32 v19, v7
	s_waitcnt lgkmcnt(7)
	v_cvt_pk_bf16_f32 v12, v218, v219
	s_waitcnt lgkmcnt(6)
	v_cvt_pk_bf16_f32 v13, v204, v205
	v_lshlrev_b32_e32 v18, 11, v9
	s_waitcnt lgkmcnt(5)
	v_cvt_pk_bf16_f32 v14, v206, v207
	s_waitcnt lgkmcnt(4)
	v_cvt_pk_bf16_f32 v15, v208, v209
	v_lshl_add_u64 v[18:19], v[20:21], 0, v[18:19]
	global_store_dwordx4 v[18:19], v[12:15], off sc1
	v_or_b32_e32 v9, s27, v34
	v_mov_b32_e32 v19, v7
	s_waitcnt lgkmcnt(3)
	v_cvt_pk_bf16_f32 v12, v210, v211
	s_waitcnt lgkmcnt(2)
	v_cvt_pk_bf16_f32 v13, v212, v213
	s_waitcnt lgkmcnt(1)
	v_cvt_pk_bf16_f32 v14, v214, v215
	v_lshlrev_b32_e32 v18, 11, v9
	s_waitcnt lgkmcnt(0)
	v_cvt_pk_bf16_f32 v15, v216, v217
	v_lshl_add_u64 v[16:17], v[20:21], 0, v[18:19]
	global_store_dwordx4 v[16:17], v[12:15], off sc1
	s_waitcnt lgkmcnt(0)

; #define LAS __attribute__((address_space(3)))
; __device__ __forceinline__ unsigned pk2(float lo, float hi) { return pg8::cvt_pk_bf16(lo, hi); }
; __device__ __forceinline__ void lds_wait() { asm volatile("s_waitcnt lgkmcnt(0)" ::: "memory"); }
; __device__ __forceinline__ void transpose_item(const float* W, int N, bf16* WT, int K, int k0, int n0, int drow0, const float* gk, LAS float* scr, int lane) {
;     ...
;     for (int i = 0; i < 32; ++i) { const int kk = 2 * i + (lane >> 5); float v = wv[i]; if (gk) v *= gk[kk]; scr[kk * 33 + (lane & 31)] = v; }
;     lds_wait();
;     const int c = lane & 7;
; #pragma unroll
;     for (int j = 0; j < 4; ++j) { const int n = (lane >> 3) + 8 * j; const LAS float* s = scr + (8 * c) * 33 + n;
;         u32x4 o; o.x = pk2(s[0 * 33], s[1 * 33]); o.y = pk2(s[2 * 33], s[3 * 33]); o.z = pk2(s[4 * 33], s[5 * 33]); o.w = pk2(s[6 * 33], s[7 * 33]);
;         *(u32x4*)(WT + (size_t)(drow0 + n) * K + k0 + 8 * c) = o; }
.LBB0_87:
	s_waitcnt vmcnt(4)
	ds_write2_b32 v16, v14, v15 offset0:140 offset1:206
	s_waitcnt lgkmcnt(0)
	s_lshl_b32 s4, s27, 1
	s_waitcnt vmcnt(0)
	ds_read2_b32 v[12:13], v31 offset1:33
	ds_read2_b32 v[204:205], v31 offset0:66 offset1:99
	ds_read2_b32 v[206:207], v31 offset0:132 offset1:165
	ds_read2_b32 v[208:209], v31 offset0:198 offset1:231
	ds_read2_b32 v[210:211], v31 offset0:8 offset1:41
	ds_read2_b32 v[212:213], v31 offset0:74 offset1:107
	ds_read2_b32 v[214:215], v31 offset0:140 offset1:173
	ds_read2_b32 v[216:217], v31 offset0:206 offset1:239
	s_add_u32 s4, s84, s4
	s_waitcnt lgkmcnt(7)
	v_cvt_pk_bf16_f32 v12, v12, v13
	ds_read2_b32 v[218:219], v31 offset0:16 offset1:49
	v_mov_b32_e32 v11, v7
	s_addc_u32 s5, s83, 0
	s_waitcnt lgkmcnt(7)
	v_cvt_pk_bf16_f32 v13, v204, v205
	ds_read2_b32 v[204:205], v31 offset0:82 offset1:115
	v_add_u32_e32 v16, s22, v30
	v_mov_b32_e32 v17, v7
	v_lshl_add_u64 v[20:21], s[4:5], 0, v[10:11]
	s_mov_b64 s[4:5], 0x1080000
	s_waitcnt lgkmcnt(7)
	v_cvt_pk_bf16_f32 v14, v206, v207
	ds_read2_b32 v[206:207], v31 offset0:148 offset1:181
	v_lshlrev_b64 v[16:17], 11, v[16:17]
	v_lshl_add_u64 v[20:21], v[20:21], 0, s[4:5]
	s_waitcnt lgkmcnt(7)
	v_cvt_pk_bf16_f32 v15, v208, v209
	ds_read2_b32 v[208:209], v31 offset0:214 offset1:247
	v_lshl_add_u64 v[16:17], v[20:21], 0, v[16:17]
	global_store_dwordx4 v[16:17], v[12:15], off sc1
	s_waitcnt lgkmcnt(7)
	s_nop 0
	v_cvt_pk_bf16_f32 v12, v210, v211
	ds_read2_b32 v[210:211], v31 offset0:24 offset1:57
	v_add_u32_e32 v18, s22, v32
	v_mov_b32_e32 v19, v7
	s_waitcnt lgkmcnt(7)
	v_cvt_pk_bf16_f32 v13, v212, v213
	ds_read2_b32 v[212:213], v31 offset0:90 offset1:123
	v_lshlrev_b64 v[18:19], 11, v[18:19]
	s_waitcnt lgkmcnt(7)
	v_cvt_pk_bf16_f32 v14, v214, v215
	ds_read2_b32 v[214:215], v31 offset0:156 offset1:189
	s_waitcnt lgkmcnt(7)
	v_cvt_pk_bf16_f32 v15, v216, v217
	ds_read2_b32 v[216:217], v31 offset0:222 offset1:255
	v_lshl_add_u64 v[18:19], v[20:21], 0, v[18:19]
	global_store_dwordx4 v[18:19], v[12:15], off sc1
	v_add_u32_e32 v18, s22, v33
	v_mov_b32_e32 v19, v7
	s_waitcnt lgkmcnt(7)
	v_cvt_pk_bf16_f32 v12, v218, v219
	s_waitcnt lgkmcnt(6)
	v_cvt_pk_bf16_f32 v13, v204, v205
	v_lshlrev_b64 v[18:19], 11, v[18:19]
	s_waitcnt lgkmcnt(5)
	v_cvt_pk_bf16_f32 v14, v206, v207
	s_waitcnt lgkmcnt(4)
	v_cvt_pk_bf16_f32 v15, v208, v209
	v_lshl_add_u64 v[18:19], v[20:21], 0, v[18:19]
	global_store_dwordx4 v[18:19], v[12:15], off sc1
	v_add_u32_e32 v18, s22, v34
	v_mov_b32_e32 v19, v7
	s_waitcnt lgkmcnt(3)
	v_cvt_pk_bf16_f32 v12, v210, v211
	s_waitcnt lgkmcnt(2)
	v_cvt_pk_bf16_f32 v13, v212, v213
	s_waitcnt lgkmcnt(1)
	v_cvt_pk_bf16_f32 v14, v214, v215
	v_lshlrev_b64 v[18:19], 11, v[18:19]
	s_waitcnt lgkmcnt(0)
	v_cvt_pk_bf16_f32 v15, v216, v217
	v_lshl_add_u64 v[16:17], v[20:21], 0, v[18:19]
	global_store_dwordx4 v[16:17], v[12:15], off sc1
	s_waitcnt lgkmcnt(0)

; #define LAS __attribute__((address_space(3)))
; __device__ __forceinline__ void transpose_item(const float* W, int N, bf16* WT, int K, int k0, int n0, int drow0, const float* gk, LAS float* scr, int lane) {
;     float wv[32];
; #pragma unroll
;     for (int i = 0; i < 32; ++i) wv[i] = W[(size_t)(k0 + 2 * i + (lane >> 5)) * N + n0 + (lane & 31)];
; __device__ __forceinline__ void p0_weight_item(const Args& a, int l, int r, LAS float* scr, int lane) {
;     ...
;         if (r < IT_BIG) { const int kb = r / 32, nb = r % 32; const float* W = a.in[f ? 31 : 4] + (size_t)l * FF * DM;
;             transpose_item(W, DM, dn, FF, 64 * kb, 32 * nb, 32 * nb, nullptr, scr, lane); return; }
.LBB0_89:
	s_andn2_b64 vcc, exec, s[4:5]
	s_cbranch_vccnz .LBB0_91
	v_readlane_b32 s52, v250, 59
	v_readlane_b32 s66, v251, 9
	v_readlane_b32 s67, v251, 10
	s_add_u32 s22, s66, s86
	s_mul_i32 s4, s26, 0xffffaea0
	s_addc_u32 s27, s67, s85
	s_add_i32 s4, s45, s4
	s_addk_i32 s4, 0xdf00
	s_and_b32 s5, s4, 0x7fffffc0
	s_lshl_b32 s4, s26, 9
	s_sub_i32 s4, s43, s4
	s_add_i32 s4, s4, 0xfffdf000
	s_and_b32 s4, s4, 0x3e0
	s_lshl_b32 s28, s4, 2
	v_or_b32_e32 v12, s5, v4
	s_add_u32 s28, s22, s28
	s_addc_u32 s29, s27, 0
	v_mov_b32_e32 v13, v7
	v_or_b32_e32 v18, 2, v12
	v_mov_b32_e32 v19, v7
	v_or_b32_e32 v20, 4, v12
	v_mov_b32_e32 v21, v7
	v_or_b32_e32 v22, 6, v12
	v_mov_b32_e32 v23, v7
	v_or_b32_e32 v24, 8, v12
	v_mov_b32_e32 v25, v7
	v_or_b32_e32 v26, 10, v12
	v_mov_b32_e32 v27, v7
	v_or_b32_e32 v28, 12, v12
	v_mov_b32_e32 v29, v7
	v_or_b32_e32 v56, 14, v12
	v_mov_b32_e32 v57, v7
	v_lshl_add_u64 v[14:15], s[28:29], 0, v[6:7]
	v_lshlrev_b64 v[16:17], 12, v[12:13]
	v_lshlrev_b64 v[18:19], 12, v[18:19]
	v_lshlrev_b64 v[20:21], 12, v[20:21]
	v_lshlrev_b64 v[22:23], 12, v[22:23]
	v_lshlrev_b64 v[24:25], 12, v[24:25]
	v_lshlrev_b64 v[26:27], 12, v[26:27]
	v_lshlrev_b64 v[28:29], 12, v[28:29]
	v_lshlrev_b64 v[56:57], 12, v[56:57]
	v_lshl_add_u64 v[16:17], v[14:15], 0, v[16:17]
	v_lshl_add_u64 v[18:19], v[14:15], 0, v[18:19]
	v_lshl_add_u64 v[20:21], v[14:15], 0, v[20:21]
	v_lshl_add_u64 v[22:23], v[14:15], 0, v[22:23]
	v_lshl_add_u64 v[24:25], v[14:15], 0, v[24:25]
	v_lshl_add_u64 v[26:27], v[14:15], 0, v[26:27]
	v_lshl_add_u64 v[28:29], v[14:15], 0, v[28:29]
	v_lshl_add_u64 v[56:57], v[14:15], 0, v[56:57]
	global_load_dword v9, v[16:17], off nt
	global_load_dword v11, v[18:19], off nt
	global_load_dword v55, v[20:21], off nt
	global_load_dword v58, v[22:23], off nt
	global_load_dword v59, v[24:25], off nt
	global_load_dword v60, v[26:27], off nt
	global_load_dword v61, v[28:29], off nt
	global_load_dword v62, v[56:57], off nt
	v_or_b32_e32 v16, 16, v12
	v_mov_b32_e32 v17, v7
	v_or_b32_e32 v18, 18, v12
	v_mov_b32_e32 v19, v7
	v_or_b32_e32 v20, 20, v12
	v_mov_b32_e32 v21, v7
	v_or_b32_e32 v22, 22, v12
	v_mov_b32_e32 v23, v7
	v_or_b32_e32 v24, 24, v12
	v_mov_b32_e32 v25, v7
	v_or_b32_e32 v26, 26, v12
	v_mov_b32_e32 v27, v7
	v_or_b32_e32 v28, 28, v12
	v_mov_b32_e32 v29, v7
	v_or_b32_e32 v56, 30, v12
	v_mov_b32_e32 v57, v7
	v_lshlrev_b64 v[16:17], 12, v[16:17]
	v_lshlrev_b64 v[18:19], 12, v[18:19]
	v_lshlrev_b64 v[20:21], 12, v[20:21]
	v_lshlrev_b64 v[22:23], 12, v[22:23]
	v_lshlrev_b64 v[24:25], 12, v[24:25]
	v_lshlrev_b64 v[26:27], 12, v[26:27]
	v_lshlrev_b64 v[28:29], 12, v[28:29]
	v_lshlrev_b64 v[56:57], 12, v[56:57]
	v_lshl_add_u64 v[16:17], v[14:15], 0, v[16:17]
	v_lshl_add_u64 v[18:19], v[14:15], 0, v[18:19]
	v_lshl_add_u64 v[20:21], v[14:15], 0, v[20:21]
	v_lshl_add_u64 v[22:23], v[14:15], 0, v[22:23]
	v_lshl_add_u64 v[24:25], v[14:15], 0, v[24:25]
	v_lshl_add_u64 v[26:27], v[14:15], 0, v[26:27]
	v_lshl_add_u64 v[28:29], v[14:15], 0, v[28:29]
	v_lshl_add_u64 v[56:57], v[14:15], 0, v[56:57]
	global_load_dword v63, v[16:17], off nt
	global_load_dword v64, v[18:19], off nt
	global_load_dword v65, v[20:21], off nt
	global_load_dword v66, v[22:23], off nt
	global_load_dword v67, v[24:25], off nt
	global_load_dword v68, v[26:27], off nt
	global_load_dword v69, v[28:29], off nt
	global_load_dword v70, v[56:57], off nt
	v_or_b32_e32 v16, 32, v12
	v_mov_b32_e32 v17, v7
	v_or_b32_e32 v18, 34, v12
	v_mov_b32_e32 v19, v7
	v_or_b32_e32 v20, 36, v12
	v_mov_b32_e32 v21, v7
	v_or_b32_e32 v22, 38, v12
	v_mov_b32_e32 v23, v7
	v_or_b32_e32 v24, 40, v12
	v_mov_b32_e32 v25, v7
	v_or_b32_e32 v26, 42, v12
	v_mov_b32_e32 v27, v7
	v_or_b32_e32 v28, 44, v12
	v_mov_b32_e32 v29, v7
	v_or_b32_e32 v56, 46, v12
	v_mov_b32_e32 v57, v7
	v_lshlrev_b64 v[16:17], 12, v[16:17]
	v_lshlrev_b64 v[18:19], 12, v[18:19]
	v_lshlrev_b64 v[20:21], 12, v[20:21]
	v_lshlrev_b64 v[22:23], 12, v[22:23]
	v_lshlrev_b64 v[24:25], 12, v[24:25]
	v_lshlrev_b64 v[26:27], 12, v[26:27]
	v_lshlrev_b64 v[28:29], 12, v[28:29]
	v_lshlrev_b64 v[56:57], 12, v[56:57]
	v_lshl_add_u64 v[16:17], v[14:15], 0, v[16:17]
	v_lshl_add_u64 v[18:19], v[14:15], 0, v[18:19]
	v_lshl_add_u64 v[20:21], v[14:15], 0, v[20:21]
	v_lshl_add_u64 v[22:23], v[14:15], 0, v[22:23]
	v_lshl_add_u64 v[24:25], v[14:15], 0, v[24:25]
	v_lshl_add_u64 v[26:27], v[14:15], 0, v[26:27]
	v_lshl_add_u64 v[28:29], v[14:15], 0, v[28:29]
	v_lshl_add_u64 v[56:57], v[14:15], 0, v[56:57]
	global_load_dword v71, v[16:17], off nt
	global_load_dword v72, v[18:19], off nt
	global_load_dword v73, v[20:21], off nt
	global_load_dword v74, v[22:23], off nt
	global_load_dword v75, v[24:25], off nt
	global_load_dword v76, v[26:27], off nt
	global_load_dword v77, v[28:29], off nt
	s_nop 0
	global_load_dword v56, v[56:57], off nt
	v_or_b32_e32 v16, 48, v12
	v_mov_b32_e32 v17, v7
	v_or_b32_e32 v18, 50, v12
	v_mov_b32_e32 v19, v7
	v_or_b32_e32 v20, 52, v12
	v_mov_b32_e32 v21, v7
	v_or_b32_e32 v22, 54, v12
	v_or_b32_e32 v24, 56, v12
	v_or_b32_e32 v26, 58, v12
	v_or_b32_e32 v28, 60, v12
	v_or_b32_e32 v12, 62, v12
	v_lshlrev_b64 v[16:17], 12, v[16:17]
	v_lshlrev_b64 v[18:19], 12, v[18:19]
	v_lshlrev_b64 v[20:21], 12, v[20:21]
	v_mov_b32_e32 v23, v7
	v_mov_b32_e32 v25, v7
	v_mov_b32_e32 v27, v7
	v_mov_b32_e32 v29, v7
	v_lshlrev_b64 v[12:13], 12, v[12:13]
	v_lshl_add_u64 v[16:17], v[14:15], 0, v[16:17]
	v_lshl_add_u64 v[18:19], v[14:15], 0, v[18:19]
	v_lshl_add_u64 v[20:21], v[14:15], 0, v[20:21]
	v_lshlrev_b64 v[22:23], 12, v[22:23]
	v_lshlrev_b64 v[24:25], 12, v[24:25]
	v_lshlrev_b64 v[26:27], 12, v[26:27]
	v_lshlrev_b64 v[28:29], 12, v[28:29]
	v_lshl_add_u64 v[12:13], v[14:15], 0, v[12:13]
	v_lshl_add_u64 v[22:23], v[14:15], 0, v[22:23]
	v_lshl_add_u64 v[24:25], v[14:15], 0, v[24:25]
	v_lshl_add_u64 v[26:27], v[14:15], 0, v[26:27]
	v_lshl_add_u64 v[28:29], v[14:15], 0, v[28:29]
	global_load_dword v14, v[16:17], off nt
	global_load_dword v15, v[18:19], off nt
	s_nop 0
	global_load_dword v16, v[20:21], off nt
	global_load_dword v17, v[22:23], off nt
	global_load_dword v18, v[24:25], off nt
	global_load_dword v19, v[26:27], off nt
	s_nop 0
	global_load_dword v20, v[28:29], off nt
	s_nop 0
	global_load_dword v12, v[12:13], off nt
	s_waitcnt vmcnt(30)
; #define LAS __attribute__((address_space(3)))
; __device__ __forceinline__ unsigned pk2(float lo, float hi) { return pg8::cvt_pk_bf16(lo, hi); }
; __device__ __forceinline__ void lds_wait() { asm volatile("s_waitcnt lgkmcnt(0)" ::: "memory"); }
; __device__ __forceinline__ void transpose_item(const float* W, int N, bf16* WT, int K, int k0, int n0, int drow0, const float* gk, LAS float* scr, int lane) {
;     ...
;     for (int i = 0; i < 32; ++i) { const int kk = 2 * i + (lane >> 5); float v = wv[i]; if (gk) v *= gk[kk]; scr[kk * 33 + (lane & 31)] = v; }
;     lds_wait();
;     const int c = lane & 7;
; #pragma unroll
;     for (int j = 0; j < 4; ++j) { const int n = (lane >> 3) + 8 * j; const LAS float* s = scr + (8 * c) * 33 + n;
;         u32x4 o; o.x = pk2(s[0 * 33], s[1 * 33]); o.y = pk2(s[2 * 33], s[3 * 33]); o.z = pk2(s[4 * 33], s[5 * 33]); o.w = pk2(s[6 * 33], s[7 * 33]);
;         *(u32x4*)(WT + (size_t)(drow0 + n) * K + k0 + 8 * c) = o; }
;     lds_wait();
	ds_write2_b32 v5, v9, v11 offset1:66
	s_waitcnt vmcnt(28)
	ds_write2_b32 v5, v55, v58 offset0:132 offset1:198
	s_waitcnt vmcnt(26)
	ds_write2_b32 v48, v59, v60 offset0:8 offset1:74
	s_waitcnt vmcnt(24)
	ds_write2_b32 v48, v61, v62 offset0:140 offset1:206
	s_waitcnt vmcnt(22)
	ds_write2_b32 v49, v63, v64 offset0:16 offset1:82
	s_waitcnt vmcnt(20)
	ds_write2_b32 v49, v65, v66 offset0:148 offset1:214
	s_waitcnt vmcnt(18)
	ds_write2_b32 v50, v67, v68 offset0:24 offset1:90
	s_waitcnt vmcnt(16)
	ds_write2_b32 v50, v69, v70 offset0:156 offset1:222
	s_waitcnt vmcnt(14)
	ds_write2_b32 v51, v71, v72 offset0:32 offset1:98
	s_waitcnt vmcnt(12)
	ds_write2_b32 v51, v73, v74 offset0:164 offset1:230
	s_waitcnt vmcnt(10)
	ds_write2_b32 v52, v75, v76 offset0:40 offset1:106
	s_waitcnt vmcnt(8)
	ds_write2_b32 v52, v77, v56 offset0:172 offset1:238
	s_waitcnt vmcnt(6)
	ds_write2_b32 v53, v14, v15 offset0:48 offset1:114
	s_waitcnt vmcnt(4)
	ds_write2_b32 v53, v16, v17 offset0:180 offset1:246
	s_waitcnt vmcnt(2)
	ds_write2_b32 v54, v18, v19 offset0:56 offset1:122
	s_waitcnt vmcnt(0)
	ds_write2_b32 v54, v20, v12 offset0:188 offset1:254
	s_lshl_b32 s5, s5, 1
	s_waitcnt lgkmcnt(0)
	s_add_u32 s28, s84, s5
	ds_read2_b32 v[12:13], v31 offset1:33
	ds_read2_b32 v[204:205], v31 offset0:66 offset1:99
	ds_read2_b32 v[206:207], v31 offset0:132 offset1:165
	ds_read2_b32 v[208:209], v31 offset0:198 offset1:231
	ds_read2_b32 v[210:211], v31 offset0:8 offset1:41
	ds_read2_b32 v[212:213], v31 offset0:74 offset1:107
	ds_read2_b32 v[214:215], v31 offset0:140 offset1:173
	ds_read2_b32 v[216:217], v31 offset0:206 offset1:239
	s_addc_u32 s29, s83, 0
	v_mov_b32_e32 v11, v7
	v_or_b32_e32 v9, s4, v30
	s_waitcnt lgkmcnt(7)
	v_cvt_pk_bf16_f32 v12, v12, v13
	ds_read2_b32 v[218:219], v31 offset0:16 offset1:49
	v_lshl_add_u64 v[18:19], s[28:29], 0, v[10:11]
	s_mov_b64 s[28:29], 0x2300000
	v_mul_u32_u24_e32 v9, 0xb00, v9
	s_waitcnt lgkmcnt(7)
	v_cvt_pk_bf16_f32 v13, v204, v205
	ds_read2_b32 v[204:205], v31 offset0:82 offset1:115
	v_lshl_add_u64 v[18:19], v[18:19], 0, s[28:29]
	v_lshlrev_b32_e32 v20, 1, v9
	v_mov_b32_e32 v21, v7
	s_waitcnt lgkmcnt(7)
	v_cvt_pk_bf16_f32 v14, v206, v207
	ds_read2_b32 v[206:207], v31 offset0:148 offset1:181
	s_waitcnt lgkmcnt(7)
	v_cvt_pk_bf16_f32 v15, v208, v209
	ds_read2_b32 v[208:209], v31 offset0:214 offset1:247
	v_lshl_add_u64 v[20:21], v[18:19], 0, v[20:21]
	v_or_b32_e32 v9, s4, v32
	global_store_dwordx4 v[20:21], v[12:15], off sc1
	v_mul_u32_u24_e32 v9, 0xb00, v9
	v_lshlrev_b32_e32 v20, 1, v9
	s_waitcnt lgkmcnt(7)
	v_cvt_pk_bf16_f32 v12, v210, v211
	ds_read2_b32 v[210:211], v31 offset0:24 offset1:57
	s_waitcnt lgkmcnt(7)
	v_cvt_pk_bf16_f32 v13, v212, v213
	ds_read2_b32 v[212:213], v31 offset0:90 offset1:123
	v_mov_b32_e32 v21, v7
	s_waitcnt lgkmcnt(7)
	v_cvt_pk_bf16_f32 v14, v214, v215
	ds_read2_b32 v[214:215], v31 offset0:156 offset1:189
	s_waitcnt lgkmcnt(7)
	v_cvt_pk_bf16_f32 v15, v216, v217
	ds_read2_b32 v[216:217], v31 offset0:222 offset1:255
	v_lshl_add_u64 v[20:21], v[18:19], 0, v[20:21]
	v_or_b32_e32 v9, s4, v33
	global_store_dwordx4 v[20:21], v[12:15], off sc1
	v_mul_u32_u24_e32 v9, 0xb00, v9
	v_lshlrev_b32_e32 v20, 1, v9
	s_waitcnt lgkmcnt(7)
	v_cvt_pk_bf16_f32 v12, v218, v219
	s_waitcnt lgkmcnt(6)
	v_cvt_pk_bf16_f32 v13, v204, v205
	v_mov_b32_e32 v21, v7
	s_waitcnt lgkmcnt(5)
	v_cvt_pk_bf16_f32 v14, v206, v207
	s_waitcnt lgkmcnt(4)
	v_cvt_pk_bf16_f32 v15, v208, v209
	v_lshl_add_u64 v[20:21], v[18:19], 0, v[20:21]
	global_store_dwordx4 v[20:21], v[12:15], off sc1
	v_or_b32_e32 v9, s4, v34
	v_mul_u32_u24_e32 v9, 0xb00, v9
	s_waitcnt lgkmcnt(3)
	v_cvt_pk_bf16_f32 v12, v210, v211
	s_waitcnt lgkmcnt(2)
	v_cvt_pk_bf16_f32 v13, v212, v213
	s_waitcnt lgkmcnt(1)
	v_cvt_pk_bf16_f32 v14, v214, v215
	s_waitcnt lgkmcnt(0)
	v_cvt_pk_bf16_f32 v15, v216, v217
	v_lshlrev_b32_e32 v16, 1, v9
	v_mov_b32_e32 v17, v7
	v_lshl_add_u64 v[16:17], v[18:19], 0, v[16:17]
	global_store_dwordx4 v[16:17], v[12:15], off sc1
	s_waitcnt lgkmcnt(0)
	v_readlane_b32 s53, v250, 60
	v_readlane_b32 s54, v250, 61
	v_readlane_b32 s55, v250, 62
	v_readlane_b32 s56, v250, 63
	v_readlane_b32 s57, v251, 0
	v_readlane_b32 s58, v251, 1
	v_readlane_b32 s59, v251, 2
	v_readlane_b32 s60, v251, 3
	v_readlane_b32 s61, v251, 4
	v_readlane_b32 s62, v251, 5
	v_readlane_b32 s63, v251, 6
	v_readlane_b32 s64, v251, 7
	v_readlane_b32 s65, v251, 8

; #define LAS __attribute__((address_space(3)))
; __device__ __forceinline__ unsigned pk2(float lo, float hi) { return pg8::cvt_pk_bf16(lo, hi); }
; __device__ __forceinline__ void lds_wait() { asm volatile("s_waitcnt lgkmcnt(0)" ::: "memory"); }
; __device__ __forceinline__ void transpose_item(const float* W, int N, bf16* WT, int K, int k0, int n0, int drow0, const float* gk, LAS float* scr, int lane) {
;     ...
;     for (int i = 0; i < 32; ++i) { const int kk = 2 * i + (lane >> 5); float v = wv[i]; if (gk) v *= gk[kk]; scr[kk * 33 + (lane & 31)] = v; }
;     lds_wait();
;     const int c = lane & 7;
; #pragma unroll
;     for (int j = 0; j < 4; ++j) { const int n = (lane >> 3) + 8 * j; const LAS float* s = scr + (8 * c) * 33 + n;
;         u32x4 o; o.x = pk2(s[0 * 33], s[1 * 33]); o.y = pk2(s[2 * 33], s[3 * 33]); o.z = pk2(s[4 * 33], s[5 * 33]); o.w = pk2(s[6 * 33], s[7 * 33]);
;         *(u32x4*)(WT + (size_t)(drow0 + n) * K + k0 + 8 * c) = o; }
.LBB0_117:
	s_lshl_b32 s4, s22, 6
	s_waitcnt vmcnt(4)
	ds_write2_b32 v16, v14, v15 offset0:140 offset1:206
	s_and_b32 s22, s4, 0xffffff00
	s_waitcnt lgkmcnt(0)
	s_and_b64 s[4:5], s[28:29], exec
	s_waitcnt vmcnt(0)
	ds_read2_b32 v[12:13], v31 offset1:33
	ds_read2_b32 v[204:205], v31 offset0:66 offset1:99
	ds_read2_b32 v[206:207], v31 offset0:132 offset1:165
	ds_read2_b32 v[16:17], v31 offset0:198 offset1:231
	ds_read2_b32 v[20:21], v31 offset0:8 offset1:41
	ds_read2_b32 v[208:209], v31 offset0:74 offset1:107
	ds_read2_b32 v[210:211], v31 offset0:140 offset1:173
	ds_read2_b32 v[212:213], v31 offset0:206 offset1:239
	s_cselect_b32 s27, 0x80, 0
	s_waitcnt lgkmcnt(7)
	v_cvt_pk_bf16_f32 v12, v12, v13
	ds_read2_b32 v[214:215], v31 offset0:16 offset1:49
	s_and_b32 s28, s34, 0x60
	s_or_b32 s22, s22, s27
	s_waitcnt lgkmcnt(7)
	v_cvt_pk_bf16_f32 v13, v204, v205
	ds_read2_b32 v[204:205], v31 offset0:82 offset1:115
	s_lshl_b64 s[4:5], s[30:31], 1
	s_or_b32 s22, s22, s28
	s_waitcnt lgkmcnt(7)
	v_cvt_pk_bf16_f32 v14, v206, v207
	ds_read2_b32 v[206:207], v31 offset0:148 offset1:181
	s_add_u32 s4, s84, s4
	v_mov_b32_e32 v11, v7
	s_addc_u32 s5, s83, s5
	s_waitcnt lgkmcnt(7)
	v_cvt_pk_bf16_f32 v15, v16, v17
	v_or_b32_e32 v16, s22, v30
	v_lshl_add_u64 v[18:19], s[4:5], 0, v[10:11]
	s_mov_b64 s[4:5], 0x1800000
	v_ashrrev_i32_e32 v17, 31, v16
	ds_read2_b32 v[216:217], v31 offset0:214 offset1:247
	v_lshl_add_u64 v[18:19], v[18:19], 0, s[4:5]
	v_lshlrev_b64 v[16:17], 11, v[16:17]
	v_lshl_add_u64 v[16:17], v[18:19], 0, v[16:17]
	global_store_dwordx4 v[16:17], v[12:15], off sc1
	s_waitcnt lgkmcnt(7)
	s_nop 0
	v_cvt_pk_bf16_f32 v12, v20, v21
	v_or_b32_e32 v20, s22, v32
	v_ashrrev_i32_e32 v21, 31, v20
	ds_read2_b32 v[218:219], v31 offset0:24 offset1:57
	v_lshlrev_b64 v[20:21], 11, v[20:21]
	s_waitcnt lgkmcnt(7)
	v_cvt_pk_bf16_f32 v13, v208, v209
	ds_read2_b32 v[208:209], v31 offset0:90 offset1:123
	v_lshl_add_u64 v[20:21], v[18:19], 0, v[20:21]
	s_waitcnt lgkmcnt(7)
	v_cvt_pk_bf16_f32 v14, v210, v211
	ds_read2_b32 v[210:211], v31 offset0:156 offset1:189
	s_waitcnt lgkmcnt(7)
	v_cvt_pk_bf16_f32 v15, v212, v213
	ds_read2_b32 v[212:213], v31 offset0:222 offset1:255
	global_store_dwordx4 v[20:21], v[12:15], off sc1
	v_or_b32_e32 v20, s22, v33
	s_waitcnt lgkmcnt(7)
	v_cvt_pk_bf16_f32 v12, v214, v215
	v_ashrrev_i32_e32 v21, 31, v20
	s_waitcnt lgkmcnt(6)
	v_cvt_pk_bf16_f32 v13, v204, v205
	v_lshlrev_b64 v[20:21], 11, v[20:21]
	s_waitcnt lgkmcnt(5)
	v_cvt_pk_bf16_f32 v14, v206, v207
	s_waitcnt lgkmcnt(4)
	v_cvt_pk_bf16_f32 v15, v216, v217
	v_lshl_add_u64 v[20:21], v[18:19], 0, v[20:21]
	global_store_dwordx4 v[20:21], v[12:15], off sc1
	v_or_b32_e32 v20, s22, v34
	v_ashrrev_i32_e32 v21, 31, v20
	s_waitcnt lgkmcnt(3)
	v_cvt_pk_bf16_f32 v12, v218, v219
	s_waitcnt lgkmcnt(2)
	v_cvt_pk_bf16_f32 v13, v208, v209
	s_waitcnt lgkmcnt(1)
	v_cvt_pk_bf16_f32 v14, v210, v211
	v_lshlrev_b64 v[20:21], 11, v[20:21]
	s_waitcnt lgkmcnt(0)
	v_cvt_pk_bf16_f32 v15, v212, v213
	v_lshl_add_u64 v[16:17], v[18:19], 0, v[20:21]
	global_store_dwordx4 v[16:17], v[12:15], off sc1
	s_waitcnt lgkmcnt(0)

; #define LAS __attribute__((address_space(3)))
; __device__ __forceinline__ void transpose_item(const float* W, int N, bf16* WT, int K, int k0, int n0, int drow0, const float* gk, LAS float* scr, int lane) {
;     float wv[32];
; #pragma unroll
;     for (int i = 0; i < 32; ++i) wv[i] = W[(size_t)(k0 + 2 * i + (lane >> 5)) * N + n0 + (lane & 31)];
; __device__ __forceinline__ void p0_weight_item(const Args& a, int l, int r, LAS float* scr, int lane) {
;     ...
;         if (r < IT_BIG) { const int kb = r / 32, nb = r % 32; const float* W = a.in[f ? 31 : 4] + (size_t)l * FF * DM;
;             transpose_item(W, DM, dn, FF, 64 * kb, 32 * nb, 32 * nb, nullptr, scr, lane); return; }
.LBB0_119:
	s_andn2_b64 vcc, exec, s[4:5]
	s_cbranch_vccnz .LBB0_121
	v_readlane_b32 s52, v250, 11
	v_readlane_b32 s60, v250, 19
	v_readlane_b32 s61, v250, 20
	s_add_u32 s22, s60, s86
	s_mul_i32 s4, s26, 0xffffaea0
	s_addc_u32 s27, s61, s85
	s_add_i32 s4, s45, s4
	s_and_b32 s5, s4, 0x7fffffc0
	s_lshl_b32 s4, s26, 9
	s_sub_i32 s4, s43, s4
	s_and_b32 s4, s4, 0x3e0
	s_lshl_b32 s26, s4, 2
	v_or_b32_e32 v12, s5, v4
	s_add_u32 s26, s22, s26
	s_addc_u32 s27, s27, 0
	v_mov_b32_e32 v13, v7
	v_or_b32_e32 v18, 2, v12
	v_mov_b32_e32 v19, v7
	v_or_b32_e32 v20, 4, v12
	v_mov_b32_e32 v21, v7
	v_or_b32_e32 v22, 6, v12
	v_mov_b32_e32 v23, v7
	v_or_b32_e32 v24, 8, v12
	v_mov_b32_e32 v25, v7
	v_or_b32_e32 v26, 10, v12
	v_mov_b32_e32 v27, v7
	v_or_b32_e32 v28, 12, v12
	v_mov_b32_e32 v29, v7
	v_or_b32_e32 v56, 14, v12
	v_mov_b32_e32 v57, v7
	v_lshl_add_u64 v[14:15], s[26:27], 0, v[6:7]
	v_lshlrev_b64 v[16:17], 12, v[12:13]
	v_lshlrev_b64 v[18:19], 12, v[18:19]
	v_lshlrev_b64 v[20:21], 12, v[20:21]
	v_lshlrev_b64 v[22:23], 12, v[22:23]
	v_lshlrev_b64 v[24:25], 12, v[24:25]
	v_lshlrev_b64 v[26:27], 12, v[26:27]
	v_lshlrev_b64 v[28:29], 12, v[28:29]
	v_lshlrev_b64 v[56:57], 12, v[56:57]
	v_lshl_add_u64 v[16:17], v[14:15], 0, v[16:17]
	v_lshl_add_u64 v[18:19], v[14:15], 0, v[18:19]
	v_lshl_add_u64 v[20:21], v[14:15], 0, v[20:21]
	v_lshl_add_u64 v[22:23], v[14:15], 0, v[22:23]
	v_lshl_add_u64 v[24:25], v[14:15], 0, v[24:25]
	v_lshl_add_u64 v[26:27], v[14:15], 0, v[26:27]
	v_lshl_add_u64 v[28:29], v[14:15], 0, v[28:29]
	v_lshl_add_u64 v[56:57], v[14:15], 0, v[56:57]
	global_load_dword v9, v[16:17], off nt
	global_load_dword v11, v[18:19], off nt
	global_load_dword v55, v[20:21], off nt
	global_load_dword v58, v[22:23], off nt
	global_load_dword v59, v[24:25], off nt
	global_load_dword v60, v[26:27], off nt
	global_load_dword v61, v[28:29], off nt
	global_load_dword v62, v[56:57], off nt
	v_or_b32_e32 v16, 16, v12
	v_mov_b32_e32 v17, v7
	v_or_b32_e32 v18, 18, v12
	v_mov_b32_e32 v19, v7
	v_or_b32_e32 v20, 20, v12
	v_mov_b32_e32 v21, v7
	v_or_b32_e32 v22, 22, v12
	v_mov_b32_e32 v23, v7
	v_or_b32_e32 v24, 24, v12
	v_mov_b32_e32 v25, v7
	v_or_b32_e32 v26, 26, v12
	v_mov_b32_e32 v27, v7
	v_or_b32_e32 v28, 28, v12
	v_mov_b32_e32 v29, v7
	v_or_b32_e32 v56, 30, v12
	v_mov_b32_e32 v57, v7
	v_lshlrev_b64 v[16:17], 12, v[16:17]
	v_lshlrev_b64 v[18:19], 12, v[18:19]
	v_lshlrev_b64 v[20:21], 12, v[20:21]
	v_lshlrev_b64 v[22:23], 12, v[22:23]
	v_lshlrev_b64 v[24:25], 12, v[24:25]
	v_lshlrev_b64 v[26:27], 12, v[26:27]
	v_lshlrev_b64 v[28:29], 12, v[28:29]
	v_lshlrev_b64 v[56:57], 12, v[56:57]
	v_lshl_add_u64 v[16:17], v[14:15], 0, v[16:17]
	v_lshl_add_u64 v[18:19], v[14:15], 0, v[18:19]
	v_lshl_add_u64 v[20:21], v[14:15], 0, v[20:21]
	v_lshl_add_u64 v[22:23], v[14:15], 0, v[22:23]
	v_lshl_add_u64 v[24:25], v[14:15], 0, v[24:25]
	v_lshl_add_u64 v[26:27], v[14:15], 0, v[26:27]
	v_lshl_add_u64 v[28:29], v[14:15], 0, v[28:29]
	v_lshl_add_u64 v[56:57], v[14:15], 0, v[56:57]
	global_load_dword v63, v[16:17], off nt
	global_load_dword v64, v[18:19], off nt
	global_load_dword v65, v[20:21], off nt
	global_load_dword v66, v[22:23], off nt
	global_load_dword v67, v[24:25], off nt
	global_load_dword v68, v[26:27], off nt
	global_load_dword v69, v[28:29], off nt
	global_load_dword v70, v[56:57], off nt
	v_or_b32_e32 v16, 32, v12
	v_mov_b32_e32 v17, v7
	v_or_b32_e32 v18, 34, v12
	v_mov_b32_e32 v19, v7
	v_or_b32_e32 v20, 36, v12
	v_mov_b32_e32 v21, v7
	v_or_b32_e32 v22, 38, v12
	v_mov_b32_e32 v23, v7
	v_or_b32_e32 v24, 40, v12
	v_mov_b32_e32 v25, v7
	v_or_b32_e32 v26, 42, v12
	v_mov_b32_e32 v27, v7
	v_or_b32_e32 v28, 44, v12
	v_mov_b32_e32 v29, v7
	v_or_b32_e32 v56, 46, v12
	v_mov_b32_e32 v57, v7
	v_lshlrev_b64 v[16:17], 12, v[16:17]
	v_lshlrev_b64 v[18:19], 12, v[18:19]
	v_lshlrev_b64 v[20:21], 12, v[20:21]
	v_lshlrev_b64 v[22:23], 12, v[22:23]
	v_lshlrev_b64 v[24:25], 12, v[24:25]
	v_lshlrev_b64 v[26:27], 12, v[26:27]
	v_lshlrev_b64 v[28:29], 12, v[28:29]
	v_lshlrev_b64 v[56:57], 12, v[56:57]
	v_lshl_add_u64 v[16:17], v[14:15], 0, v[16:17]
	v_lshl_add_u64 v[18:19], v[14:15], 0, v[18:19]
	v_lshl_add_u64 v[20:21], v[14:15], 0, v[20:21]
	v_lshl_add_u64 v[22:23], v[14:15], 0, v[22:23]
	v_lshl_add_u64 v[24:25], v[14:15], 0, v[24:25]
	v_lshl_add_u64 v[26:27], v[14:15], 0, v[26:27]
	v_lshl_add_u64 v[28:29], v[14:15], 0, v[28:29]
	v_lshl_add_u64 v[56:57], v[14:15], 0, v[56:57]
	global_load_dword v71, v[16:17], off nt
	global_load_dword v72, v[18:19], off nt
	global_load_dword v73, v[20:21], off nt
	global_load_dword v74, v[22:23], off nt
	global_load_dword v75, v[24:25], off nt
	global_load_dword v76, v[26:27], off nt
	global_load_dword v77, v[28:29], off nt
	s_nop 0
	global_load_dword v56, v[56:57], off nt
	v_or_b32_e32 v16, 48, v12
	v_mov_b32_e32 v17, v7
	v_or_b32_e32 v18, 50, v12
	v_mov_b32_e32 v19, v7
	v_or_b32_e32 v20, 52, v12
	v_mov_b32_e32 v21, v7
	v_or_b32_e32 v22, 54, v12
	v_or_b32_e32 v24, 56, v12
	v_or_b32_e32 v26, 58, v12
	v_or_b32_e32 v28, 60, v12
	v_or_b32_e32 v12, 62, v12
	v_lshlrev_b64 v[16:17], 12, v[16:17]
	v_lshlrev_b64 v[18:19], 12, v[18:19]
	v_lshlrev_b64 v[20:21], 12, v[20:21]
	v_mov_b32_e32 v23, v7
	v_mov_b32_e32 v25, v7
	v_mov_b32_e32 v27, v7
	v_mov_b32_e32 v29, v7
	v_lshlrev_b64 v[12:13], 12, v[12:13]
	v_lshl_add_u64 v[16:17], v[14:15], 0, v[16:17]
	v_lshl_add_u64 v[18:19], v[14:15], 0, v[18:19]
	v_lshl_add_u64 v[20:21], v[14:15], 0, v[20:21]
	v_lshlrev_b64 v[22:23], 12, v[22:23]
	v_lshlrev_b64 v[24:25], 12, v[24:25]
	v_lshlrev_b64 v[26:27], 12, v[26:27]
	v_lshlrev_b64 v[28:29], 12, v[28:29]
	v_lshl_add_u64 v[12:13], v[14:15], 0, v[12:13]
	v_lshl_add_u64 v[22:23], v[14:15], 0, v[22:23]
	v_lshl_add_u64 v[24:25], v[14:15], 0, v[24:25]
	v_lshl_add_u64 v[26:27], v[14:15], 0, v[26:27]
	v_lshl_add_u64 v[28:29], v[14:15], 0, v[28:29]
	global_load_dword v14, v[16:17], off nt
	global_load_dword v15, v[18:19], off nt
	s_nop 0
	global_load_dword v16, v[20:21], off nt
	global_load_dword v17, v[22:23], off nt
	global_load_dword v18, v[24:25], off nt
	global_load_dword v19, v[26:27], off nt
	s_nop 0
	global_load_dword v20, v[28:29], off nt
	s_nop 0
	global_load_dword v12, v[12:13], off nt
	s_waitcnt vmcnt(30)
; #define LAS __attribute__((address_space(3)))
; __device__ __forceinline__ unsigned pk2(float lo, float hi) { return pg8::cvt_pk_bf16(lo, hi); }
; __device__ __forceinline__ void lds_wait() { asm volatile("s_waitcnt lgkmcnt(0)" ::: "memory"); }
; __device__ __forceinline__ void transpose_item(const float* W, int N, bf16* WT, int K, int k0, int n0, int drow0, const float* gk, LAS float* scr, int lane) {
;     ...
;     for (int i = 0; i < 32; ++i) { const int kk = 2 * i + (lane >> 5); float v = wv[i]; if (gk) v *= gk[kk]; scr[kk * 33 + (lane & 31)] = v; }
;     lds_wait();
;     const int c = lane & 7;
; #pragma unroll
;     for (int j = 0; j < 4; ++j) { const int n = (lane >> 3) + 8 * j; const LAS float* s = scr + (8 * c) * 33 + n;
;         u32x4 o; o.x = pk2(s[0 * 33], s[1 * 33]); o.y = pk2(s[2 * 33], s[3 * 33]); o.z = pk2(s[4 * 33], s[5 * 33]); o.w = pk2(s[6 * 33], s[7 * 33]);
;         *(u32x4*)(WT + (size_t)(drow0 + n) * K + k0 + 8 * c) = o; }
;     lds_wait();
	ds_write2_b32 v5, v9, v11 offset1:66
	s_waitcnt vmcnt(28)
	ds_write2_b32 v5, v55, v58 offset0:132 offset1:198
	s_waitcnt vmcnt(26)
	ds_write2_b32 v48, v59, v60 offset0:8 offset1:74
	s_waitcnt vmcnt(24)
	ds_write2_b32 v48, v61, v62 offset0:140 offset1:206
	s_waitcnt vmcnt(22)
	ds_write2_b32 v49, v63, v64 offset0:16 offset1:82
	s_waitcnt vmcnt(20)
	ds_write2_b32 v49, v65, v66 offset0:148 offset1:214
	s_waitcnt vmcnt(18)
	ds_write2_b32 v50, v67, v68 offset0:24 offset1:90
	s_waitcnt vmcnt(16)
	ds_write2_b32 v50, v69, v70 offset0:156 offset1:222
	s_waitcnt vmcnt(14)
	ds_write2_b32 v51, v71, v72 offset0:32 offset1:98
	s_waitcnt vmcnt(12)
	ds_write2_b32 v51, v73, v74 offset0:164 offset1:230
	s_waitcnt vmcnt(10)
	ds_write2_b32 v52, v75, v76 offset0:40 offset1:106
	s_waitcnt vmcnt(8)
	ds_write2_b32 v52, v77, v56 offset0:172 offset1:238
	s_waitcnt vmcnt(6)
	ds_write2_b32 v53, v14, v15 offset0:48 offset1:114
	s_waitcnt vmcnt(4)
	ds_write2_b32 v53, v16, v17 offset0:180 offset1:246
	s_waitcnt vmcnt(2)
	ds_write2_b32 v54, v18, v19 offset0:56 offset1:122
	s_waitcnt vmcnt(0)
	ds_write2_b32 v54, v20, v12 offset0:188 offset1:254
	s_lshl_b32 s5, s5, 1
	s_waitcnt lgkmcnt(0)
	s_add_u32 s26, s84, s5
	ds_read2_b32 v[12:13], v31 offset1:33
	ds_read2_b32 v[204:205], v31 offset0:66 offset1:99
	ds_read2_b32 v[206:207], v31 offset0:132 offset1:165
	ds_read2_b32 v[208:209], v31 offset0:198 offset1:231
	ds_read2_b32 v[210:211], v31 offset0:8 offset1:41
	ds_read2_b32 v[212:213], v31 offset0:74 offset1:107
	ds_read2_b32 v[214:215], v31 offset0:140 offset1:173
	ds_read2_b32 v[216:217], v31 offset0:206 offset1:239
	s_addc_u32 s27, s83, 0
	v_mov_b32_e32 v11, v7
	v_or_b32_e32 v9, s4, v30
	s_waitcnt lgkmcnt(7)
	v_cvt_pk_bf16_f32 v12, v12, v13
	ds_read2_b32 v[218:219], v31 offset0:16 offset1:49
	v_lshl_add_u64 v[18:19], s[26:27], 0, v[10:11]
	s_mov_b64 s[26:27], 0xb00000
	v_mul_u32_u24_e32 v9, 0xb00, v9
	s_waitcnt lgkmcnt(7)
	v_cvt_pk_bf16_f32 v13, v204, v205
	ds_read2_b32 v[204:205], v31 offset0:82 offset1:115
	v_lshl_add_u64 v[18:19], v[18:19], 0, s[26:27]
	v_lshlrev_b32_e32 v20, 1, v9
	v_mov_b32_e32 v21, v7
	s_waitcnt lgkmcnt(7)
	v_cvt_pk_bf16_f32 v14, v206, v207
	ds_read2_b32 v[206:207], v31 offset0:148 offset1:181
	s_waitcnt lgkmcnt(7)
	v_cvt_pk_bf16_f32 v15, v208, v209
	ds_read2_b32 v[208:209], v31 offset0:214 offset1:247
	v_lshl_add_u64 v[20:21], v[18:19], 0, v[20:21]
	v_or_b32_e32 v9, s4, v32
	global_store_dwordx4 v[20:21], v[12:15], off sc1
	v_mul_u32_u24_e32 v9, 0xb00, v9
	v_lshlrev_b32_e32 v20, 1, v9
	s_waitcnt lgkmcnt(7)
	v_cvt_pk_bf16_f32 v12, v210, v211
	ds_read2_b32 v[210:211], v31 offset0:24 offset1:57
	s_waitcnt lgkmcnt(7)
	v_cvt_pk_bf16_f32 v13, v212, v213
	ds_read2_b32 v[212:213], v31 offset0:90 offset1:123
	v_mov_b32_e32 v21, v7
	s_waitcnt lgkmcnt(7)
	v_cvt_pk_bf16_f32 v14, v214, v215
	ds_read2_b32 v[214:215], v31 offset0:156 offset1:189
	s_waitcnt lgkmcnt(7)
	v_cvt_pk_bf16_f32 v15, v216, v217
	ds_read2_b32 v[216:217], v31 offset0:222 offset1:255
	v_lshl_add_u64 v[20:21], v[18:19], 0, v[20:21]
	v_or_b32_e32 v9, s4, v33
	global_store_dwordx4 v[20:21], v[12:15], off sc1
	v_mul_u32_u24_e32 v9, 0xb00, v9
	v_lshlrev_b32_e32 v20, 1, v9
	s_waitcnt lgkmcnt(7)
	v_cvt_pk_bf16_f32 v12, v218, v219
	s_waitcnt lgkmcnt(6)
	v_cvt_pk_bf16_f32 v13, v204, v205
	v_mov_b32_e32 v21, v7
	s_waitcnt lgkmcnt(5)
	v_cvt_pk_bf16_f32 v14, v206, v207
	s_waitcnt lgkmcnt(4)
	v_cvt_pk_bf16_f32 v15, v208, v209
	v_lshl_add_u64 v[20:21], v[18:19], 0, v[20:21]
	global_store_dwordx4 v[20:21], v[12:15], off sc1
	v_or_b32_e32 v9, s4, v34
	v_mul_u32_u24_e32 v9, 0xb00, v9
	s_waitcnt lgkmcnt(3)
	v_cvt_pk_bf16_f32 v12, v210, v211
	s_waitcnt lgkmcnt(2)
	v_cvt_pk_bf16_f32 v13, v212, v213
	s_waitcnt lgkmcnt(1)
	v_cvt_pk_bf16_f32 v14, v214, v215
	s_waitcnt lgkmcnt(0)
	v_cvt_pk_bf16_f32 v15, v216, v217
	v_lshlrev_b32_e32 v16, 1, v9
	v_mov_b32_e32 v17, v7
	v_lshl_add_u64 v[16:17], v[18:19], 0, v[16:17]
	global_store_dwordx4 v[16:17], v[12:15], off sc1
	s_waitcnt lgkmcnt(0)
	v_readlane_b32 s53, v250, 12
	v_readlane_b32 s54, v250, 13
	v_readlane_b32 s55, v250, 14
	v_readlane_b32 s56, v250, 15
	v_readlane_b32 s57, v250, 16
	v_readlane_b32 s58, v250, 17
	v_readlane_b32 s59, v250, 18
	v_readlane_b32 s62, v250, 21
	v_readlane_b32 s63, v250, 22
	v_readlane_b32 s64, v250, 23
	v_readlane_b32 s65, v250, 24
	v_readlane_b32 s66, v250, 25
	v_readlane_b32 s67, v250, 26

; #define LAS __attribute__((address_space(3)))
; __device__ __forceinline__ unsigned pk2(float lo, float hi) { return pg8::cvt_pk_bf16(lo, hi); }
; __device__ __forceinline__ void lds_wait() { asm volatile("s_waitcnt lgkmcnt(0)" ::: "memory"); }
; __device__ __forceinline__ void transpose_item(const float* W, int N, bf16* WT, int K, int k0, int n0, int drow0, const float* gk, LAS float* scr, int lane) {
;     ...
;     for (int i = 0; i < 32; ++i) { const int kk = 2 * i + (lane >> 5); float v = wv[i]; if (gk) v *= gk[kk]; scr[kk * 33 + (lane & 31)] = v; }
;     lds_wait();
;     const int c = lane & 7;
; #pragma unroll
;     for (int j = 0; j < 4; ++j) { const int n = (lane >> 3) + 8 * j; const LAS float* s = scr + (8 * c) * 33 + n;
;         u32x4 o; o.x = pk2(s[0 * 33], s[1 * 33]); o.y = pk2(s[2 * 33], s[3 * 33]); o.z = pk2(s[4 * 33], s[5 * 33]); o.w = pk2(s[6 * 33], s[7 * 33]);
;         *(u32x4*)(WT + (size_t)(drow0 + n) * K + k0 + 8 * c) = o; }
; __device__ __forceinline__ void p0_weight_item(const Args& a, int l, int r, LAS float* scr, int lane) {
;     ...
;             transpose_item(W, FF, gu, DM, k0, n0, (n0 >> 7) * 256 + up * 128 + (n0 & 127), nrm + k0, scr, lane); return; }
.LBB0_1029:
	s_lshl_b32 s0, s24, 6
	s_and_b32 s7, s0, 0xffffff00
	s_and_b64 s[0:1], s[4:5], exec
	s_cselect_b32 s0, 0x80, 0
	s_and_b32 s1, s6, 0x60
	s_or_b32 s0, s7, s0
	ds_write2_b32 v38, v36, v37 offset0:140 offset1:206
	s_or_b32 s0, s0, s1
	s_waitcnt lgkmcnt(0)
	v_or_b32_e32 v42, s0, v5
	ds_read2_b32 v[34:35], v52 offset1:33
	ds_read2_b32 v[204:205], v52 offset0:66 offset1:99
	ds_read2_b32 v[206:207], v52 offset0:132 offset1:165
	ds_read2_b32 v[208:209], v52 offset0:198 offset1:231
	ds_read2_b32 v[210:211], v52 offset0:8 offset1:41
	ds_read2_b32 v[212:213], v52 offset0:74 offset1:107
	ds_read2_b32 v[214:215], v52 offset0:140 offset1:173
	ds_read2_b32 v[216:217], v52 offset0:206 offset1:239
	v_ashrrev_i32_e32 v43, 31, v42
	s_waitcnt lgkmcnt(7)
	v_cvt_pk_bf16_f32 v34, v34, v35
	ds_read2_b32 v[218:219], v52 offset0:16 offset1:49
	v_lshl_add_u64 v[38:39], s[28:29], 1, v[8:9]
	v_lshlrev_b64 v[42:43], 11, v[42:43]
	s_waitcnt lgkmcnt(7)
	v_cvt_pk_bf16_f32 v35, v204, v205
	ds_read2_b32 v[204:205], v52 offset0:82 offset1:115
	v_lshl_add_u64 v[42:43], v[38:39], 0, v[42:43]
	s_waitcnt lgkmcnt(7)
	v_cvt_pk_bf16_f32 v36, v206, v207
	ds_read2_b32 v[206:207], v52 offset0:148 offset1:181
	s_waitcnt lgkmcnt(7)
	v_cvt_pk_bf16_f32 v37, v208, v209
	ds_read2_b32 v[208:209], v52 offset0:214 offset1:247
	global_store_dwordx4 v[42:43], v[34:37], off sc1
	v_or_b32_e32 v42, s0, v53
	v_ashrrev_i32_e32 v43, 31, v42
	s_waitcnt lgkmcnt(7)
	v_cvt_pk_bf16_f32 v34, v210, v211
	ds_read2_b32 v[210:211], v52 offset0:24 offset1:57
	v_lshlrev_b64 v[42:43], 11, v[42:43]
	s_waitcnt lgkmcnt(7)
	v_cvt_pk_bf16_f32 v35, v212, v213
	ds_read2_b32 v[212:213], v52 offset0:90 offset1:123
	v_lshl_add_u64 v[42:43], v[38:39], 0, v[42:43]
	s_waitcnt lgkmcnt(7)
	v_cvt_pk_bf16_f32 v36, v214, v215
	ds_read2_b32 v[214:215], v52 offset0:156 offset1:189
	s_waitcnt lgkmcnt(7)
	v_cvt_pk_bf16_f32 v37, v216, v217
	global_store_dwordx4 v[42:43], v[34:37], off sc1
	v_or_b32_e32 v42, s0, v54
	v_ashrrev_i32_e32 v43, 31, v42
	s_waitcnt lgkmcnt(6)
	v_cvt_pk_bf16_f32 v34, v218, v219
	v_lshlrev_b64 v[42:43], 11, v[42:43]
	s_waitcnt lgkmcnt(5)
	v_cvt_pk_bf16_f32 v35, v204, v205
	v_lshl_add_u64 v[42:43], v[38:39], 0, v[42:43]
	s_waitcnt lgkmcnt(4)
	v_cvt_pk_bf16_f32 v36, v206, v207
	s_waitcnt lgkmcnt(3)
	v_cvt_pk_bf16_f32 v37, v208, v209
	global_store_dwordx4 v[42:43], v[34:37], off sc1
	v_or_b32_e32 v42, s0, v55
	v_ashrrev_i32_e32 v43, 31, v42
	s_waitcnt lgkmcnt(2)
	v_cvt_pk_bf16_f32 v34, v210, v211
	ds_read2_b32 v[40:41], v52 offset0:222 offset1:255
	v_lshlrev_b64 v[42:43], 11, v[42:43]
	s_waitcnt lgkmcnt(2)
	v_cvt_pk_bf16_f32 v35, v212, v213
	v_lshl_add_u64 v[38:39], v[38:39], 0, v[42:43]
	s_waitcnt lgkmcnt(1)
	v_cvt_pk_bf16_f32 v36, v214, v215
	s_waitcnt lgkmcnt(0)
	v_cvt_pk_bf16_f32 v37, v40, v41
	global_store_dwordx4 v[38:39], v[34:37], off sc1
	s_waitcnt lgkmcnt(0)

; __device__ __forceinline__ void p0_weight_item(const Args& a, int l, int r, LAS float* scr, int lane) {
;     ...
;         if (r < 2 * IT_BIG) { const int up = r >= IT_BIG; const int it = r - up * IT_BIG; const int kb = it / 88, nb = it % 88, k0 = 64 * kb, n0 = 32 * nb;
;             const float* W = a.in[(f ? 29 : 2) + up] + (size_t)l * DM * FF;
;             transpose_item(W, FF, gu, DM, k0, n0, (n0 >> 7) * 256 + up * 128 + (n0 & 127), nrm + k0, scr, lane); return; }
;         r -= 2 * IT_BIG;
;         if (r < IT_BIG) { const int kb = r / 32, nb = r % 32; const float* W = a.in[f ? 31 : 4] + (size_t)l * FF * DM;
;             transpose_item(W, DM, dn, FF, 64 * kb, 32 * nb, 32 * nb, nullptr, scr, lane); return; }
;         r -= IT_BIG;
;     }
;     if (r < IT_BIG) {
;         const int kb = r / 88, nb = r % 88, k0 = 64 * kb, n0 = 32 * nb; const int tile = n0 >> 8, c0 = n0 & 255;
;         int drow = n0;
;         if (tile >= 1 && tile <= 4) { const int hh = c0 >> 7, d0 = c0 & 127, bj = d0 >> 6, dd0 = d0 & 63; drow = tile * 256 + bj * 128 + hh * 64 + dd0; }
;         transpose_item(a.in[6] + (size_t)l * DM * IW, IW, (bf16*)(wl + WL_WIN), DM, k0, n0, drow, a.in[5] + (size_t)l * DM + k0, scr, lane); return; }
;     r -= IT_BIG;
;     if (r < IT_OUT) {
;         const int kb = r / 32, nb = r % 32, k0 = 64 * kb;
;         const float* gk = (k0 < 256) ? a.in[17] + (size_t)l * 256 + k0 : (k0 < 768 ? a.in[18] + (size_t)l * 512 + (k0 - 256) : a.in[26] + (size_t)l * 256 + (k0 - 768));
;         transpose_item(a.in[27] + (size_t)l * DM * DM, DM, (bf16*)(wl + WL_WOUT), DM, k0, 32 * nb, 32 * nb, gk, scr, lane); return; }
;     r -= IT_OUT;
;     if (r < IT_GLU) { const int kb = r / 8, nb = r % 8; transpose_item(a.in[15] + (size_t)l * 65536, 256, (bf16*)(wl + WL_GLU), 256, 64 * kb, 32 * nb, 32 * nb, nullptr, scr, lane); return; }
;     r -= IT_GLU;
;     if (r < IT_LW) { const int blk = r >> 1, nb = r & 1; transpose_item(a.in[21] + (size_t)l * 16384 + blk * 4096, 64, (bf16*)(wl + WL_WA) + blk * 4096, 64, 0, 32 * nb, 32 * nb, nullptr, scr, lane); return; }
;     r -= IT_LW;
;     { const int blk = r >> 1, nb = r & 1; transpose_item(a.in[23] + (size_t)l * 16384 + blk * 4096, 64, (bf16*)(wl + WL_WX) + blk * 4096, 64, 0, 32 * nb, 32 * nb, nullptr, scr, lane); }
.LBB0_1031:
	s_add_i32 s39, s27, 0x2100
	s_cmpk_gt_i32 s39, 0xaff
	s_mov_b64 s[0:1], -1
	s_cbranch_scc0 .LBB0_1143
	s_cmpk_gt_u32 s39, 0x107f
	s_cbranch_scc0 .LBB0_1140
	s_cmpk_gt_u32 s39, 0x1b7f
	s_cbranch_scc0 .LBB0_1113
	s_add_i32 s0, s27, 0x1080
	s_cmpk_lt_u32 s0, 0x1080
	s_mov_b64 s[0:1], -1
	s_cbranch_scc1 .LBB0_1110
	s_cmpk_gt_u32 s39, 0x267f
	s_cbranch_scc0 .LBB0_1081
	s_cmpk_gt_u32 s27, 0x77f
	s_cbranch_scc0 .LBB0_1046
	s_cmpk_gt_u32 s27, 0x79f
	s_cbranch_scc0 .LBB0_1043
	s_add_i32 s0, s35, 0xfffba000
	s_and_b32 s4, s0, 32
	s_cmpk_gt_u32 s27, 0x7a7
	s_mov_b64 s[0:1], -1
	v_lshlrev_b32_e32 v34, 2, v4
	v_or_b32_e32 v39, s4, v5
	v_or_b32_e32 v38, s4, v53
	v_or_b32_e32 v37, s4, v54
	v_or_b32_e32 v36, s4, v55
	s_cbranch_scc0 .LBB0_1040
	s_and_b32 s0, s34, 0x7ffff000
	s_add_i32 s82, s0, 0xffc2c000
	s_lshl_b64 s[0:1], s[82:83], 2
	v_readlane_b32 s5, v253, 55
	s_add_u32 s0, s5, s0
	v_readlane_b32 s5, v253, 56
	s_addc_u32 s1, s5, s1
	s_lshl_b32 s5, s4, 2
	s_add_u32 s0, s0, s5
	s_addc_u32 s1, s1, 0
	v_lshlrev_b32_e32 v144, 2, v2
	v_lshl_add_u64 v[40:41], s[0:1], 0, v[144:145]
	v_mov_b32_e32 v35, v145
	v_lshl_add_u64 v[40:41], v[40:41], 0, v[34:35]
	s_movk_i32 s0, 0x1000
	global_load_dword v35, v[40:41], off nt
	global_load_dword v46, v[40:41], off offset:512 nt
	global_load_dword v47, v[40:41], off offset:1024 nt
	global_load_dword v48, v[40:41], off offset:1536 nt
	global_load_dword v49, v[40:41], off offset:2048 nt
	global_load_dword v50, v[40:41], off offset:2560 nt
	global_load_dword v51, v[40:41], off offset:3072 nt
	global_load_dword v69, v[40:41], off offset:3584 nt
	v_add_co_u32_e32 v42, vcc, s0, v40
	s_movk_i32 s0, 0x2000
	s_nop 0
	v_addc_co_u32_e32 v43, vcc, 0, v41, vcc
	v_add_co_u32_e32 v44, vcc, s0, v40
	s_movk_i32 s0, 0x3000
	s_nop 0
	v_addc_co_u32_e32 v45, vcc, 0, v41, vcc
	global_load_dword v70, v[44:45], off offset:-4096 nt
	global_load_dword v71, v[42:43], off offset:512 nt
	global_load_dword v72, v[42:43], off offset:1024 nt
	global_load_dword v73, v[42:43], off offset:1536 nt
	global_load_dword v74, v[42:43], off offset:2048 nt
	global_load_dword v75, v[42:43], off offset:2560 nt
	global_load_dword v76, v[42:43], off offset:3072 nt
	s_nop 0
	global_load_dword v42, v[42:43], off offset:3584 nt
	s_nop 0
	global_load_dword v43, v[44:45], off nt
	global_load_dword v77, v[44:45], off offset:512 nt
	global_load_dword v78, v[44:45], off offset:1024 nt
	global_load_dword v79, v[44:45], off offset:1536 nt
	global_load_dword v80, v[44:45], off offset:2048 nt
	global_load_dword v81, v[44:45], off offset:2560 nt
	global_load_dword v82, v[44:45], off offset:3072 nt
	s_nop 0
	global_load_dword v44, v[44:45], off offset:3584 nt
	v_add_co_u32_e32 v40, vcc, s0, v40
	v_lshlrev_b32_e32 v144, 7, v39
	s_nop 0
	v_addc_co_u32_e32 v41, vcc, 0, v41, vcc
	global_load_dword v45, v[40:41], off nt
	global_load_dword v83, v[40:41], off offset:512 nt
	global_load_dword v84, v[40:41], off offset:1024 nt
	global_load_dword v85, v[40:41], off offset:1536 nt
	global_load_dword v86, v[40:41], off offset:2048 nt
	global_load_dword v87, v[40:41], off offset:2560 nt
	global_load_dword v88, v[40:41], off offset:3072 nt
	s_nop 0
	global_load_dword v40, v[40:41], off offset:3584 nt
	s_mov_b64 s[0:1], 0
	s_waitcnt vmcnt(0)
	ds_write2_b32 v3, v35, v46 offset1:66
	ds_write2_b32 v3, v47, v48 offset0:132 offset1:198
	v_add_u32_e32 v35, 0x400, v3
	ds_write2_b32 v35, v49, v50 offset0:8 offset1:74
	ds_write2_b32 v35, v51, v69 offset0:140 offset1:206
	v_add_u32_e32 v35, 0x800, v3
	ds_write2_b32 v35, v70, v71 offset0:16 offset1:82
	ds_write2_b32 v35, v72, v73 offset0:148 offset1:214
	v_add_u32_e32 v35, 0xc00, v3
	ds_write2_b32 v35, v74, v75 offset0:24 offset1:90
	ds_write2_b32 v35, v76, v42 offset0:156 offset1:222
	v_add_u32_e32 v35, 0x1000, v3
	ds_write2_b32 v35, v43, v77 offset0:32 offset1:98
	ds_write2_b32 v35, v78, v79 offset0:164 offset1:230
	v_add_u32_e32 v35, 0x1400, v3
	ds_write2_b32 v35, v80, v81 offset0:40 offset1:106
	ds_write2_b32 v35, v82, v44 offset0:172 offset1:238
	v_add_u32_e32 v35, 0x1800, v3
	ds_write2_b32 v35, v45, v83 offset0:48 offset1:114
	ds_write2_b32 v35, v84, v85 offset0:180 offset1:246
	v_add_u32_e32 v35, 0x1c00, v3
	ds_write2_b32 v35, v86, v87 offset0:56 offset1:122
	ds_write2_b32 v35, v88, v40 offset0:188 offset1:254
	s_waitcnt lgkmcnt(0)
	ds_read2_b32 v[40:41], v52 offset1:33
	ds_read2_b32 v[204:205], v52 offset0:66 offset1:99
	ds_read2_b32 v[206:207], v52 offset0:132 offset1:165
	ds_read2_b32 v[208:209], v52 offset0:198 offset1:231
	ds_read2_b32 v[210:211], v52 offset0:8 offset1:41
	ds_read2_b32 v[212:213], v52 offset0:74 offset1:107
	ds_read2_b32 v[214:215], v52 offset0:140 offset1:173
	ds_read2_b32 v[216:217], v52 offset0:206 offset1:239
	s_waitcnt lgkmcnt(7)
	v_cvt_pk_bf16_f32 v40, v40, v41
	ds_read2_b32 v[218:219], v52 offset0:16 offset1:49
	s_waitcnt lgkmcnt(7)
	v_cvt_pk_bf16_f32 v41, v204, v205
	ds_read2_b32 v[204:205], v52 offset0:82 offset1:115
	v_lshl_add_u64 v[44:45], s[82:83], 1, v[10:11]
	s_waitcnt lgkmcnt(7)
	v_cvt_pk_bf16_f32 v42, v206, v207
	ds_read2_b32 v[206:207], v52 offset0:148 offset1:181
	s_waitcnt lgkmcnt(7)
	v_cvt_pk_bf16_f32 v43, v208, v209
	ds_read2_b32 v[208:209], v52 offset0:214 offset1:247
	v_lshl_add_u64 v[46:47], v[44:45], 0, v[144:145]
	global_store_dwordx4 v[46:47], v[40:43], off sc1
	v_lshlrev_b32_e32 v144, 7, v38
	s_waitcnt lgkmcnt(7)
	v_cvt_pk_bf16_f32 v40, v210, v211
	ds_read2_b32 v[210:211], v52 offset0:24 offset1:57
	s_waitcnt lgkmcnt(7)
	v_cvt_pk_bf16_f32 v41, v212, v213
	ds_read2_b32 v[212:213], v52 offset0:90 offset1:123
	s_waitcnt lgkmcnt(7)
	v_cvt_pk_bf16_f32 v42, v214, v215
	ds_read2_b32 v[214:215], v52 offset0:156 offset1:189
	s_waitcnt lgkmcnt(7)
	v_cvt_pk_bf16_f32 v43, v216, v217
	v_lshl_add_u64 v[46:47], v[44:45], 0, v[144:145]
	global_store_dwordx4 v[46:47], v[40:43], off sc1
	v_lshlrev_b32_e32 v144, 7, v37
	s_waitcnt lgkmcnt(6)
	v_cvt_pk_bf16_f32 v40, v218, v219
	s_waitcnt lgkmcnt(5)
	v_cvt_pk_bf16_f32 v41, v204, v205
	s_waitcnt lgkmcnt(4)
	v_cvt_pk_bf16_f32 v42, v206, v207
	s_waitcnt lgkmcnt(3)
	v_cvt_pk_bf16_f32 v43, v208, v209
	v_lshl_add_u64 v[46:47], v[44:45], 0, v[144:145]
	global_store_dwordx4 v[46:47], v[40:43], off sc1
	ds_read2_b32 v[46:47], v52 offset0:222 offset1:255
	v_lshlrev_b32_e32 v144, 7, v36
	s_waitcnt lgkmcnt(3)
	v_cvt_pk_bf16_f32 v40, v210, v211
	s_waitcnt lgkmcnt(2)
	v_cvt_pk_bf16_f32 v41, v212, v213
	v_lshl_add_u64 v[44:45], v[44:45], 0, v[144:145]
	s_waitcnt lgkmcnt(1)
	v_cvt_pk_bf16_f32 v42, v214, v215
	s_waitcnt lgkmcnt(0)
	v_cvt_pk_bf16_f32 v43, v46, v47
	global_store_dwordx4 v[44:45], v[40:43], off sc1
	s_waitcnt lgkmcnt(0)
; #define LAS __attribute__((address_space(3)))
; __device__ __forceinline__ unsigned pk2(float lo, float hi) { return pg8::cvt_pk_bf16(lo, hi); }
; __device__ __forceinline__ void lds_wait() { asm volatile("s_waitcnt lgkmcnt(0)" ::: "memory"); }
; __device__ __forceinline__ void transpose_item(const float* W, int N, bf16* WT, int K, int k0, int n0, int drow0, const float* gk, LAS float* scr, int lane) {
;     float wv[32];
; #pragma unroll
;     for (int i = 0; i < 32; ++i) wv[i] = W[(size_t)(k0 + 2 * i + (lane >> 5)) * N + n0 + (lane & 31)];
; #pragma unroll
;     for (int i = 0; i < 32; ++i) { const int kk = 2 * i + (lane >> 5); float v = wv[i]; if (gk) v *= gk[kk]; scr[kk * 33 + (lane & 31)] = v; }
;     lds_wait();
;     const int c = lane & 7;
; #pragma unroll
;     for (int j = 0; j < 4; ++j) { const int n = (lane >> 3) + 8 * j; const LAS float* s = scr + (8 * c) * 33 + n;
;         u32x4 o; o.x = pk2(s[0 * 33], s[1 * 33]); o.y = pk2(s[2 * 33], s[3 * 33]); o.z = pk2(s[4 * 33], s[5 * 33]); o.w = pk2(s[6 * 33], s[7 * 33]);
;         *(u32x4*)(WT + (size_t)(drow0 + n) * K + k0 + 8 * c) = o; }
;     lds_wait();
; __device__ __forceinline__ void p0_weight_item(const Args& a, int l, int r, LAS float* scr, int lane) {
;     ...
;     if (r < IT_LW) { const int blk = r >> 1, nb = r & 1; transpose_item(a.in[21] + (size_t)l * 16384 + blk * 4096, 64, (bf16*)(wl + WL_WA) + blk * 4096, 64, 0, 32 * nb, 32 * nb, nullptr, scr, lane); return; }
.LBB0_1040:
	s_andn2_b64 vcc, exec, s[0:1]
	s_cbranch_vccnz .LBB0_1042
	s_and_b32 s0, s34, 0x3ff000
	s_add_i32 s82, s0, 0xffc30000
	s_lshl_b64 s[0:1], s[82:83], 2
	v_readlane_b32 s5, v253, 59
	s_add_u32 s0, s5, s0
	v_readlane_b32 s5, v253, 60
	s_addc_u32 s1, s5, s1
	s_lshl_b32 s4, s4, 2
	s_add_u32 s0, s0, s4
	s_addc_u32 s1, s1, 0
	v_lshlrev_b32_e32 v144, 2, v2
	v_lshl_add_u64 v[40:41], s[0:1], 0, v[144:145]
	v_mov_b32_e32 v35, v145
	v_lshl_add_u64 v[34:35], v[40:41], 0, v[34:35]
	s_movk_i32 s0, 0x1000
	global_load_dword v44, v[34:35], off nt
	global_load_dword v45, v[34:35], off offset:512 nt
	global_load_dword v46, v[34:35], off offset:1024 nt
	global_load_dword v47, v[34:35], off offset:1536 nt
	global_load_dword v48, v[34:35], off offset:2048 nt
	global_load_dword v49, v[34:35], off offset:2560 nt
	global_load_dword v50, v[34:35], off offset:3072 nt
	global_load_dword v51, v[34:35], off offset:3584 nt
	v_add_co_u32_e32 v40, vcc, s0, v34
	s_movk_i32 s0, 0x2000
	s_nop 0
	v_addc_co_u32_e32 v41, vcc, 0, v35, vcc
	v_add_co_u32_e32 v42, vcc, s0, v34
	s_movk_i32 s0, 0x3000
	s_nop 0
	v_addc_co_u32_e32 v43, vcc, 0, v35, vcc
	global_load_dword v69, v[42:43], off offset:-4096 nt
	global_load_dword v70, v[40:41], off offset:512 nt
	global_load_dword v71, v[40:41], off offset:1024 nt
	global_load_dword v72, v[40:41], off offset:1536 nt
	global_load_dword v73, v[40:41], off offset:2048 nt
	global_load_dword v74, v[40:41], off offset:2560 nt
	global_load_dword v75, v[40:41], off offset:3072 nt
	s_nop 0
	global_load_dword v40, v[40:41], off offset:3584 nt
	s_nop 0
	global_load_dword v41, v[42:43], off nt
	global_load_dword v76, v[42:43], off offset:512 nt
	global_load_dword v77, v[42:43], off offset:1024 nt
	global_load_dword v78, v[42:43], off offset:1536 nt
	global_load_dword v79, v[42:43], off offset:2048 nt
	global_load_dword v80, v[42:43], off offset:2560 nt
	global_load_dword v81, v[42:43], off offset:3072 nt
	s_nop 0
	global_load_dword v42, v[42:43], off offset:3584 nt
	v_add_co_u32_e32 v34, vcc, s0, v34
	v_lshlrev_b32_e32 v144, 7, v39
	s_nop 0
	v_addc_co_u32_e32 v35, vcc, 0, v35, vcc
	global_load_dword v43, v[34:35], off nt
	global_load_dword v82, v[34:35], off offset:512 nt
	global_load_dword v83, v[34:35], off offset:1024 nt
	global_load_dword v84, v[34:35], off offset:1536 nt
	global_load_dword v85, v[34:35], off offset:2048 nt
	global_load_dword v86, v[34:35], off offset:2560 nt
	global_load_dword v87, v[34:35], off offset:3072 nt
	s_nop 0
	global_load_dword v34, v[34:35], off offset:3584 nt
	v_add_u32_e32 v35, 0x400, v3
	s_waitcnt vmcnt(0)
	ds_write2_b32 v3, v44, v45 offset1:66
	ds_write2_b32 v3, v46, v47 offset0:132 offset1:198
	ds_write2_b32 v35, v48, v49 offset0:8 offset1:74
	ds_write2_b32 v35, v50, v51 offset0:140 offset1:206
	v_add_u32_e32 v35, 0x800, v3
	ds_write2_b32 v35, v69, v70 offset0:16 offset1:82
	ds_write2_b32 v35, v71, v72 offset0:148 offset1:214
	v_add_u32_e32 v35, 0xc00, v3
	ds_write2_b32 v35, v73, v74 offset0:24 offset1:90
	ds_write2_b32 v35, v75, v40 offset0:156 offset1:222
	v_add_u32_e32 v35, 0x1000, v3
	ds_write2_b32 v35, v41, v76 offset0:32 offset1:98
	ds_write2_b32 v35, v77, v78 offset0:164 offset1:230
	v_add_u32_e32 v35, 0x1400, v3
	ds_write2_b32 v35, v79, v80 offset0:40 offset1:106
	ds_write2_b32 v35, v81, v42 offset0:172 offset1:238
	v_add_u32_e32 v35, 0x1800, v3
	ds_write2_b32 v35, v43, v82 offset0:48 offset1:114
	ds_write2_b32 v35, v83, v84 offset0:180 offset1:246
	v_add_u32_e32 v35, 0x1c00, v3
	ds_write2_b32 v35, v85, v86 offset0:56 offset1:122
	ds_write2_b32 v35, v87, v34 offset0:188 offset1:254
	s_waitcnt lgkmcnt(0)
	ds_read2_b32 v[40:41], v52 offset1:33
	ds_read2_b32 v[204:205], v52 offset0:66 offset1:99
	ds_read2_b32 v[206:207], v52 offset0:132 offset1:165
	ds_read2_b32 v[208:209], v52 offset0:198 offset1:231
	ds_read2_b32 v[210:211], v52 offset0:8 offset1:41
	ds_read2_b32 v[212:213], v52 offset0:74 offset1:107
	ds_read2_b32 v[214:215], v52 offset0:140 offset1:173
	ds_read2_b32 v[216:217], v52 offset0:16 offset1:49
	s_waitcnt lgkmcnt(7)
	v_cvt_pk_bf16_f32 v40, v40, v41
	ds_read2_b32 v[218:219], v52 offset0:82 offset1:115
	s_waitcnt lgkmcnt(7)
	v_cvt_pk_bf16_f32 v41, v204, v205
	ds_read2_b32 v[204:205], v52 offset0:148 offset1:181
	v_lshl_add_u64 v[34:35], s[82:83], 1, v[12:13]
	s_waitcnt lgkmcnt(7)
	v_cvt_pk_bf16_f32 v42, v206, v207
	ds_read2_b32 v[206:207], v52 offset0:214 offset1:247
	s_waitcnt lgkmcnt(7)
	v_cvt_pk_bf16_f32 v43, v208, v209
	ds_read2_b32 v[208:209], v52 offset0:24 offset1:57
	v_lshl_add_u64 v[44:45], v[34:35], 0, v[144:145]
	global_store_dwordx4 v[44:45], v[40:43], off sc1
	v_lshlrev_b32_e32 v144, 7, v38
	s_waitcnt lgkmcnt(7)
	v_cvt_pk_bf16_f32 v40, v210, v211
	ds_read2_b32 v[44:45], v52 offset0:206 offset1:239
	s_waitcnt lgkmcnt(7)
	v_cvt_pk_bf16_f32 v41, v212, v213
	ds_read2_b32 v[210:211], v52 offset0:90 offset1:123
	v_lshl_add_u64 v[38:39], v[34:35], 0, v[144:145]
	s_waitcnt lgkmcnt(7)
	v_cvt_pk_bf16_f32 v42, v214, v215
	ds_read2_b32 v[212:213], v52 offset0:156 offset1:189
	s_waitcnt lgkmcnt(2)
	v_cvt_pk_bf16_f32 v43, v44, v45
	global_store_dwordx4 v[38:39], v[40:43], off sc1
	s_waitcnt lgkmcnt(2)
	v_cvt_pk_bf16_f32 v38, v216, v217
	s_waitcnt lgkmcnt(2)
	v_cvt_pk_bf16_f32 v39, v218, v219
	s_waitcnt lgkmcnt(2)
	v_cvt_pk_bf16_f32 v40, v204, v205
	v_lshlrev_b32_e32 v144, 7, v37
	s_waitcnt lgkmcnt(2)
	v_cvt_pk_bf16_f32 v41, v206, v207
	v_lshl_add_u64 v[42:43], v[34:35], 0, v[144:145]
	global_store_dwordx4 v[42:43], v[38:41], off sc1
	ds_read2_b32 v[42:43], v52 offset0:222 offset1:255
	v_lshlrev_b32_e32 v144, 7, v36
	s_waitcnt lgkmcnt(3)
	v_cvt_pk_bf16_f32 v38, v208, v209
	s_waitcnt lgkmcnt(2)
	v_cvt_pk_bf16_f32 v39, v210, v211
	v_lshl_add_u64 v[34:35], v[34:35], 0, v[144:145]
	s_waitcnt lgkmcnt(1)
	v_cvt_pk_bf16_f32 v40, v212, v213
	s_waitcnt lgkmcnt(0)
	v_cvt_pk_bf16_f32 v41, v42, v43
	global_store_dwordx4 v[34:35], v[38:41], off sc1
	s_waitcnt lgkmcnt(0)

; #define LAS __attribute__((address_space(3)))
; __device__ __forceinline__ void transpose_item(const float* W, int N, bf16* WT, int K, int k0, int n0, int drow0, const float* gk, LAS float* scr, int lane) {
;     float wv[32];
; #pragma unroll
;     for (int i = 0; i < 32; ++i) wv[i] = W[(size_t)(k0 + 2 * i + (lane >> 5)) * N + n0 + (lane & 31)];
; __device__ __forceinline__ void p0_weight_item(const Args& a, int l, int r, LAS float* scr, int lane) {
;     ...
;     if (r < IT_GLU) { const int kb = r / 8, nb = r % 8; transpose_item(a.in[15] + (size_t)l * 65536, 256, (bf16*)(wl + WL_GLU), 256, 64 * kb, 32 * nb, 32 * nb, nullptr, scr, lane); return; }
.LBB0_1043:
	s_andn2_b64 vcc, exec, s[0:1]
	s_cbranch_vccnz .LBB0_1045
	s_and_b32 s0, s38, 0x3fc0
	s_add_i32 s1, s35, 0xfffba000
	s_addk_i32 s0, 0xc400
	s_and_b32 s4, s1, 0xe0
	v_or_b32_e32 v144, s0, v0
	s_lshl_b32 s82, s4, 2
	v_lshl_add_u64 v[34:35], v[14:15], 0, s[82:83]
	v_lshlrev_b64 v[36:37], 10, v[144:145]
	v_lshl_add_u64 v[36:37], v[34:35], 0, v[36:37]
	global_load_dword v38, v[36:37], off nt
	v_or_b32_e32 v36, 2, v144
	v_mov_b32_e32 v37, v145
	v_lshlrev_b64 v[36:37], 10, v[36:37]
	v_lshl_add_u64 v[36:37], v[34:35], 0, v[36:37]
	global_load_dword v39, v[36:37], off nt
	v_or_b32_e32 v36, 4, v144
	v_mov_b32_e32 v37, v145
	v_lshlrev_b64 v[36:37], 10, v[36:37]
	v_lshl_add_u64 v[36:37], v[34:35], 0, v[36:37]
	global_load_dword v40, v[36:37], off nt
	v_or_b32_e32 v36, 6, v144
	v_mov_b32_e32 v37, v145
	v_lshlrev_b64 v[36:37], 10, v[36:37]
	v_lshl_add_u64 v[36:37], v[34:35], 0, v[36:37]
	global_load_dword v41, v[36:37], off nt
	v_or_b32_e32 v36, 8, v144
	v_mov_b32_e32 v37, v145
	v_lshlrev_b64 v[36:37], 10, v[36:37]
	v_lshl_add_u64 v[36:37], v[34:35], 0, v[36:37]
	global_load_dword v42, v[36:37], off nt
	v_or_b32_e32 v36, 10, v144
	v_mov_b32_e32 v37, v145
	v_lshlrev_b64 v[36:37], 10, v[36:37]
	v_lshl_add_u64 v[36:37], v[34:35], 0, v[36:37]
	global_load_dword v43, v[36:37], off nt
	v_or_b32_e32 v36, 12, v144
	v_mov_b32_e32 v37, v145
	v_lshlrev_b64 v[36:37], 10, v[36:37]
	v_lshl_add_u64 v[36:37], v[34:35], 0, v[36:37]
	global_load_dword v44, v[36:37], off nt
	v_or_b32_e32 v36, 14, v144
	v_mov_b32_e32 v37, v145
	v_lshlrev_b64 v[36:37], 10, v[36:37]
	v_lshl_add_u64 v[36:37], v[34:35], 0, v[36:37]
	global_load_dword v45, v[36:37], off nt
	v_or_b32_e32 v36, 16, v144
	v_mov_b32_e32 v37, v145
	v_lshlrev_b64 v[36:37], 10, v[36:37]
	v_lshl_add_u64 v[36:37], v[34:35], 0, v[36:37]
	global_load_dword v46, v[36:37], off nt
	v_or_b32_e32 v36, 18, v144
	v_mov_b32_e32 v37, v145
	v_lshlrev_b64 v[36:37], 10, v[36:37]
	v_lshl_add_u64 v[36:37], v[34:35], 0, v[36:37]
	global_load_dword v47, v[36:37], off nt
	v_or_b32_e32 v36, 20, v144
	v_mov_b32_e32 v37, v145
	v_lshlrev_b64 v[36:37], 10, v[36:37]
	v_lshl_add_u64 v[36:37], v[34:35], 0, v[36:37]
	global_load_dword v48, v[36:37], off nt
	v_or_b32_e32 v36, 22, v144
	v_mov_b32_e32 v37, v145
	v_lshlrev_b64 v[36:37], 10, v[36:37]
	v_lshl_add_u64 v[36:37], v[34:35], 0, v[36:37]
	global_load_dword v49, v[36:37], off nt
	v_or_b32_e32 v36, 24, v144
	v_mov_b32_e32 v37, v145
	v_lshlrev_b64 v[36:37], 10, v[36:37]
	v_lshl_add_u64 v[36:37], v[34:35], 0, v[36:37]
	global_load_dword v50, v[36:37], off nt
	v_or_b32_e32 v36, 26, v144
	v_mov_b32_e32 v37, v145
	v_lshlrev_b64 v[36:37], 10, v[36:37]
	v_lshl_add_u64 v[36:37], v[34:35], 0, v[36:37]
	global_load_dword v51, v[36:37], off nt
	v_or_b32_e32 v36, 28, v144
	v_mov_b32_e32 v37, v145
	v_lshlrev_b64 v[36:37], 10, v[36:37]
	v_lshl_add_u64 v[36:37], v[34:35], 0, v[36:37]
	global_load_dword v69, v[36:37], off nt
	v_or_b32_e32 v36, 30, v144
	v_mov_b32_e32 v37, v145
	v_lshlrev_b64 v[36:37], 10, v[36:37]
	v_lshl_add_u64 v[36:37], v[34:35], 0, v[36:37]
	global_load_dword v70, v[36:37], off nt
	v_or_b32_e32 v36, 32, v144
	v_mov_b32_e32 v37, v145
	v_lshlrev_b64 v[36:37], 10, v[36:37]
	v_lshl_add_u64 v[36:37], v[34:35], 0, v[36:37]
	global_load_dword v71, v[36:37], off nt
	v_or_b32_e32 v36, 34, v144
	v_mov_b32_e32 v37, v145
	v_lshlrev_b64 v[36:37], 10, v[36:37]
	v_lshl_add_u64 v[36:37], v[34:35], 0, v[36:37]
	global_load_dword v72, v[36:37], off nt
	v_or_b32_e32 v36, 36, v144
	v_mov_b32_e32 v37, v145
	v_lshlrev_b64 v[36:37], 10, v[36:37]
	v_lshl_add_u64 v[36:37], v[34:35], 0, v[36:37]
	global_load_dword v73, v[36:37], off nt
	v_or_b32_e32 v36, 38, v144
	v_mov_b32_e32 v37, v145
	v_lshlrev_b64 v[36:37], 10, v[36:37]
	v_lshl_add_u64 v[36:37], v[34:35], 0, v[36:37]
	global_load_dword v74, v[36:37], off nt
	v_or_b32_e32 v36, 40, v144
	v_mov_b32_e32 v37, v145
	v_lshlrev_b64 v[36:37], 10, v[36:37]
	v_lshl_add_u64 v[36:37], v[34:35], 0, v[36:37]
	global_load_dword v75, v[36:37], off nt
	v_or_b32_e32 v36, 42, v144
	v_mov_b32_e32 v37, v145
	v_lshlrev_b64 v[36:37], 10, v[36:37]
	v_lshl_add_u64 v[36:37], v[34:35], 0, v[36:37]
	global_load_dword v76, v[36:37], off nt
	v_or_b32_e32 v36, 44, v144
	v_mov_b32_e32 v37, v145
	v_lshlrev_b64 v[36:37], 10, v[36:37]
	v_lshl_add_u64 v[36:37], v[34:35], 0, v[36:37]
	global_load_dword v77, v[36:37], off nt
	v_or_b32_e32 v36, 46, v144
	v_mov_b32_e32 v37, v145
	v_lshlrev_b64 v[36:37], 10, v[36:37]
	v_lshl_add_u64 v[36:37], v[34:35], 0, v[36:37]
	global_load_dword v78, v[36:37], off nt
	v_or_b32_e32 v36, 48, v144
	v_mov_b32_e32 v37, v145
	v_lshlrev_b64 v[36:37], 10, v[36:37]
	v_lshl_add_u64 v[36:37], v[34:35], 0, v[36:37]
	global_load_dword v79, v[36:37], off nt
	v_or_b32_e32 v36, 50, v144
	v_mov_b32_e32 v37, v145
	v_lshlrev_b64 v[36:37], 10, v[36:37]
	v_lshl_add_u64 v[36:37], v[34:35], 0, v[36:37]
	global_load_dword v80, v[36:37], off nt
	v_or_b32_e32 v36, 52, v144
	v_mov_b32_e32 v37, v145
	v_lshlrev_b64 v[36:37], 10, v[36:37]
	v_lshl_add_u64 v[36:37], v[34:35], 0, v[36:37]
	global_load_dword v81, v[36:37], off nt
	v_or_b32_e32 v36, 54, v144
	v_mov_b32_e32 v37, v145
	v_lshlrev_b64 v[36:37], 10, v[36:37]
	v_lshl_add_u64 v[36:37], v[34:35], 0, v[36:37]
	global_load_dword v82, v[36:37], off nt
	v_or_b32_e32 v36, 56, v144
	v_mov_b32_e32 v37, v145
	v_lshlrev_b64 v[36:37], 10, v[36:37]
	v_lshl_add_u64 v[36:37], v[34:35], 0, v[36:37]
	global_load_dword v83, v[36:37], off nt
	v_or_b32_e32 v36, 58, v144
	v_mov_b32_e32 v37, v145
	v_lshlrev_b64 v[36:37], 10, v[36:37]
	v_lshl_add_u64 v[36:37], v[34:35], 0, v[36:37]
	global_load_dword v84, v[36:37], off nt
	v_or_b32_e32 v36, 60, v144
	v_mov_b32_e32 v37, v145
	v_lshlrev_b64 v[36:37], 10, v[36:37]
	v_lshl_add_u64 v[36:37], v[34:35], 0, v[36:37]
	v_or_b32_e32 v144, 62, v144
	global_load_dword v85, v[36:37], off nt
	v_lshlrev_b64 v[36:37], 10, v[144:145]
	v_lshl_add_u64 v[34:35], v[34:35], 0, v[36:37]
	global_load_dword v34, v[34:35], off nt
	v_add_u32_e32 v35, 0x400, v3
	s_waitcnt vmcnt(0)
; #define LAS __attribute__((address_space(3)))
; __device__ __forceinline__ unsigned pk2(float lo, float hi) { return pg8::cvt_pk_bf16(lo, hi); }
; __device__ __forceinline__ void lds_wait() { asm volatile("s_waitcnt lgkmcnt(0)" ::: "memory"); }
; __device__ __forceinline__ void transpose_item(const float* W, int N, bf16* WT, int K, int k0, int n0, int drow0, const float* gk, LAS float* scr, int lane) {
;     ...
;     for (int i = 0; i < 32; ++i) { const int kk = 2 * i + (lane >> 5); float v = wv[i]; if (gk) v *= gk[kk]; scr[kk * 33 + (lane & 31)] = v; }
;     lds_wait();
;     const int c = lane & 7;
; #pragma unroll
;     for (int j = 0; j < 4; ++j) { const int n = (lane >> 3) + 8 * j; const LAS float* s = scr + (8 * c) * 33 + n;
;         u32x4 o; o.x = pk2(s[0 * 33], s[1 * 33]); o.y = pk2(s[2 * 33], s[3 * 33]); o.z = pk2(s[4 * 33], s[5 * 33]); o.w = pk2(s[6 * 33], s[7 * 33]);
;         *(u32x4*)(WT + (size_t)(drow0 + n) * K + k0 + 8 * c) = o; }
;     lds_wait();
	ds_write2_b32 v3, v38, v39 offset1:66
	ds_write2_b32 v3, v40, v41 offset0:132 offset1:198
	ds_write2_b32 v35, v42, v43 offset0:8 offset1:74
	ds_write2_b32 v35, v44, v45 offset0:140 offset1:206
	v_add_u32_e32 v35, 0x800, v3
	ds_write2_b32 v35, v46, v47 offset0:16 offset1:82
	ds_write2_b32 v35, v48, v49 offset0:148 offset1:214
	v_add_u32_e32 v35, 0xc00, v3
	ds_write2_b32 v35, v50, v51 offset0:24 offset1:90
	ds_write2_b32 v35, v69, v70 offset0:156 offset1:222
	v_add_u32_e32 v35, 0x1000, v3
	ds_write2_b32 v35, v71, v72 offset0:32 offset1:98
	ds_write2_b32 v35, v73, v74 offset0:164 offset1:230
	v_add_u32_e32 v35, 0x1400, v3
	ds_write2_b32 v35, v75, v76 offset0:40 offset1:106
	ds_write2_b32 v35, v77, v78 offset0:172 offset1:238
	v_add_u32_e32 v35, 0x1800, v3
	ds_write2_b32 v35, v79, v80 offset0:48 offset1:114
	ds_write2_b32 v35, v81, v82 offset0:180 offset1:246
	v_add_u32_e32 v35, 0x1c00, v3
	ds_write2_b32 v35, v83, v84 offset0:56 offset1:122
	ds_write2_b32 v35, v85, v34 offset0:188 offset1:254
	s_waitcnt lgkmcnt(0)
	ds_read2_b32 v[34:35], v52 offset1:33
	ds_read2_b32 v[204:205], v52 offset0:66 offset1:99
	ds_read2_b32 v[206:207], v52 offset0:132 offset1:165
	ds_read2_b32 v[40:41], v52 offset0:198 offset1:231
	ds_read2_b32 v[208:209], v52 offset0:8 offset1:41
	ds_read2_b32 v[210:211], v52 offset0:74 offset1:107
	ds_read2_b32 v[212:213], v52 offset0:140 offset1:173
	ds_read2_b32 v[214:215], v52 offset0:16 offset1:49
	s_waitcnt lgkmcnt(7)
	v_cvt_pk_bf16_f32 v34, v34, v35
	ds_read2_b32 v[216:217], v52 offset0:82 offset1:115
	s_waitcnt lgkmcnt(7)
	v_cvt_pk_bf16_f32 v35, v204, v205
	ds_read2_b32 v[204:205], v52 offset0:148 offset1:181
	s_waitcnt lgkmcnt(7)
	v_cvt_pk_bf16_f32 v36, v206, v207
	ds_read2_b32 v[206:207], v52 offset0:24 offset1:57
	s_mov_b32 s1, s83
	s_waitcnt lgkmcnt(7)
	v_cvt_pk_bf16_f32 v37, v40, v41
	v_or_b32_e32 v40, s4, v5
	v_lshl_add_u64 v[38:39], s[0:1], 1, v[16:17]
	v_lshlrev_b32_e32 v144, 9, v40
	ds_read2_b32 v[218:219], v52 offset0:90 offset1:123
	v_lshl_add_u64 v[40:41], v[38:39], 0, v[144:145]
	global_store_dwordx4 v[40:41], v[34:37], off sc1
	s_waitcnt lgkmcnt(7)
	v_cvt_pk_bf16_f32 v34, v208, v209
	ds_read2_b32 v[40:41], v52 offset0:206 offset1:239
	s_waitcnt lgkmcnt(7)
	v_cvt_pk_bf16_f32 v35, v210, v211
	ds_read2_b32 v[208:209], v52 offset0:156 offset1:189
	s_waitcnt lgkmcnt(7)
	v_cvt_pk_bf16_f32 v36, v212, v213
	s_waitcnt lgkmcnt(1)
	v_cvt_pk_bf16_f32 v37, v40, v41
	v_or_b32_e32 v40, s4, v53
	v_lshlrev_b32_e32 v144, 9, v40
	v_lshl_add_u64 v[40:41], v[38:39], 0, v[144:145]
	global_store_dwordx4 v[40:41], v[34:37], off sc1
	ds_read2_b32 v[40:41], v52 offset0:214 offset1:247
	s_waitcnt lgkmcnt(2)
	v_cvt_pk_bf16_f32 v34, v214, v215
	s_waitcnt lgkmcnt(2)
	v_cvt_pk_bf16_f32 v35, v216, v217
	s_waitcnt lgkmcnt(2)
	v_cvt_pk_bf16_f32 v36, v204, v205
	s_waitcnt lgkmcnt(0)
	v_cvt_pk_bf16_f32 v37, v40, v41
	v_or_b32_e32 v40, s4, v54
	v_lshlrev_b32_e32 v144, 9, v40
	v_lshl_add_u64 v[40:41], v[38:39], 0, v[144:145]
	global_store_dwordx4 v[40:41], v[34:37], off sc1
	ds_read2_b32 v[40:41], v52 offset0:222 offset1:255
	s_waitcnt lgkmcnt(1)
	v_cvt_pk_bf16_f32 v34, v206, v207
	s_waitcnt lgkmcnt(1)
	v_cvt_pk_bf16_f32 v35, v218, v219
	s_waitcnt lgkmcnt(1)
	v_cvt_pk_bf16_f32 v36, v208, v209
	s_waitcnt lgkmcnt(0)
	v_cvt_pk_bf16_f32 v37, v40, v41
	v_or_b32_e32 v40, s4, v55
	v_lshlrev_b32_e32 v144, 9, v40
	v_lshl_add_u64 v[38:39], v[38:39], 0, v[144:145]
	global_store_dwordx4 v[38:39], v[34:37], off sc1
	s_waitcnt lgkmcnt(0)

; #define LAS __attribute__((address_space(3)))
; __device__ __forceinline__ unsigned pk2(float lo, float hi) { return pg8::cvt_pk_bf16(lo, hi); }
; __device__ __forceinline__ void lds_wait() { asm volatile("s_waitcnt lgkmcnt(0)" ::: "memory"); }
; __device__ __forceinline__ void transpose_item(const float* W, int N, bf16* WT, int K, int k0, int n0, int drow0, const float* gk, LAS float* scr, int lane) {
;     ...
;     for (int i = 0; i < 32; ++i) { const int kk = 2 * i + (lane >> 5); float v = wv[i]; if (gk) v *= gk[kk]; scr[kk * 33 + (lane & 31)] = v; }
;     lds_wait();
;     const int c = lane & 7;
; #pragma unroll
;     for (int j = 0; j < 4; ++j) { const int n = (lane >> 3) + 8 * j; const LAS float* s = scr + (8 * c) * 33 + n;
;         u32x4 o; o.x = pk2(s[0 * 33], s[1 * 33]); o.y = pk2(s[2 * 33], s[3 * 33]); o.z = pk2(s[4 * 33], s[5 * 33]); o.w = pk2(s[6 * 33], s[7 * 33]);
;         *(u32x4*)(WT + (size_t)(drow0 + n) * K + k0 + 8 * c) = o; }
.LBB0_1079:
	ds_write2_b32 v38, v36, v37 offset0:140 offset1:206
	s_waitcnt lgkmcnt(0)
	ds_read2_b32 v[34:35], v52 offset1:33
	ds_read2_b32 v[204:205], v52 offset0:66 offset1:99
	ds_read2_b32 v[206:207], v52 offset0:132 offset1:165
	ds_read2_b32 v[40:41], v52 offset0:198 offset1:231
	ds_read2_b32 v[208:209], v52 offset0:8 offset1:41
	ds_read2_b32 v[210:211], v52 offset0:74 offset1:107
	ds_read2_b32 v[212:213], v52 offset0:140 offset1:173
	ds_read2_b32 v[214:215], v52 offset0:16 offset1:49
	s_waitcnt lgkmcnt(7)
	v_cvt_pk_bf16_f32 v34, v34, v35
	ds_read2_b32 v[216:217], v52 offset0:82 offset1:115
	s_waitcnt lgkmcnt(7)
	v_cvt_pk_bf16_f32 v35, v204, v205
	ds_read2_b32 v[204:205], v52 offset0:148 offset1:181
	s_waitcnt lgkmcnt(7)
	v_cvt_pk_bf16_f32 v36, v206, v207
	ds_read2_b32 v[206:207], v52 offset0:24 offset1:57
	s_mov_b32 s5, s83
	s_waitcnt lgkmcnt(7)
	v_cvt_pk_bf16_f32 v37, v40, v41
	v_or_b32_e32 v40, s28, v5
	v_lshl_add_u64 v[38:39], s[4:5], 1, v[20:21]
	v_lshlrev_b32_e32 v144, 11, v40
	ds_read2_b32 v[218:219], v52 offset0:90 offset1:123
	v_lshl_add_u64 v[40:41], v[38:39], 0, v[144:145]
	global_store_dwordx4 v[40:41], v[34:37], off sc1
	s_waitcnt lgkmcnt(7)
	v_cvt_pk_bf16_f32 v34, v208, v209
	ds_read2_b32 v[40:41], v52 offset0:206 offset1:239
	s_waitcnt lgkmcnt(7)
	v_cvt_pk_bf16_f32 v35, v210, v211
	ds_read2_b32 v[208:209], v52 offset0:156 offset1:189
	s_waitcnt lgkmcnt(7)
	v_cvt_pk_bf16_f32 v36, v212, v213
	s_waitcnt lgkmcnt(1)
	v_cvt_pk_bf16_f32 v37, v40, v41
	v_or_b32_e32 v40, s28, v53
	v_lshlrev_b32_e32 v144, 11, v40
	v_lshl_add_u64 v[40:41], v[38:39], 0, v[144:145]
	global_store_dwordx4 v[40:41], v[34:37], off sc1
	ds_read2_b32 v[40:41], v52 offset0:214 offset1:247
	s_waitcnt lgkmcnt(2)
	v_cvt_pk_bf16_f32 v34, v214, v215
	s_waitcnt lgkmcnt(2)
	v_cvt_pk_bf16_f32 v35, v216, v217
	s_waitcnt lgkmcnt(2)
	v_cvt_pk_bf16_f32 v36, v204, v205
	s_waitcnt lgkmcnt(0)
	v_cvt_pk_bf16_f32 v37, v40, v41
	v_or_b32_e32 v40, s28, v54
	v_lshlrev_b32_e32 v144, 11, v40
	v_lshl_add_u64 v[40:41], v[38:39], 0, v[144:145]
	global_store_dwordx4 v[40:41], v[34:37], off sc1
	ds_read2_b32 v[40:41], v52 offset0:222 offset1:255
	s_waitcnt lgkmcnt(1)
	v_cvt_pk_bf16_f32 v34, v206, v207
	s_waitcnt lgkmcnt(1)
	v_cvt_pk_bf16_f32 v35, v218, v219
	s_waitcnt lgkmcnt(1)
	v_cvt_pk_bf16_f32 v36, v208, v209
	s_waitcnt lgkmcnt(0)
	v_cvt_pk_bf16_f32 v37, v40, v41
	v_or_b32_e32 v40, s28, v55
	v_lshlrev_b32_e32 v144, 11, v40
	v_lshl_add_u64 v[38:39], v[38:39], 0, v[144:145]
	global_store_dwordx4 v[38:39], v[34:37], off sc1
	s_waitcnt lgkmcnt(0)

; #define LAS __attribute__((address_space(3)))
; __device__ __forceinline__ unsigned pk2(float lo, float hi) { return pg8::cvt_pk_bf16(lo, hi); }
; __device__ __forceinline__ void lds_wait() { asm volatile("s_waitcnt lgkmcnt(0)" ::: "memory"); }
; __device__ __forceinline__ void transpose_item(const float* W, int N, bf16* WT, int K, int k0, int n0, int drow0, const float* gk, LAS float* scr, int lane) {
;     ...
;     for (int i = 0; i < 32; ++i) { const int kk = 2 * i + (lane >> 5); float v = wv[i]; if (gk) v *= gk[kk]; scr[kk * 33 + (lane & 31)] = v; }
;     lds_wait();
;     const int c = lane & 7;
; #pragma unroll
;     for (int j = 0; j < 4; ++j) { const int n = (lane >> 3) + 8 * j; const LAS float* s = scr + (8 * c) * 33 + n;
;         u32x4 o; o.x = pk2(s[0 * 33], s[1 * 33]); o.y = pk2(s[2 * 33], s[3 * 33]); o.z = pk2(s[4 * 33], s[5 * 33]); o.w = pk2(s[6 * 33], s[7 * 33]);
;         *(u32x4*)(WT + (size_t)(drow0 + n) * K + k0 + 8 * c) = o; }
.LBB0_1108:
	ds_write2_b32 v38, v36, v37 offset0:140 offset1:206
	s_waitcnt lgkmcnt(0)
	ds_read2_b32 v[34:35], v52 offset1:33
	ds_read2_b32 v[204:205], v52 offset0:66 offset1:99
	ds_read2_b32 v[206:207], v52 offset0:132 offset1:165
	ds_read2_b32 v[208:209], v52 offset0:198 offset1:231
	ds_read2_b32 v[210:211], v52 offset0:8 offset1:41
	ds_read2_b32 v[212:213], v52 offset0:74 offset1:107
	ds_read2_b32 v[214:215], v52 offset0:140 offset1:173
	ds_read2_b32 v[216:217], v52 offset0:206 offset1:239
	s_waitcnt lgkmcnt(7)
	v_cvt_pk_bf16_f32 v34, v34, v35
	ds_read2_b32 v[218:219], v52 offset0:16 offset1:49
	s_waitcnt lgkmcnt(7)
	v_cvt_pk_bf16_f32 v35, v204, v205
	ds_read2_b32 v[204:205], v52 offset0:82 offset1:115
	s_lshl_b32 s82, s7, 1
	s_waitcnt lgkmcnt(7)
	v_cvt_pk_bf16_f32 v36, v206, v207
	ds_read2_b32 v[206:207], v52 offset0:148 offset1:181
	v_add_u32_e32 v144, s6, v5
	v_lshl_add_u64 v[38:39], v[24:25], 0, s[82:83]
	s_waitcnt lgkmcnt(7)
	v_cvt_pk_bf16_f32 v37, v208, v209
	ds_read2_b32 v[208:209], v52 offset0:214 offset1:247
	v_lshlrev_b64 v[40:41], 11, v[144:145]
	v_lshl_add_u64 v[40:41], v[38:39], 0, v[40:41]
	global_store_dwordx4 v[40:41], v[34:37], off sc1
	v_add_u32_e32 v144, s6, v53
	s_waitcnt lgkmcnt(7)
	v_cvt_pk_bf16_f32 v34, v210, v211
	ds_read2_b32 v[210:211], v52 offset0:24 offset1:57
	s_waitcnt lgkmcnt(7)
	v_cvt_pk_bf16_f32 v35, v212, v213
	ds_read2_b32 v[212:213], v52 offset0:90 offset1:123
	s_waitcnt lgkmcnt(7)
	v_cvt_pk_bf16_f32 v36, v214, v215
	ds_read2_b32 v[214:215], v52 offset0:156 offset1:189
	s_waitcnt lgkmcnt(7)
	v_cvt_pk_bf16_f32 v37, v216, v217
	ds_read2_b32 v[216:217], v52 offset0:222 offset1:255
	v_lshlrev_b64 v[40:41], 11, v[144:145]
	v_lshl_add_u64 v[40:41], v[38:39], 0, v[40:41]
	global_store_dwordx4 v[40:41], v[34:37], off sc1
	v_add_u32_e32 v144, s6, v54
	s_waitcnt lgkmcnt(7)
	v_cvt_pk_bf16_f32 v34, v218, v219
	s_waitcnt lgkmcnt(6)
	v_cvt_pk_bf16_f32 v35, v204, v205
	s_waitcnt lgkmcnt(5)
	v_cvt_pk_bf16_f32 v36, v206, v207
	s_waitcnt lgkmcnt(4)
	v_cvt_pk_bf16_f32 v37, v208, v209
	v_lshlrev_b64 v[40:41], 11, v[144:145]
	v_lshl_add_u64 v[40:41], v[38:39], 0, v[40:41]
	global_store_dwordx4 v[40:41], v[34:37], off sc1
	v_add_u32_e32 v144, s6, v55
	s_waitcnt lgkmcnt(3)
	v_cvt_pk_bf16_f32 v34, v210, v211
	s_waitcnt lgkmcnt(2)
	v_cvt_pk_bf16_f32 v35, v212, v213
	s_waitcnt lgkmcnt(1)
	v_cvt_pk_bf16_f32 v36, v214, v215
	s_waitcnt lgkmcnt(0)
	v_cvt_pk_bf16_f32 v37, v216, v217
	v_lshlrev_b64 v[40:41], 11, v[144:145]
	v_lshl_add_u64 v[38:39], v[38:39], 0, v[40:41]
	global_store_dwordx4 v[38:39], v[34:37], off sc1
	s_waitcnt lgkmcnt(0)

; #define LAS __attribute__((address_space(3)))
; __device__ __forceinline__ void transpose_item(const float* W, int N, bf16* WT, int K, int k0, int n0, int drow0, const float* gk, LAS float* scr, int lane) {
;     float wv[32];
; #pragma unroll
;     for (int i = 0; i < 32; ++i) wv[i] = W[(size_t)(k0 + 2 * i + (lane >> 5)) * N + n0 + (lane & 31)];
; __device__ __forceinline__ void p0_weight_item(const Args& a, int l, int r, LAS float* scr, int lane) {
;     ...
;         if (r < IT_BIG) { const int kb = r / 32, nb = r % 32; const float* W = a.in[f ? 31 : 4] + (size_t)l * FF * DM;
;             transpose_item(W, DM, dn, FF, 64 * kb, 32 * nb, 32 * nb, nullptr, scr, lane); return; }
.LBB0_1110:
	s_andn2_b64 vcc, exec, s[0:1]
	s_cbranch_vccnz .LBB0_1112
	s_add_i32 s0, s35, 0xfffdb000
	s_and_b32 s1, s26, 0x7fffffc0
	s_and_b32 s0, s0, 0x3e0
	v_or_b32_e32 v144, s1, v0
	s_lshl_b32 s82, s0, 2
	v_lshl_add_u64 v[34:35], v[26:27], 0, s[82:83]
	v_lshlrev_b64 v[36:37], 12, v[144:145]
	v_lshl_add_u64 v[36:37], v[34:35], 0, v[36:37]
	global_load_dword v38, v[36:37], off nt
	v_or_b32_e32 v36, 2, v144
	v_mov_b32_e32 v37, v145
	v_lshlrev_b64 v[36:37], 12, v[36:37]
	v_lshl_add_u64 v[36:37], v[34:35], 0, v[36:37]
	global_load_dword v39, v[36:37], off nt
	v_or_b32_e32 v36, 4, v144
	v_mov_b32_e32 v37, v145
	v_lshlrev_b64 v[36:37], 12, v[36:37]
	v_lshl_add_u64 v[36:37], v[34:35], 0, v[36:37]
	global_load_dword v40, v[36:37], off nt
	v_or_b32_e32 v36, 6, v144
	v_mov_b32_e32 v37, v145
	v_lshlrev_b64 v[36:37], 12, v[36:37]
	v_lshl_add_u64 v[36:37], v[34:35], 0, v[36:37]
	global_load_dword v41, v[36:37], off nt
	v_or_b32_e32 v36, 8, v144
	v_mov_b32_e32 v37, v145
	v_lshlrev_b64 v[36:37], 12, v[36:37]
	v_lshl_add_u64 v[36:37], v[34:35], 0, v[36:37]
	global_load_dword v42, v[36:37], off nt
	v_or_b32_e32 v36, 10, v144
	v_mov_b32_e32 v37, v145
	v_lshlrev_b64 v[36:37], 12, v[36:37]
	v_lshl_add_u64 v[36:37], v[34:35], 0, v[36:37]
	global_load_dword v43, v[36:37], off nt
	v_or_b32_e32 v36, 12, v144
	v_mov_b32_e32 v37, v145
	v_lshlrev_b64 v[36:37], 12, v[36:37]
	v_lshl_add_u64 v[36:37], v[34:35], 0, v[36:37]
	global_load_dword v44, v[36:37], off nt
	v_or_b32_e32 v36, 14, v144
	v_mov_b32_e32 v37, v145
	v_lshlrev_b64 v[36:37], 12, v[36:37]
	v_lshl_add_u64 v[36:37], v[34:35], 0, v[36:37]
	global_load_dword v45, v[36:37], off nt
	v_or_b32_e32 v36, 16, v144
	v_mov_b32_e32 v37, v145
	v_lshlrev_b64 v[36:37], 12, v[36:37]
	v_lshl_add_u64 v[36:37], v[34:35], 0, v[36:37]
	global_load_dword v46, v[36:37], off nt
	v_or_b32_e32 v36, 18, v144
	v_mov_b32_e32 v37, v145
	v_lshlrev_b64 v[36:37], 12, v[36:37]
	v_lshl_add_u64 v[36:37], v[34:35], 0, v[36:37]
	global_load_dword v47, v[36:37], off nt
	v_or_b32_e32 v36, 20, v144
	v_mov_b32_e32 v37, v145
	v_lshlrev_b64 v[36:37], 12, v[36:37]
	v_lshl_add_u64 v[36:37], v[34:35], 0, v[36:37]
	global_load_dword v48, v[36:37], off nt
	v_or_b32_e32 v36, 22, v144
	v_mov_b32_e32 v37, v145
	v_lshlrev_b64 v[36:37], 12, v[36:37]
	v_lshl_add_u64 v[36:37], v[34:35], 0, v[36:37]
	global_load_dword v49, v[36:37], off nt
	v_or_b32_e32 v36, 24, v144
	v_mov_b32_e32 v37, v145
	v_lshlrev_b64 v[36:37], 12, v[36:37]
	v_lshl_add_u64 v[36:37], v[34:35], 0, v[36:37]
	global_load_dword v50, v[36:37], off nt
	v_or_b32_e32 v36, 26, v144
	v_mov_b32_e32 v37, v145
	v_lshlrev_b64 v[36:37], 12, v[36:37]
	v_lshl_add_u64 v[36:37], v[34:35], 0, v[36:37]
	global_load_dword v51, v[36:37], off nt
	v_or_b32_e32 v36, 28, v144
	v_mov_b32_e32 v37, v145
	v_lshlrev_b64 v[36:37], 12, v[36:37]
	v_lshl_add_u64 v[36:37], v[34:35], 0, v[36:37]
	global_load_dword v69, v[36:37], off nt
	v_or_b32_e32 v36, 30, v144
	v_mov_b32_e32 v37, v145
	v_lshlrev_b64 v[36:37], 12, v[36:37]
	v_lshl_add_u64 v[36:37], v[34:35], 0, v[36:37]
	global_load_dword v70, v[36:37], off nt
	v_or_b32_e32 v36, 32, v144
	v_mov_b32_e32 v37, v145
	v_lshlrev_b64 v[36:37], 12, v[36:37]
	v_lshl_add_u64 v[36:37], v[34:35], 0, v[36:37]
	global_load_dword v71, v[36:37], off nt
	v_or_b32_e32 v36, 34, v144
	v_mov_b32_e32 v37, v145
	v_lshlrev_b64 v[36:37], 12, v[36:37]
	v_lshl_add_u64 v[36:37], v[34:35], 0, v[36:37]
	global_load_dword v72, v[36:37], off nt
	v_or_b32_e32 v36, 36, v144
	v_mov_b32_e32 v37, v145
	v_lshlrev_b64 v[36:37], 12, v[36:37]
	v_lshl_add_u64 v[36:37], v[34:35], 0, v[36:37]
	global_load_dword v73, v[36:37], off nt
	v_or_b32_e32 v36, 38, v144
	v_mov_b32_e32 v37, v145
	v_lshlrev_b64 v[36:37], 12, v[36:37]
	v_lshl_add_u64 v[36:37], v[34:35], 0, v[36:37]
	global_load_dword v74, v[36:37], off nt
	v_or_b32_e32 v36, 40, v144
	v_mov_b32_e32 v37, v145
	v_lshlrev_b64 v[36:37], 12, v[36:37]
	v_lshl_add_u64 v[36:37], v[34:35], 0, v[36:37]
	global_load_dword v75, v[36:37], off nt
	v_or_b32_e32 v36, 42, v144
	v_mov_b32_e32 v37, v145
	v_lshlrev_b64 v[36:37], 12, v[36:37]
	v_lshl_add_u64 v[36:37], v[34:35], 0, v[36:37]
	global_load_dword v76, v[36:37], off nt
	v_or_b32_e32 v36, 44, v144
	v_mov_b32_e32 v37, v145
	v_lshlrev_b64 v[36:37], 12, v[36:37]
	v_lshl_add_u64 v[36:37], v[34:35], 0, v[36:37]
	global_load_dword v77, v[36:37], off nt
	v_or_b32_e32 v36, 46, v144
	v_mov_b32_e32 v37, v145
	v_lshlrev_b64 v[36:37], 12, v[36:37]
	v_lshl_add_u64 v[36:37], v[34:35], 0, v[36:37]
	global_load_dword v78, v[36:37], off nt
	v_or_b32_e32 v36, 48, v144
	v_mov_b32_e32 v37, v145
	v_lshlrev_b64 v[36:37], 12, v[36:37]
	v_lshl_add_u64 v[36:37], v[34:35], 0, v[36:37]
	global_load_dword v79, v[36:37], off nt
	v_or_b32_e32 v36, 50, v144
	v_mov_b32_e32 v37, v145
	v_lshlrev_b64 v[36:37], 12, v[36:37]
	v_lshl_add_u64 v[36:37], v[34:35], 0, v[36:37]
	global_load_dword v80, v[36:37], off nt
	v_or_b32_e32 v36, 52, v144
	v_mov_b32_e32 v37, v145
	v_lshlrev_b64 v[36:37], 12, v[36:37]
	v_lshl_add_u64 v[36:37], v[34:35], 0, v[36:37]
	global_load_dword v81, v[36:37], off nt
	v_or_b32_e32 v36, 54, v144
	v_mov_b32_e32 v37, v145
	v_lshlrev_b64 v[36:37], 12, v[36:37]
	v_lshl_add_u64 v[36:37], v[34:35], 0, v[36:37]
	global_load_dword v82, v[36:37], off nt
	v_or_b32_e32 v36, 56, v144
	v_mov_b32_e32 v37, v145
	v_lshlrev_b64 v[36:37], 12, v[36:37]
	v_lshl_add_u64 v[36:37], v[34:35], 0, v[36:37]
	global_load_dword v83, v[36:37], off nt
	v_or_b32_e32 v36, 58, v144
	v_mov_b32_e32 v37, v145
	v_lshlrev_b64 v[36:37], 12, v[36:37]
	v_lshl_add_u64 v[36:37], v[34:35], 0, v[36:37]
	global_load_dword v84, v[36:37], off nt
	v_or_b32_e32 v36, 60, v144
	v_mov_b32_e32 v37, v145
	v_lshlrev_b64 v[36:37], 12, v[36:37]
	v_lshl_add_u64 v[36:37], v[34:35], 0, v[36:37]
	v_or_b32_e32 v144, 62, v144
	global_load_dword v85, v[36:37], off nt
	v_lshlrev_b64 v[36:37], 12, v[144:145]
	v_lshl_add_u64 v[34:35], v[34:35], 0, v[36:37]
	global_load_dword v34, v[34:35], off nt
	v_add_u32_e32 v35, 0x400, v3
	s_waitcnt vmcnt(0)
; #define LAS __attribute__((address_space(3)))
; __device__ __forceinline__ unsigned pk2(float lo, float hi) { return pg8::cvt_pk_bf16(lo, hi); }
; __device__ __forceinline__ void lds_wait() { asm volatile("s_waitcnt lgkmcnt(0)" ::: "memory"); }
; __device__ __forceinline__ void transpose_item(const float* W, int N, bf16* WT, int K, int k0, int n0, int drow0, const float* gk, LAS float* scr, int lane) {
;     ...
;     for (int i = 0; i < 32; ++i) { const int kk = 2 * i + (lane >> 5); float v = wv[i]; if (gk) v *= gk[kk]; scr[kk * 33 + (lane & 31)] = v; }
;     lds_wait();
;     const int c = lane & 7;
; #pragma unroll
;     for (int j = 0; j < 4; ++j) { const int n = (lane >> 3) + 8 * j; const LAS float* s = scr + (8 * c) * 33 + n;
;         u32x4 o; o.x = pk2(s[0 * 33], s[1 * 33]); o.y = pk2(s[2 * 33], s[3 * 33]); o.z = pk2(s[4 * 33], s[5 * 33]); o.w = pk2(s[6 * 33], s[7 * 33]);
;         *(u32x4*)(WT + (size_t)(drow0 + n) * K + k0 + 8 * c) = o; }
;     lds_wait();
	ds_write2_b32 v3, v38, v39 offset1:66
	ds_write2_b32 v3, v40, v41 offset0:132 offset1:198
	ds_write2_b32 v35, v42, v43 offset0:8 offset1:74
	ds_write2_b32 v35, v44, v45 offset0:140 offset1:206
	v_add_u32_e32 v35, 0x800, v3
	ds_write2_b32 v35, v46, v47 offset0:16 offset1:82
	ds_write2_b32 v35, v48, v49 offset0:148 offset1:214
	v_add_u32_e32 v35, 0xc00, v3
	ds_write2_b32 v35, v50, v51 offset0:24 offset1:90
	ds_write2_b32 v35, v69, v70 offset0:156 offset1:222
	v_add_u32_e32 v35, 0x1000, v3
	ds_write2_b32 v35, v71, v72 offset0:32 offset1:98
	ds_write2_b32 v35, v73, v74 offset0:164 offset1:230
	v_add_u32_e32 v35, 0x1400, v3
	ds_write2_b32 v35, v75, v76 offset0:40 offset1:106
	ds_write2_b32 v35, v77, v78 offset0:172 offset1:238
	v_add_u32_e32 v35, 0x1800, v3
	ds_write2_b32 v35, v79, v80 offset0:48 offset1:114
	ds_write2_b32 v35, v81, v82 offset0:180 offset1:246
	v_add_u32_e32 v35, 0x1c00, v3
	ds_write2_b32 v35, v83, v84 offset0:56 offset1:122
	ds_write2_b32 v35, v85, v34 offset0:188 offset1:254
	s_waitcnt lgkmcnt(0)
	ds_read2_b32 v[34:35], v52 offset1:33
	ds_read2_b32 v[204:205], v52 offset0:66 offset1:99
	ds_read2_b32 v[206:207], v52 offset0:132 offset1:165
	ds_read2_b32 v[40:41], v52 offset0:198 offset1:231
	ds_read2_b32 v[208:209], v52 offset0:8 offset1:41
	ds_read2_b32 v[210:211], v52 offset0:74 offset1:107
	ds_read2_b32 v[212:213], v52 offset0:140 offset1:173
	ds_read2_b32 v[214:215], v52 offset0:16 offset1:49
	s_waitcnt lgkmcnt(7)
	v_cvt_pk_bf16_f32 v34, v34, v35
	ds_read2_b32 v[216:217], v52 offset0:82 offset1:115
	s_waitcnt lgkmcnt(7)
	v_cvt_pk_bf16_f32 v35, v204, v205
	ds_read2_b32 v[204:205], v52 offset0:148 offset1:181
	s_waitcnt lgkmcnt(7)
	v_cvt_pk_bf16_f32 v36, v206, v207
	ds_read2_b32 v[206:207], v52 offset0:24 offset1:57
	s_waitcnt lgkmcnt(7)
	v_cvt_pk_bf16_f32 v37, v40, v41
	v_or_b32_e32 v40, s0, v5
	s_lshl_b32 s82, s1, 1
	v_mul_u32_u24_e32 v40, 0xb00, v40
	v_lshl_add_u64 v[38:39], v[28:29], 0, s[82:83]
	v_lshlrev_b32_e32 v144, 1, v40
	ds_read2_b32 v[218:219], v52 offset0:90 offset1:123
	v_lshl_add_u64 v[40:41], v[38:39], 0, v[144:145]
	global_store_dwordx4 v[40:41], v[34:37], off sc1
	s_waitcnt lgkmcnt(7)
	v_cvt_pk_bf16_f32 v34, v208, v209
	ds_read2_b32 v[40:41], v52 offset0:206 offset1:239
	s_waitcnt lgkmcnt(7)
	v_cvt_pk_bf16_f32 v35, v210, v211
	ds_read2_b32 v[208:209], v52 offset0:156 offset1:189
	s_waitcnt lgkmcnt(7)
	v_cvt_pk_bf16_f32 v36, v212, v213
	s_waitcnt lgkmcnt(1)
	v_cvt_pk_bf16_f32 v37, v40, v41
	v_or_b32_e32 v40, s0, v53
	v_mul_u32_u24_e32 v40, 0xb00, v40
	v_lshlrev_b32_e32 v144, 1, v40
	v_lshl_add_u64 v[40:41], v[38:39], 0, v[144:145]
	global_store_dwordx4 v[40:41], v[34:37], off sc1
	ds_read2_b32 v[40:41], v52 offset0:214 offset1:247
	s_waitcnt lgkmcnt(2)
	v_cvt_pk_bf16_f32 v34, v214, v215
	s_waitcnt lgkmcnt(2)
	v_cvt_pk_bf16_f32 v35, v216, v217
	s_waitcnt lgkmcnt(2)
	v_cvt_pk_bf16_f32 v36, v204, v205
	s_waitcnt lgkmcnt(0)
	v_cvt_pk_bf16_f32 v37, v40, v41
	v_or_b32_e32 v40, s0, v54
	v_mul_u32_u24_e32 v40, 0xb00, v40
	v_lshlrev_b32_e32 v144, 1, v40
	v_lshl_add_u64 v[40:41], v[38:39], 0, v[144:145]
	global_store_dwordx4 v[40:41], v[34:37], off sc1
	ds_read2_b32 v[40:41], v52 offset0:222 offset1:255
	s_waitcnt lgkmcnt(1)
	v_cvt_pk_bf16_f32 v34, v206, v207
	s_waitcnt lgkmcnt(1)
	v_cvt_pk_bf16_f32 v35, v218, v219
	s_waitcnt lgkmcnt(1)
	v_cvt_pk_bf16_f32 v36, v208, v209
	s_waitcnt lgkmcnt(0)
	v_cvt_pk_bf16_f32 v37, v40, v41
	v_or_b32_e32 v40, s0, v55
	v_mul_u32_u24_e32 v40, 0xb00, v40
	v_lshlrev_b32_e32 v144, 1, v40
	v_lshl_add_u64 v[38:39], v[38:39], 0, v[144:145]
	global_store_dwordx4 v[38:39], v[34:37], off sc1
	s_waitcnt lgkmcnt(0)

; #define LAS __attribute__((address_space(3)))
; __device__ __forceinline__ unsigned pk2(float lo, float hi) { return pg8::cvt_pk_bf16(lo, hi); }
; __device__ __forceinline__ void lds_wait() { asm volatile("s_waitcnt lgkmcnt(0)" ::: "memory"); }
; __device__ __forceinline__ void transpose_item(const float* W, int N, bf16* WT, int K, int k0, int n0, int drow0, const float* gk, LAS float* scr, int lane) {
;     ...
;     for (int i = 0; i < 32; ++i) { const int kk = 2 * i + (lane >> 5); float v = wv[i]; if (gk) v *= gk[kk]; scr[kk * 33 + (lane & 31)] = v; }
;     lds_wait();
;     const int c = lane & 7;
; #pragma unroll
;     for (int j = 0; j < 4; ++j) { const int n = (lane >> 3) + 8 * j; const LAS float* s = scr + (8 * c) * 33 + n;
;         u32x4 o; o.x = pk2(s[0 * 33], s[1 * 33]); o.y = pk2(s[2 * 33], s[3 * 33]); o.z = pk2(s[4 * 33], s[5 * 33]); o.w = pk2(s[6 * 33], s[7 * 33]);
;         *(u32x4*)(WT + (size_t)(drow0 + n) * K + k0 + 8 * c) = o; }
; __device__ __forceinline__ void p0_weight_item(const Args& a, int l, int r, LAS float* scr, int lane) {
;     ...
;             transpose_item(W, FF, gu, DM, k0, n0, (n0 >> 7) * 256 + up * 128 + (n0 & 127), nrm + k0, scr, lane); return; }
.LBB0_1138:
	s_lshl_b32 s0, s24, 6
	s_and_b32 s7, s0, 0xffffff00
	s_and_b64 s[0:1], s[4:5], exec
	s_cselect_b32 s0, 0x80, 0
	s_and_b32 s1, s6, 0x60
	s_or_b32 s0, s7, s0
	ds_write2_b32 v38, v36, v37 offset0:140 offset1:206
	s_or_b32 s0, s0, s1
	s_waitcnt lgkmcnt(0)
	v_or_b32_e32 v42, s0, v5
	ds_read2_b32 v[34:35], v52 offset1:33
	ds_read2_b32 v[204:205], v52 offset0:66 offset1:99
	ds_read2_b32 v[206:207], v52 offset0:132 offset1:165
	ds_read2_b32 v[208:209], v52 offset0:198 offset1:231
	ds_read2_b32 v[210:211], v52 offset0:8 offset1:41
	ds_read2_b32 v[212:213], v52 offset0:74 offset1:107
	ds_read2_b32 v[214:215], v52 offset0:140 offset1:173
	ds_read2_b32 v[216:217], v52 offset0:206 offset1:239
	v_ashrrev_i32_e32 v43, 31, v42
	s_waitcnt lgkmcnt(7)
	v_cvt_pk_bf16_f32 v34, v34, v35
	ds_read2_b32 v[218:219], v52 offset0:16 offset1:49
	v_lshl_add_u64 v[38:39], s[28:29], 1, v[30:31]
	v_lshlrev_b64 v[42:43], 11, v[42:43]
	s_waitcnt lgkmcnt(7)
	v_cvt_pk_bf16_f32 v35, v204, v205
	ds_read2_b32 v[204:205], v52 offset0:82 offset1:115
	v_lshl_add_u64 v[42:43], v[38:39], 0, v[42:43]
	s_waitcnt lgkmcnt(7)
	v_cvt_pk_bf16_f32 v36, v206, v207
	ds_read2_b32 v[206:207], v52 offset0:148 offset1:181
	s_waitcnt lgkmcnt(7)
	v_cvt_pk_bf16_f32 v37, v208, v209
	ds_read2_b32 v[208:209], v52 offset0:214 offset1:247
	global_store_dwordx4 v[42:43], v[34:37], off sc1
	v_or_b32_e32 v42, s0, v53
	v_ashrrev_i32_e32 v43, 31, v42
	s_waitcnt lgkmcnt(7)
	v_cvt_pk_bf16_f32 v34, v210, v211
	ds_read2_b32 v[210:211], v52 offset0:24 offset1:57
	v_lshlrev_b64 v[42:43], 11, v[42:43]
	s_waitcnt lgkmcnt(7)
	v_cvt_pk_bf16_f32 v35, v212, v213
	ds_read2_b32 v[212:213], v52 offset0:90 offset1:123
	v_lshl_add_u64 v[42:43], v[38:39], 0, v[42:43]
	s_waitcnt lgkmcnt(7)
	v_cvt_pk_bf16_f32 v36, v214, v215
	ds_read2_b32 v[214:215], v52 offset0:156 offset1:189
	s_waitcnt lgkmcnt(7)
	v_cvt_pk_bf16_f32 v37, v216, v217
	global_store_dwordx4 v[42:43], v[34:37], off sc1
	v_or_b32_e32 v42, s0, v54
	v_ashrrev_i32_e32 v43, 31, v42
	s_waitcnt lgkmcnt(6)
	v_cvt_pk_bf16_f32 v34, v218, v219
	v_lshlrev_b64 v[42:43], 11, v[42:43]
	s_waitcnt lgkmcnt(5)
	v_cvt_pk_bf16_f32 v35, v204, v205
	v_lshl_add_u64 v[42:43], v[38:39], 0, v[42:43]
	s_waitcnt lgkmcnt(4)
	v_cvt_pk_bf16_f32 v36, v206, v207
	s_waitcnt lgkmcnt(3)
	v_cvt_pk_bf16_f32 v37, v208, v209
	global_store_dwordx4 v[42:43], v[34:37], off sc1
	v_or_b32_e32 v42, s0, v55
	v_ashrrev_i32_e32 v43, 31, v42
	s_waitcnt lgkmcnt(2)
	v_cvt_pk_bf16_f32 v34, v210, v211
	ds_read2_b32 v[40:41], v52 offset0:222 offset1:255
	v_lshlrev_b64 v[42:43], 11, v[42:43]
	s_waitcnt lgkmcnt(2)
	v_cvt_pk_bf16_f32 v35, v212, v213
	v_lshl_add_u64 v[38:39], v[38:39], 0, v[42:43]
	s_waitcnt lgkmcnt(1)
	v_cvt_pk_bf16_f32 v36, v214, v215
	s_waitcnt lgkmcnt(0)
	v_cvt_pk_bf16_f32 v37, v40, v41
	global_store_dwordx4 v[38:39], v[34:37], off sc1
	s_waitcnt lgkmcnt(0)

; #define LAS __attribute__((address_space(3)))
; __device__ __forceinline__ void transpose_item(const float* W, int N, bf16* WT, int K, int k0, int n0, int drow0, const float* gk, LAS float* scr, int lane) {
;     float wv[32];
; #pragma unroll
;     for (int i = 0; i < 32; ++i) wv[i] = W[(size_t)(k0 + 2 * i + (lane >> 5)) * N + n0 + (lane & 31)];
; __device__ __forceinline__ void p0_weight_item(const Args& a, int l, int r, LAS float* scr, int lane) {
;     ...
;         if (r < IT_BIG) { const int kb = r / 32, nb = r % 32; const float* W = a.in[f ? 31 : 4] + (size_t)l * FF * DM;
;             transpose_item(W, DM, dn, FF, 64 * kb, 32 * nb, 32 * nb, nullptr, scr, lane); return; }
.LBB0_1140:
	s_andn2_b64 vcc, exec, s[0:1]
	s_cbranch_vccnz .LBB0_1142
	s_add_i32 s0, s26, 0x2100
	s_and_b32 s1, s0, 0x7fffffc0
	s_add_i32 s0, s35, 0xffffc000
	s_and_b32 s0, s0, 0x3e0
	v_or_b32_e32 v144, s1, v0
	s_lshl_b32 s82, s0, 2
	v_lshl_add_u64 v[34:35], v[32:33], 0, s[82:83]
	v_lshlrev_b64 v[36:37], 12, v[144:145]
	v_lshl_add_u64 v[36:37], v[34:35], 0, v[36:37]
	global_load_dword v38, v[36:37], off nt
	v_or_b32_e32 v36, 2, v144
	v_mov_b32_e32 v37, v145
	v_lshlrev_b64 v[36:37], 12, v[36:37]
	v_lshl_add_u64 v[36:37], v[34:35], 0, v[36:37]
	global_load_dword v39, v[36:37], off nt
	v_or_b32_e32 v36, 4, v144
	v_mov_b32_e32 v37, v145
	v_lshlrev_b64 v[36:37], 12, v[36:37]
	v_lshl_add_u64 v[36:37], v[34:35], 0, v[36:37]
	global_load_dword v40, v[36:37], off nt
	v_or_b32_e32 v36, 6, v144
	v_mov_b32_e32 v37, v145
	v_lshlrev_b64 v[36:37], 12, v[36:37]
	v_lshl_add_u64 v[36:37], v[34:35], 0, v[36:37]
	global_load_dword v41, v[36:37], off nt
	v_or_b32_e32 v36, 8, v144
	v_mov_b32_e32 v37, v145
	v_lshlrev_b64 v[36:37], 12, v[36:37]
	v_lshl_add_u64 v[36:37], v[34:35], 0, v[36:37]
	global_load_dword v42, v[36:37], off nt
	v_or_b32_e32 v36, 10, v144
	v_mov_b32_e32 v37, v145
	v_lshlrev_b64 v[36:37], 12, v[36:37]
	v_lshl_add_u64 v[36:37], v[34:35], 0, v[36:37]
	global_load_dword v43, v[36:37], off nt
	v_or_b32_e32 v36, 12, v144
	v_mov_b32_e32 v37, v145
	v_lshlrev_b64 v[36:37], 12, v[36:37]
	v_lshl_add_u64 v[36:37], v[34:35], 0, v[36:37]
	global_load_dword v44, v[36:37], off nt
	v_or_b32_e32 v36, 14, v144
	v_mov_b32_e32 v37, v145
	v_lshlrev_b64 v[36:37], 12, v[36:37]
	v_lshl_add_u64 v[36:37], v[34:35], 0, v[36:37]
	global_load_dword v45, v[36:37], off nt
	v_or_b32_e32 v36, 16, v144
	v_mov_b32_e32 v37, v145
	v_lshlrev_b64 v[36:37], 12, v[36:37]
	v_lshl_add_u64 v[36:37], v[34:35], 0, v[36:37]
	global_load_dword v46, v[36:37], off nt
	v_or_b32_e32 v36, 18, v144
	v_mov_b32_e32 v37, v145
	v_lshlrev_b64 v[36:37], 12, v[36:37]
	v_lshl_add_u64 v[36:37], v[34:35], 0, v[36:37]
	global_load_dword v47, v[36:37], off nt
	v_or_b32_e32 v36, 20, v144
	v_mov_b32_e32 v37, v145
	v_lshlrev_b64 v[36:37], 12, v[36:37]
	v_lshl_add_u64 v[36:37], v[34:35], 0, v[36:37]
	global_load_dword v48, v[36:37], off nt
	v_or_b32_e32 v36, 22, v144
	v_mov_b32_e32 v37, v145
	v_lshlrev_b64 v[36:37], 12, v[36:37]
	v_lshl_add_u64 v[36:37], v[34:35], 0, v[36:37]
	global_load_dword v49, v[36:37], off nt
	v_or_b32_e32 v36, 24, v144
	v_mov_b32_e32 v37, v145
	v_lshlrev_b64 v[36:37], 12, v[36:37]
	v_lshl_add_u64 v[36:37], v[34:35], 0, v[36:37]
	global_load_dword v50, v[36:37], off nt
	v_or_b32_e32 v36, 26, v144
	v_mov_b32_e32 v37, v145
	v_lshlrev_b64 v[36:37], 12, v[36:37]
	v_lshl_add_u64 v[36:37], v[34:35], 0, v[36:37]
	global_load_dword v51, v[36:37], off nt
	v_or_b32_e32 v36, 28, v144
	v_mov_b32_e32 v37, v145
	v_lshlrev_b64 v[36:37], 12, v[36:37]
	v_lshl_add_u64 v[36:37], v[34:35], 0, v[36:37]
	global_load_dword v69, v[36:37], off nt
	v_or_b32_e32 v36, 30, v144
	v_mov_b32_e32 v37, v145
	v_lshlrev_b64 v[36:37], 12, v[36:37]
	v_lshl_add_u64 v[36:37], v[34:35], 0, v[36:37]
	global_load_dword v70, v[36:37], off nt
	v_or_b32_e32 v36, 32, v144
	v_mov_b32_e32 v37, v145
	v_lshlrev_b64 v[36:37], 12, v[36:37]
	v_lshl_add_u64 v[36:37], v[34:35], 0, v[36:37]
	global_load_dword v71, v[36:37], off nt
	v_or_b32_e32 v36, 34, v144
	v_mov_b32_e32 v37, v145
	v_lshlrev_b64 v[36:37], 12, v[36:37]
	v_lshl_add_u64 v[36:37], v[34:35], 0, v[36:37]
	global_load_dword v72, v[36:37], off nt
	v_or_b32_e32 v36, 36, v144
	v_mov_b32_e32 v37, v145
	v_lshlrev_b64 v[36:37], 12, v[36:37]
	v_lshl_add_u64 v[36:37], v[34:35], 0, v[36:37]
	global_load_dword v73, v[36:37], off nt
	v_or_b32_e32 v36, 38, v144
	v_mov_b32_e32 v37, v145
	v_lshlrev_b64 v[36:37], 12, v[36:37]
	v_lshl_add_u64 v[36:37], v[34:35], 0, v[36:37]
	global_load_dword v74, v[36:37], off nt
	v_or_b32_e32 v36, 40, v144
	v_mov_b32_e32 v37, v145
	v_lshlrev_b64 v[36:37], 12, v[36:37]
	v_lshl_add_u64 v[36:37], v[34:35], 0, v[36:37]
	global_load_dword v75, v[36:37], off nt
	v_or_b32_e32 v36, 42, v144
	v_mov_b32_e32 v37, v145
	v_lshlrev_b64 v[36:37], 12, v[36:37]
	v_lshl_add_u64 v[36:37], v[34:35], 0, v[36:37]
	global_load_dword v76, v[36:37], off nt
	v_or_b32_e32 v36, 44, v144
	v_mov_b32_e32 v37, v145
	v_lshlrev_b64 v[36:37], 12, v[36:37]
	v_lshl_add_u64 v[36:37], v[34:35], 0, v[36:37]
	global_load_dword v77, v[36:37], off nt
	v_or_b32_e32 v36, 46, v144
	v_mov_b32_e32 v37, v145
	v_lshlrev_b64 v[36:37], 12, v[36:37]
	v_lshl_add_u64 v[36:37], v[34:35], 0, v[36:37]
	global_load_dword v78, v[36:37], off nt
	v_or_b32_e32 v36, 48, v144
	v_mov_b32_e32 v37, v145
	v_lshlrev_b64 v[36:37], 12, v[36:37]
	v_lshl_add_u64 v[36:37], v[34:35], 0, v[36:37]
	global_load_dword v79, v[36:37], off nt
	v_or_b32_e32 v36, 50, v144
	v_mov_b32_e32 v37, v145
	v_lshlrev_b64 v[36:37], 12, v[36:37]
	v_lshl_add_u64 v[36:37], v[34:35], 0, v[36:37]
	global_load_dword v80, v[36:37], off nt
	v_or_b32_e32 v36, 52, v144
	v_mov_b32_e32 v37, v145
	v_lshlrev_b64 v[36:37], 12, v[36:37]
	v_lshl_add_u64 v[36:37], v[34:35], 0, v[36:37]
	global_load_dword v81, v[36:37], off nt
	v_or_b32_e32 v36, 54, v144
	v_mov_b32_e32 v37, v145
	v_lshlrev_b64 v[36:37], 12, v[36:37]
	v_lshl_add_u64 v[36:37], v[34:35], 0, v[36:37]
	global_load_dword v82, v[36:37], off nt
	v_or_b32_e32 v36, 56, v144
	v_mov_b32_e32 v37, v145
	v_lshlrev_b64 v[36:37], 12, v[36:37]
	v_lshl_add_u64 v[36:37], v[34:35], 0, v[36:37]
	global_load_dword v83, v[36:37], off nt
	v_or_b32_e32 v36, 58, v144
	v_mov_b32_e32 v37, v145
	v_lshlrev_b64 v[36:37], 12, v[36:37]
	v_lshl_add_u64 v[36:37], v[34:35], 0, v[36:37]
	global_load_dword v84, v[36:37], off nt
	v_or_b32_e32 v36, 60, v144
	v_mov_b32_e32 v37, v145
	v_lshlrev_b64 v[36:37], 12, v[36:37]
	v_lshl_add_u64 v[36:37], v[34:35], 0, v[36:37]
	v_or_b32_e32 v144, 62, v144
	global_load_dword v85, v[36:37], off nt
	v_lshlrev_b64 v[36:37], 12, v[144:145]
	v_lshl_add_u64 v[34:35], v[34:35], 0, v[36:37]
	global_load_dword v34, v[34:35], off nt
	v_add_u32_e32 v35, 0x400, v3
	s_waitcnt vmcnt(0)
; #define LAS __attribute__((address_space(3)))
; __device__ __forceinline__ unsigned pk2(float lo, float hi) { return pg8::cvt_pk_bf16(lo, hi); }
; __device__ __forceinline__ void lds_wait() { asm volatile("s_waitcnt lgkmcnt(0)" ::: "memory"); }
; __device__ __forceinline__ void transpose_item(const float* W, int N, bf16* WT, int K, int k0, int n0, int drow0, const float* gk, LAS float* scr, int lane) {
;     ...
;     for (int i = 0; i < 32; ++i) { const int kk = 2 * i + (lane >> 5); float v = wv[i]; if (gk) v *= gk[kk]; scr[kk * 33 + (lane & 31)] = v; }
;     lds_wait();
;     const int c = lane & 7;
; #pragma unroll
;     for (int j = 0; j < 4; ++j) { const int n = (lane >> 3) + 8 * j; const LAS float* s = scr + (8 * c) * 33 + n;
;         u32x4 o; o.x = pk2(s[0 * 33], s[1 * 33]); o.y = pk2(s[2 * 33], s[3 * 33]); o.z = pk2(s[4 * 33], s[5 * 33]); o.w = pk2(s[6 * 33], s[7 * 33]);
;         *(u32x4*)(WT + (size_t)(drow0 + n) * K + k0 + 8 * c) = o; }
;     lds_wait();
	ds_write2_b32 v3, v38, v39 offset1:66
	ds_write2_b32 v3, v40, v41 offset0:132 offset1:198
	ds_write2_b32 v35, v42, v43 offset0:8 offset1:74
	ds_write2_b32 v35, v44, v45 offset0:140 offset1:206
	v_add_u32_e32 v35, 0x800, v3
	ds_write2_b32 v35, v46, v47 offset0:16 offset1:82
	ds_write2_b32 v35, v48, v49 offset0:148 offset1:214
	v_add_u32_e32 v35, 0xc00, v3
	ds_write2_b32 v35, v50, v51 offset0:24 offset1:90
	ds_write2_b32 v35, v69, v70 offset0:156 offset1:222
	v_add_u32_e32 v35, 0x1000, v3
	ds_write2_b32 v35, v71, v72 offset0:32 offset1:98
	ds_write2_b32 v35, v73, v74 offset0:164 offset1:230
	v_add_u32_e32 v35, 0x1400, v3
	ds_write2_b32 v35, v75, v76 offset0:40 offset1:106
	ds_write2_b32 v35, v77, v78 offset0:172 offset1:238
	v_add_u32_e32 v35, 0x1800, v3
	ds_write2_b32 v35, v79, v80 offset0:48 offset1:114
	ds_write2_b32 v35, v81, v82 offset0:180 offset1:246
	v_add_u32_e32 v35, 0x1c00, v3
	ds_write2_b32 v35, v83, v84 offset0:56 offset1:122
	ds_write2_b32 v35, v85, v34 offset0:188 offset1:254
	s_waitcnt lgkmcnt(0)
	ds_read2_b32 v[34:35], v52 offset1:33
	ds_read2_b32 v[204:205], v52 offset0:66 offset1:99
	ds_read2_b32 v[206:207], v52 offset0:132 offset1:165
	ds_read2_b32 v[40:41], v52 offset0:198 offset1:231
	ds_read2_b32 v[208:209], v52 offset0:8 offset1:41
	ds_read2_b32 v[210:211], v52 offset0:74 offset1:107
	ds_read2_b32 v[212:213], v52 offset0:140 offset1:173
	ds_read2_b32 v[214:215], v52 offset0:16 offset1:49
	s_waitcnt lgkmcnt(7)
	v_cvt_pk_bf16_f32 v34, v34, v35
	ds_read2_b32 v[216:217], v52 offset0:82 offset1:115
	s_waitcnt lgkmcnt(7)
	v_cvt_pk_bf16_f32 v35, v204, v205
	ds_read2_b32 v[204:205], v52 offset0:148 offset1:181
	s_waitcnt lgkmcnt(7)
	v_cvt_pk_bf16_f32 v36, v206, v207
	ds_read2_b32 v[206:207], v52 offset0:24 offset1:57
	s_waitcnt lgkmcnt(7)
	v_cvt_pk_bf16_f32 v37, v40, v41
	v_or_b32_e32 v40, s0, v5
	s_lshl_b32 s82, s1, 1
	v_mul_u32_u24_e32 v40, 0xb00, v40
	v_lshl_add_u64 v[38:39], v[6:7], 0, s[82:83]
	v_lshlrev_b32_e32 v144, 1, v40
	ds_read2_b32 v[218:219], v52 offset0:90 offset1:123
	v_lshl_add_u64 v[40:41], v[38:39], 0, v[144:145]
	global_store_dwordx4 v[40:41], v[34:37], off sc1
	s_waitcnt lgkmcnt(7)
	v_cvt_pk_bf16_f32 v34, v208, v209
	ds_read2_b32 v[40:41], v52 offset0:206 offset1:239
	s_waitcnt lgkmcnt(7)
	v_cvt_pk_bf16_f32 v35, v210, v211
	ds_read2_b32 v[208:209], v52 offset0:156 offset1:189
	s_waitcnt lgkmcnt(7)
	v_cvt_pk_bf16_f32 v36, v212, v213
	s_waitcnt lgkmcnt(1)
	v_cvt_pk_bf16_f32 v37, v40, v41
	v_or_b32_e32 v40, s0, v53
	v_mul_u32_u24_e32 v40, 0xb00, v40
	v_lshlrev_b32_e32 v144, 1, v40
	v_lshl_add_u64 v[40:41], v[38:39], 0, v[144:145]
	global_store_dwordx4 v[40:41], v[34:37], off sc1
	ds_read2_b32 v[40:41], v52 offset0:214 offset1:247
	s_waitcnt lgkmcnt(2)
	v_cvt_pk_bf16_f32 v34, v214, v215
	s_waitcnt lgkmcnt(2)
	v_cvt_pk_bf16_f32 v35, v216, v217
	s_waitcnt lgkmcnt(2)
	v_cvt_pk_bf16_f32 v36, v204, v205
	s_waitcnt lgkmcnt(0)
	v_cvt_pk_bf16_f32 v37, v40, v41
	v_or_b32_e32 v40, s0, v54
	v_mul_u32_u24_e32 v40, 0xb00, v40
	v_lshlrev_b32_e32 v144, 1, v40
	v_lshl_add_u64 v[40:41], v[38:39], 0, v[144:145]
	global_store_dwordx4 v[40:41], v[34:37], off sc1
	ds_read2_b32 v[40:41], v52 offset0:222 offset1:255
	s_waitcnt lgkmcnt(1)
	v_cvt_pk_bf16_f32 v34, v206, v207
	s_waitcnt lgkmcnt(1)
	v_cvt_pk_bf16_f32 v35, v218, v219
	s_waitcnt lgkmcnt(1)
	v_cvt_pk_bf16_f32 v36, v208, v209
	s_waitcnt lgkmcnt(0)
	v_cvt_pk_bf16_f32 v37, v40, v41
	v_or_b32_e32 v40, s0, v55
	v_mul_u32_u24_e32 v40, 0xb00, v40
	v_lshlrev_b32_e32 v144, 1, v40
	v_lshl_add_u64 v[38:39], v[38:39], 0, v[144:145]
	global_store_dwordx4 v[38:39], v[34:37], off sc1
	s_waitcnt lgkmcnt(0)

; __device__ __forceinline__ void p0_weight_item(const Args& a, int l, int r, LAS float* scr, int lane) {
;     ...
;         if (r < 2 * IT_BIG) { const int up = r >= IT_BIG; const int it = r - up * IT_BIG; const int kb = it / 88, nb = it % 88, k0 = 64 * kb, n0 = 32 * nb;
;             const float* W = a.in[(f ? 29 : 2) + up] + (size_t)l * DM * FF;
;             transpose_item(W, FF, gu, DM, k0, n0, (n0 >> 7) * 256 + up * 128 + (n0 & 127), nrm + k0, scr, lane); return; }
;         r -= 2 * IT_BIG;
;         if (r < IT_BIG) { const int kb = r / 32, nb = r % 32; const float* W = a.in[f ? 31 : 4] + (size_t)l * FF * DM;
;             transpose_item(W, DM, dn, FF, 64 * kb, 32 * nb, 32 * nb, nullptr, scr, lane); return; }
;         r -= IT_BIG;
;     }
;     if (r < IT_BIG) {
;         const int kb = r / 88, nb = r % 88, k0 = 64 * kb, n0 = 32 * nb; const int tile = n0 >> 8, c0 = n0 & 255;
;         int drow = n0;
;         if (tile >= 1 && tile <= 4) { const int hh = c0 >> 7, d0 = c0 & 127, bj = d0 >> 6, dd0 = d0 & 63; drow = tile * 256 + bj * 128 + hh * 64 + dd0; }
;         transpose_item(a.in[6] + (size_t)l * DM * IW, IW, (bf16*)(wl + WL_WIN), DM, k0, n0, drow, a.in[5] + (size_t)l * DM + k0, scr, lane); return; }
;     r -= IT_BIG;
;     if (r < IT_OUT) {
;         const int kb = r / 32, nb = r % 32, k0 = 64 * kb;
;         const float* gk = (k0 < 256) ? a.in[17] + (size_t)l * 256 + k0 : (k0 < 768 ? a.in[18] + (size_t)l * 512 + (k0 - 256) : a.in[26] + (size_t)l * 256 + (k0 - 768));
;         transpose_item(a.in[27] + (size_t)l * DM * DM, DM, (bf16*)(wl + WL_WOUT), DM, k0, 32 * nb, 32 * nb, gk, scr, lane); return; }
;     r -= IT_OUT;
;     if (r < IT_GLU) { const int kb = r / 8, nb = r % 8; transpose_item(a.in[15] + (size_t)l * 65536, 256, (bf16*)(wl + WL_GLU), 256, 64 * kb, 32 * nb, 32 * nb, nullptr, scr, lane); return; }
;     r -= IT_GLU;
;     if (r < IT_LW) { const int blk = r >> 1, nb = r & 1; transpose_item(a.in[21] + (size_t)l * 16384 + blk * 4096, 64, (bf16*)(wl + WL_WA) + blk * 4096, 64, 0, 32 * nb, 32 * nb, nullptr, scr, lane); return; }
;     r -= IT_LW;
;     { const int blk = r >> 1, nb = r & 1; transpose_item(a.in[23] + (size_t)l * 16384 + blk * 4096, 64, (bf16*)(wl + WL_WX) + blk * 4096, 64, 0, 32 * nb, 32 * nb, nullptr, scr, lane); }
.LBB0_1662:
	s_add_i32 s39, s27, 0x2100
	s_cmpk_gt_i32 s39, 0xaff
	s_mov_b64 s[0:1], -1
	s_cbranch_scc0 .LBB0_1774
	s_cmpk_gt_u32 s39, 0x107f
	s_cbranch_scc0 .LBB0_1771
	s_cmpk_gt_u32 s39, 0x1b7f
	s_cbranch_scc0 .LBB0_1744
	s_add_i32 s0, s27, 0x1080
	s_cmpk_lt_u32 s0, 0x1080
	s_mov_b64 s[0:1], -1
	s_cbranch_scc1 .LBB0_1741
	s_cmpk_gt_u32 s39, 0x267f
	s_cbranch_scc0 .LBB0_1712
	s_cmpk_gt_u32 s27, 0x77f
	s_cbranch_scc0 .LBB0_1677
	s_cmpk_gt_u32 s27, 0x79f
	s_cbranch_scc0 .LBB0_1674
	s_add_i32 s0, s35, 0xfffb6000
	s_and_b32 s4, s0, 32
	s_cmpk_gt_u32 s27, 0x7a7
	s_mov_b64 s[0:1], -1
	v_lshlrev_b32_e32 v34, 2, v4
	v_or_b32_e32 v39, s4, v5
	v_or_b32_e32 v38, s4, v53
	v_or_b32_e32 v37, s4, v54
	v_or_b32_e32 v36, s4, v55
	s_cbranch_scc0 .LBB0_1671
	s_and_b32 s0, s34, 0x7ffff000
	s_add_i32 s82, s0, 0xffc2c000
	s_lshl_b64 s[0:1], s[82:83], 2
	v_readlane_b32 s5, v253, 55
	s_add_u32 s0, s5, s0
	v_readlane_b32 s5, v253, 56
	s_addc_u32 s1, s5, s1
	s_lshl_b32 s5, s4, 2
	s_add_u32 s0, s0, s5
	s_addc_u32 s1, s1, 0
	v_lshlrev_b32_e32 v144, 2, v2
	v_lshl_add_u64 v[40:41], s[0:1], 0, v[144:145]
	v_mov_b32_e32 v35, v145
	v_lshl_add_u64 v[40:41], v[40:41], 0, v[34:35]
	s_movk_i32 s0, 0x1000
	global_load_dword v35, v[40:41], off nt
	global_load_dword v46, v[40:41], off offset:512 nt
	global_load_dword v47, v[40:41], off offset:1024 nt
	global_load_dword v48, v[40:41], off offset:1536 nt
	global_load_dword v49, v[40:41], off offset:2048 nt
	global_load_dword v50, v[40:41], off offset:2560 nt
	global_load_dword v51, v[40:41], off offset:3072 nt
	global_load_dword v69, v[40:41], off offset:3584 nt
	v_add_co_u32_e32 v42, vcc, s0, v40
	s_movk_i32 s0, 0x2000
	s_nop 0
	v_addc_co_u32_e32 v43, vcc, 0, v41, vcc
	v_add_co_u32_e32 v44, vcc, s0, v40
	s_movk_i32 s0, 0x3000
	s_nop 0
	v_addc_co_u32_e32 v45, vcc, 0, v41, vcc
	global_load_dword v70, v[44:45], off offset:-4096 nt
	global_load_dword v71, v[42:43], off offset:512 nt
	global_load_dword v72, v[42:43], off offset:1024 nt
	global_load_dword v73, v[42:43], off offset:1536 nt
	global_load_dword v74, v[42:43], off offset:2048 nt
	global_load_dword v75, v[42:43], off offset:2560 nt
	global_load_dword v76, v[42:43], off offset:3072 nt
	s_nop 0
	global_load_dword v42, v[42:43], off offset:3584 nt
	s_nop 0
	global_load_dword v43, v[44:45], off nt
	global_load_dword v77, v[44:45], off offset:512 nt
	global_load_dword v78, v[44:45], off offset:1024 nt
	global_load_dword v79, v[44:45], off offset:1536 nt
	global_load_dword v80, v[44:45], off offset:2048 nt
	global_load_dword v81, v[44:45], off offset:2560 nt
	global_load_dword v82, v[44:45], off offset:3072 nt
	s_nop 0
	global_load_dword v44, v[44:45], off offset:3584 nt
	v_add_co_u32_e32 v40, vcc, s0, v40
	v_lshlrev_b32_e32 v144, 7, v39
	s_nop 0
	v_addc_co_u32_e32 v41, vcc, 0, v41, vcc
	global_load_dword v45, v[40:41], off nt
	global_load_dword v83, v[40:41], off offset:512 nt
	global_load_dword v84, v[40:41], off offset:1024 nt
	global_load_dword v85, v[40:41], off offset:1536 nt
	global_load_dword v86, v[40:41], off offset:2048 nt
	global_load_dword v87, v[40:41], off offset:2560 nt
	global_load_dword v88, v[40:41], off offset:3072 nt
	s_nop 0
	global_load_dword v40, v[40:41], off offset:3584 nt
	s_mov_b64 s[0:1], 0
	s_waitcnt vmcnt(0)
	ds_write2_b32 v3, v35, v46 offset1:66
	ds_write2_b32 v3, v47, v48 offset0:132 offset1:198
	v_add_u32_e32 v35, 0x400, v3
	ds_write2_b32 v35, v49, v50 offset0:8 offset1:74
	ds_write2_b32 v35, v51, v69 offset0:140 offset1:206
	v_add_u32_e32 v35, 0x800, v3
	ds_write2_b32 v35, v70, v71 offset0:16 offset1:82
	ds_write2_b32 v35, v72, v73 offset0:148 offset1:214
	v_add_u32_e32 v35, 0xc00, v3
	ds_write2_b32 v35, v74, v75 offset0:24 offset1:90
	ds_write2_b32 v35, v76, v42 offset0:156 offset1:222
	v_add_u32_e32 v35, 0x1000, v3
	ds_write2_b32 v35, v43, v77 offset0:32 offset1:98
	ds_write2_b32 v35, v78, v79 offset0:164 offset1:230
	v_add_u32_e32 v35, 0x1400, v3
	ds_write2_b32 v35, v80, v81 offset0:40 offset1:106
	ds_write2_b32 v35, v82, v44 offset0:172 offset1:238
	v_add_u32_e32 v35, 0x1800, v3
	ds_write2_b32 v35, v45, v83 offset0:48 offset1:114
	ds_write2_b32 v35, v84, v85 offset0:180 offset1:246
	v_add_u32_e32 v35, 0x1c00, v3
	ds_write2_b32 v35, v86, v87 offset0:56 offset1:122
	ds_write2_b32 v35, v88, v40 offset0:188 offset1:254
	s_waitcnt lgkmcnt(0)
	ds_read2_b32 v[40:41], v52 offset1:33
	ds_read2_b32 v[204:205], v52 offset0:66 offset1:99
	ds_read2_b32 v[206:207], v52 offset0:132 offset1:165
	ds_read2_b32 v[208:209], v52 offset0:198 offset1:231
	ds_read2_b32 v[210:211], v52 offset0:8 offset1:41
	ds_read2_b32 v[212:213], v52 offset0:74 offset1:107
	ds_read2_b32 v[214:215], v52 offset0:140 offset1:173
	ds_read2_b32 v[216:217], v52 offset0:206 offset1:239
	s_waitcnt lgkmcnt(7)
	v_cvt_pk_bf16_f32 v40, v40, v41
	ds_read2_b32 v[218:219], v52 offset0:16 offset1:49
	s_waitcnt lgkmcnt(7)
	v_cvt_pk_bf16_f32 v41, v204, v205
	ds_read2_b32 v[204:205], v52 offset0:82 offset1:115
	v_lshl_add_u64 v[44:45], s[82:83], 1, v[10:11]
	s_waitcnt lgkmcnt(7)
	v_cvt_pk_bf16_f32 v42, v206, v207
	ds_read2_b32 v[206:207], v52 offset0:148 offset1:181
	s_waitcnt lgkmcnt(7)
	v_cvt_pk_bf16_f32 v43, v208, v209
	ds_read2_b32 v[208:209], v52 offset0:214 offset1:247
	v_lshl_add_u64 v[46:47], v[44:45], 0, v[144:145]
	global_store_dwordx4 v[46:47], v[40:43], off sc1
	v_lshlrev_b32_e32 v144, 7, v38
	s_waitcnt lgkmcnt(7)
	v_cvt_pk_bf16_f32 v40, v210, v211
	ds_read2_b32 v[210:211], v52 offset0:24 offset1:57
	s_waitcnt lgkmcnt(7)
	v_cvt_pk_bf16_f32 v41, v212, v213
	ds_read2_b32 v[212:213], v52 offset0:90 offset1:123
	s_waitcnt lgkmcnt(7)
	v_cvt_pk_bf16_f32 v42, v214, v215
	ds_read2_b32 v[214:215], v52 offset0:156 offset1:189
	s_waitcnt lgkmcnt(7)
	v_cvt_pk_bf16_f32 v43, v216, v217
	v_lshl_add_u64 v[46:47], v[44:45], 0, v[144:145]
	global_store_dwordx4 v[46:47], v[40:43], off sc1
	v_lshlrev_b32_e32 v144, 7, v37
	s_waitcnt lgkmcnt(6)
	v_cvt_pk_bf16_f32 v40, v218, v219
	s_waitcnt lgkmcnt(5)
	v_cvt_pk_bf16_f32 v41, v204, v205
	s_waitcnt lgkmcnt(4)
	v_cvt_pk_bf16_f32 v42, v206, v207
	s_waitcnt lgkmcnt(3)
	v_cvt_pk_bf16_f32 v43, v208, v209
	v_lshl_add_u64 v[46:47], v[44:45], 0, v[144:145]
	global_store_dwordx4 v[46:47], v[40:43], off sc1
	ds_read2_b32 v[46:47], v52 offset0:222 offset1:255
	v_lshlrev_b32_e32 v144, 7, v36
	s_waitcnt lgkmcnt(3)
	v_cvt_pk_bf16_f32 v40, v210, v211
	s_waitcnt lgkmcnt(2)
	v_cvt_pk_bf16_f32 v41, v212, v213
	v_lshl_add_u64 v[44:45], v[44:45], 0, v[144:145]
	s_waitcnt lgkmcnt(1)
	v_cvt_pk_bf16_f32 v42, v214, v215
	s_waitcnt lgkmcnt(0)
	v_cvt_pk_bf16_f32 v43, v46, v47
	global_store_dwordx4 v[44:45], v[40:43], off sc1
	s_waitcnt lgkmcnt(0)

; #define LAS __attribute__((address_space(3)))
; __device__ __forceinline__ void transpose_item(const float* W, int N, bf16* WT, int K, int k0, int n0, int drow0, const float* gk, LAS float* scr, int lane) {
;     float wv[32];
; #pragma unroll
;     for (int i = 0; i < 32; ++i) wv[i] = W[(size_t)(k0 + 2 * i + (lane >> 5)) * N + n0 + (lane & 31)];
; __device__ __forceinline__ void p0_weight_item(const Args& a, int l, int r, LAS float* scr, int lane) {
;     ...
;     if (r < IT_GLU) { const int kb = r / 8, nb = r % 8; transpose_item(a.in[15] + (size_t)l * 65536, 256, (bf16*)(wl + WL_GLU), 256, 64 * kb, 32 * nb, 32 * nb, nullptr, scr, lane); return; }
.LBB0_1674:
	s_andn2_b64 vcc, exec, s[0:1]
	s_cbranch_vccnz .LBB0_1676
	s_and_b32 s0, s38, 0x3fc0
	s_add_i32 s1, s35, 0xfffb6000
	s_addk_i32 s0, 0xc400
	s_and_b32 s4, s1, 0xe0
	v_or_b32_e32 v144, s0, v0
	s_lshl_b32 s82, s4, 2
	v_lshl_add_u64 v[34:35], v[14:15], 0, s[82:83]
	v_lshlrev_b64 v[36:37], 10, v[144:145]
	v_lshl_add_u64 v[36:37], v[34:35], 0, v[36:37]
	global_load_dword v38, v[36:37], off nt
	v_or_b32_e32 v36, 2, v144
	v_mov_b32_e32 v37, v145
	v_lshlrev_b64 v[36:37], 10, v[36:37]
	v_lshl_add_u64 v[36:37], v[34:35], 0, v[36:37]
	global_load_dword v39, v[36:37], off nt
	v_or_b32_e32 v36, 4, v144
	v_mov_b32_e32 v37, v145
	v_lshlrev_b64 v[36:37], 10, v[36:37]
	v_lshl_add_u64 v[36:37], v[34:35], 0, v[36:37]
	global_load_dword v40, v[36:37], off nt
	v_or_b32_e32 v36, 6, v144
	v_mov_b32_e32 v37, v145
	v_lshlrev_b64 v[36:37], 10, v[36:37]
	v_lshl_add_u64 v[36:37], v[34:35], 0, v[36:37]
	global_load_dword v41, v[36:37], off nt
	v_or_b32_e32 v36, 8, v144
	v_mov_b32_e32 v37, v145
	v_lshlrev_b64 v[36:37], 10, v[36:37]
	v_lshl_add_u64 v[36:37], v[34:35], 0, v[36:37]
	global_load_dword v42, v[36:37], off nt
	v_or_b32_e32 v36, 10, v144
	v_mov_b32_e32 v37, v145
	v_lshlrev_b64 v[36:37], 10, v[36:37]
	v_lshl_add_u64 v[36:37], v[34:35], 0, v[36:37]
	global_load_dword v43, v[36:37], off nt
	v_or_b32_e32 v36, 12, v144
	v_mov_b32_e32 v37, v145
	v_lshlrev_b64 v[36:37], 10, v[36:37]
	v_lshl_add_u64 v[36:37], v[34:35], 0, v[36:37]
	global_load_dword v44, v[36:37], off nt
	v_or_b32_e32 v36, 14, v144
	v_mov_b32_e32 v37, v145
	v_lshlrev_b64 v[36:37], 10, v[36:37]
	v_lshl_add_u64 v[36:37], v[34:35], 0, v[36:37]
	global_load_dword v45, v[36:37], off nt
	v_or_b32_e32 v36, 16, v144
	v_mov_b32_e32 v37, v145
	v_lshlrev_b64 v[36:37], 10, v[36:37]
	v_lshl_add_u64 v[36:37], v[34:35], 0, v[36:37]
	global_load_dword v46, v[36:37], off nt
	v_or_b32_e32 v36, 18, v144
	v_mov_b32_e32 v37, v145
	v_lshlrev_b64 v[36:37], 10, v[36:37]
	v_lshl_add_u64 v[36:37], v[34:35], 0, v[36:37]
	global_load_dword v47, v[36:37], off nt
	v_or_b32_e32 v36, 20, v144
	v_mov_b32_e32 v37, v145
	v_lshlrev_b64 v[36:37], 10, v[36:37]
	v_lshl_add_u64 v[36:37], v[34:35], 0, v[36:37]
	global_load_dword v48, v[36:37], off nt
	v_or_b32_e32 v36, 22, v144
	v_mov_b32_e32 v37, v145
	v_lshlrev_b64 v[36:37], 10, v[36:37]
	v_lshl_add_u64 v[36:37], v[34:35], 0, v[36:37]
	global_load_dword v49, v[36:37], off nt
	v_or_b32_e32 v36, 24, v144
	v_mov_b32_e32 v37, v145
	v_lshlrev_b64 v[36:37], 10, v[36:37]
	v_lshl_add_u64 v[36:37], v[34:35], 0, v[36:37]
	global_load_dword v50, v[36:37], off nt
	v_or_b32_e32 v36, 26, v144
	v_mov_b32_e32 v37, v145
	v_lshlrev_b64 v[36:37], 10, v[36:37]
	v_lshl_add_u64 v[36:37], v[34:35], 0, v[36:37]
	global_load_dword v51, v[36:37], off nt
	v_or_b32_e32 v36, 28, v144
	v_mov_b32_e32 v37, v145
	v_lshlrev_b64 v[36:37], 10, v[36:37]
	v_lshl_add_u64 v[36:37], v[34:35], 0, v[36:37]
	global_load_dword v69, v[36:37], off nt
	v_or_b32_e32 v36, 30, v144
	v_mov_b32_e32 v37, v145
	v_lshlrev_b64 v[36:37], 10, v[36:37]
	v_lshl_add_u64 v[36:37], v[34:35], 0, v[36:37]
	global_load_dword v70, v[36:37], off nt
	v_or_b32_e32 v36, 32, v144
	v_mov_b32_e32 v37, v145
	v_lshlrev_b64 v[36:37], 10, v[36:37]
	v_lshl_add_u64 v[36:37], v[34:35], 0, v[36:37]
	global_load_dword v71, v[36:37], off nt
	v_or_b32_e32 v36, 34, v144
	v_mov_b32_e32 v37, v145
	v_lshlrev_b64 v[36:37], 10, v[36:37]
	v_lshl_add_u64 v[36:37], v[34:35], 0, v[36:37]
	global_load_dword v72, v[36:37], off nt
	v_or_b32_e32 v36, 36, v144
	v_mov_b32_e32 v37, v145
	v_lshlrev_b64 v[36:37], 10, v[36:37]
	v_lshl_add_u64 v[36:37], v[34:35], 0, v[36:37]
	global_load_dword v73, v[36:37], off nt
	v_or_b32_e32 v36, 38, v144
	v_mov_b32_e32 v37, v145
	v_lshlrev_b64 v[36:37], 10, v[36:37]
	v_lshl_add_u64 v[36:37], v[34:35], 0, v[36:37]
	global_load_dword v74, v[36:37], off nt
	v_or_b32_e32 v36, 40, v144
	v_mov_b32_e32 v37, v145
	v_lshlrev_b64 v[36:37], 10, v[36:37]
	v_lshl_add_u64 v[36:37], v[34:35], 0, v[36:37]
	global_load_dword v75, v[36:37], off nt
	v_or_b32_e32 v36, 42, v144
	v_mov_b32_e32 v37, v145
	v_lshlrev_b64 v[36:37], 10, v[36:37]
	v_lshl_add_u64 v[36:37], v[34:35], 0, v[36:37]
	global_load_dword v76, v[36:37], off nt
	v_or_b32_e32 v36, 44, v144
	v_mov_b32_e32 v37, v145
	v_lshlrev_b64 v[36:37], 10, v[36:37]
	v_lshl_add_u64 v[36:37], v[34:35], 0, v[36:37]
	global_load_dword v77, v[36:37], off nt
	v_or_b32_e32 v36, 46, v144
	v_mov_b32_e32 v37, v145
	v_lshlrev_b64 v[36:37], 10, v[36:37]
	v_lshl_add_u64 v[36:37], v[34:35], 0, v[36:37]
	global_load_dword v78, v[36:37], off nt
	v_or_b32_e32 v36, 48, v144
	v_mov_b32_e32 v37, v145
	v_lshlrev_b64 v[36:37], 10, v[36:37]
	v_lshl_add_u64 v[36:37], v[34:35], 0, v[36:37]
	global_load_dword v79, v[36:37], off nt
	v_or_b32_e32 v36, 50, v144
	v_mov_b32_e32 v37, v145
	v_lshlrev_b64 v[36:37], 10, v[36:37]
	v_lshl_add_u64 v[36:37], v[34:35], 0, v[36:37]
	global_load_dword v80, v[36:37], off nt
	v_or_b32_e32 v36, 52, v144
	v_mov_b32_e32 v37, v145
	v_lshlrev_b64 v[36:37], 10, v[36:37]
	v_lshl_add_u64 v[36:37], v[34:35], 0, v[36:37]
	global_load_dword v81, v[36:37], off nt
	v_or_b32_e32 v36, 54, v144
	v_mov_b32_e32 v37, v145
	v_lshlrev_b64 v[36:37], 10, v[36:37]
	v_lshl_add_u64 v[36:37], v[34:35], 0, v[36:37]
	global_load_dword v82, v[36:37], off nt
	v_or_b32_e32 v36, 56, v144
	v_mov_b32_e32 v37, v145
	v_lshlrev_b64 v[36:37], 10, v[36:37]
	v_lshl_add_u64 v[36:37], v[34:35], 0, v[36:37]
	global_load_dword v83, v[36:37], off nt
	v_or_b32_e32 v36, 58, v144
	v_mov_b32_e32 v37, v145
	v_lshlrev_b64 v[36:37], 10, v[36:37]
	v_lshl_add_u64 v[36:37], v[34:35], 0, v[36:37]
	global_load_dword v84, v[36:37], off nt
	v_or_b32_e32 v36, 60, v144
	v_mov_b32_e32 v37, v145
	v_lshlrev_b64 v[36:37], 10, v[36:37]
	v_lshl_add_u64 v[36:37], v[34:35], 0, v[36:37]
	v_or_b32_e32 v144, 62, v144
	global_load_dword v85, v[36:37], off nt
	v_lshlrev_b64 v[36:37], 10, v[144:145]
	v_lshl_add_u64 v[34:35], v[34:35], 0, v[36:37]
	global_load_dword v34, v[34:35], off nt
	v_add_u32_e32 v35, 0x400, v3
	s_waitcnt vmcnt(0)
; #define LAS __attribute__((address_space(3)))
; __device__ __forceinline__ unsigned pk2(float lo, float hi) { return pg8::cvt_pk_bf16(lo, hi); }
; __device__ __forceinline__ void lds_wait() { asm volatile("s_waitcnt lgkmcnt(0)" ::: "memory"); }
; __device__ __forceinline__ void transpose_item(const float* W, int N, bf16* WT, int K, int k0, int n0, int drow0, const float* gk, LAS float* scr, int lane) {
;     ...
;     for (int i = 0; i < 32; ++i) { const int kk = 2 * i + (lane >> 5); float v = wv[i]; if (gk) v *= gk[kk]; scr[kk * 33 + (lane & 31)] = v; }
;     lds_wait();
;     const int c = lane & 7;
; #pragma unroll
;     for (int j = 0; j < 4; ++j) { const int n = (lane >> 3) + 8 * j; const LAS float* s = scr + (8 * c) * 33 + n;
;         u32x4 o; o.x = pk2(s[0 * 33], s[1 * 33]); o.y = pk2(s[2 * 33], s[3 * 33]); o.z = pk2(s[4 * 33], s[5 * 33]); o.w = pk2(s[6 * 33], s[7 * 33]);
;         *(u32x4*)(WT + (size_t)(drow0 + n) * K + k0 + 8 * c) = o; }
;     lds_wait();
	ds_write2_b32 v3, v38, v39 offset1:66
	ds_write2_b32 v3, v40, v41 offset0:132 offset1:198
	ds_write2_b32 v35, v42, v43 offset0:8 offset1:74
	ds_write2_b32 v35, v44, v45 offset0:140 offset1:206
	v_add_u32_e32 v35, 0x800, v3
	ds_write2_b32 v35, v46, v47 offset0:16 offset1:82
	ds_write2_b32 v35, v48, v49 offset0:148 offset1:214
	v_add_u32_e32 v35, 0xc00, v3
	ds_write2_b32 v35, v50, v51 offset0:24 offset1:90
	ds_write2_b32 v35, v69, v70 offset0:156 offset1:222
	v_add_u32_e32 v35, 0x1000, v3
	ds_write2_b32 v35, v71, v72 offset0:32 offset1:98
	ds_write2_b32 v35, v73, v74 offset0:164 offset1:230
	v_add_u32_e32 v35, 0x1400, v3
	ds_write2_b32 v35, v75, v76 offset0:40 offset1:106
	ds_write2_b32 v35, v77, v78 offset0:172 offset1:238
	v_add_u32_e32 v35, 0x1800, v3
	ds_write2_b32 v35, v79, v80 offset0:48 offset1:114
	ds_write2_b32 v35, v81, v82 offset0:180 offset1:246
	v_add_u32_e32 v35, 0x1c00, v3
	ds_write2_b32 v35, v83, v84 offset0:56 offset1:122
	ds_write2_b32 v35, v85, v34 offset0:188 offset1:254
	s_waitcnt lgkmcnt(0)
	ds_read2_b32 v[34:35], v52 offset1:33
	ds_read2_b32 v[204:205], v52 offset0:66 offset1:99
	ds_read2_b32 v[206:207], v52 offset0:132 offset1:165
	ds_read2_b32 v[40:41], v52 offset0:198 offset1:231
	ds_read2_b32 v[208:209], v52 offset0:8 offset1:41
	ds_read2_b32 v[210:211], v52 offset0:74 offset1:107
	ds_read2_b32 v[212:213], v52 offset0:140 offset1:173
	ds_read2_b32 v[214:215], v52 offset0:16 offset1:49
	s_waitcnt lgkmcnt(7)
	v_cvt_pk_bf16_f32 v34, v34, v35
	ds_read2_b32 v[216:217], v52 offset0:82 offset1:115
	s_waitcnt lgkmcnt(7)
	v_cvt_pk_bf16_f32 v35, v204, v205
	ds_read2_b32 v[204:205], v52 offset0:148 offset1:181
	s_waitcnt lgkmcnt(7)
	v_cvt_pk_bf16_f32 v36, v206, v207
	ds_read2_b32 v[206:207], v52 offset0:24 offset1:57
	s_mov_b32 s1, s83
	s_waitcnt lgkmcnt(7)
	v_cvt_pk_bf16_f32 v37, v40, v41
	v_or_b32_e32 v40, s4, v5
	v_lshl_add_u64 v[38:39], s[0:1], 1, v[16:17]
	v_lshlrev_b32_e32 v144, 9, v40
	ds_read2_b32 v[218:219], v52 offset0:90 offset1:123
	v_lshl_add_u64 v[40:41], v[38:39], 0, v[144:145]
	global_store_dwordx4 v[40:41], v[34:37], off sc1
	s_waitcnt lgkmcnt(7)
	v_cvt_pk_bf16_f32 v34, v208, v209
	ds_read2_b32 v[40:41], v52 offset0:206 offset1:239
	s_waitcnt lgkmcnt(7)
	v_cvt_pk_bf16_f32 v35, v210, v211
	ds_read2_b32 v[208:209], v52 offset0:156 offset1:189
	s_waitcnt lgkmcnt(7)
	v_cvt_pk_bf16_f32 v36, v212, v213
	s_waitcnt lgkmcnt(1)
	v_cvt_pk_bf16_f32 v37, v40, v41
	v_or_b32_e32 v40, s4, v53
	v_lshlrev_b32_e32 v144, 9, v40
	v_lshl_add_u64 v[40:41], v[38:39], 0, v[144:145]
	global_store_dwordx4 v[40:41], v[34:37], off sc1
	ds_read2_b32 v[40:41], v52 offset0:214 offset1:247
	s_waitcnt lgkmcnt(2)
	v_cvt_pk_bf16_f32 v34, v214, v215
	s_waitcnt lgkmcnt(2)
	v_cvt_pk_bf16_f32 v35, v216, v217
	s_waitcnt lgkmcnt(2)
	v_cvt_pk_bf16_f32 v36, v204, v205
	s_waitcnt lgkmcnt(0)
	v_cvt_pk_bf16_f32 v37, v40, v41
	v_or_b32_e32 v40, s4, v54
	v_lshlrev_b32_e32 v144, 9, v40
	v_lshl_add_u64 v[40:41], v[38:39], 0, v[144:145]
	global_store_dwordx4 v[40:41], v[34:37], off sc1
	ds_read2_b32 v[40:41], v52 offset0:222 offset1:255
	s_waitcnt lgkmcnt(1)
	v_cvt_pk_bf16_f32 v34, v206, v207
	s_waitcnt lgkmcnt(1)
	v_cvt_pk_bf16_f32 v35, v218, v219
	s_waitcnt lgkmcnt(1)
	v_cvt_pk_bf16_f32 v36, v208, v209
	s_waitcnt lgkmcnt(0)
	v_cvt_pk_bf16_f32 v37, v40, v41
	v_or_b32_e32 v40, s4, v55
	v_lshlrev_b32_e32 v144, 9, v40
	v_lshl_add_u64 v[38:39], v[38:39], 0, v[144:145]
	global_store_dwordx4 v[38:39], v[34:37], off sc1
	s_waitcnt lgkmcnt(0)

; #define LAS __attribute__((address_space(3)))
; __device__ __forceinline__ void transpose_item(const float* W, int N, bf16* WT, int K, int k0, int n0, int drow0, const float* gk, LAS float* scr, int lane) {
;     float wv[32];
; #pragma unroll
;     for (int i = 0; i < 32; ++i) wv[i] = W[(size_t)(k0 + 2 * i + (lane >> 5)) * N + n0 + (lane & 31)];
; __device__ __forceinline__ void p0_weight_item(const Args& a, int l, int r, LAS float* scr, int lane) {
;     ...
;         if (r < IT_BIG) { const int kb = r / 32, nb = r % 32; const float* W = a.in[f ? 31 : 4] + (size_t)l * FF * DM;
;             transpose_item(W, DM, dn, FF, 64 * kb, 32 * nb, 32 * nb, nullptr, scr, lane); return; }
.LBB0_1741:
	s_andn2_b64 vcc, exec, s[0:1]
	s_cbranch_vccnz .LBB0_1743
	s_add_i32 s0, s35, 0xfffd7000
	s_and_b32 s1, s26, 0x7fffffc0
	s_and_b32 s0, s0, 0x3e0
	v_or_b32_e32 v144, s1, v0
	s_lshl_b32 s82, s0, 2
	v_lshl_add_u64 v[34:35], v[26:27], 0, s[82:83]
	v_lshlrev_b64 v[36:37], 12, v[144:145]
	v_lshl_add_u64 v[36:37], v[34:35], 0, v[36:37]
	global_load_dword v38, v[36:37], off nt
	v_or_b32_e32 v36, 2, v144
	v_mov_b32_e32 v37, v145
	v_lshlrev_b64 v[36:37], 12, v[36:37]
	v_lshl_add_u64 v[36:37], v[34:35], 0, v[36:37]
	global_load_dword v39, v[36:37], off nt
	v_or_b32_e32 v36, 4, v144
	v_mov_b32_e32 v37, v145
	v_lshlrev_b64 v[36:37], 12, v[36:37]
	v_lshl_add_u64 v[36:37], v[34:35], 0, v[36:37]
	global_load_dword v40, v[36:37], off nt
	v_or_b32_e32 v36, 6, v144
	v_mov_b32_e32 v37, v145
	v_lshlrev_b64 v[36:37], 12, v[36:37]
	v_lshl_add_u64 v[36:37], v[34:35], 0, v[36:37]
	global_load_dword v41, v[36:37], off nt
	v_or_b32_e32 v36, 8, v144
	v_mov_b32_e32 v37, v145
	v_lshlrev_b64 v[36:37], 12, v[36:37]
	v_lshl_add_u64 v[36:37], v[34:35], 0, v[36:37]
	global_load_dword v42, v[36:37], off nt
	v_or_b32_e32 v36, 10, v144
	v_mov_b32_e32 v37, v145
	v_lshlrev_b64 v[36:37], 12, v[36:37]
	v_lshl_add_u64 v[36:37], v[34:35], 0, v[36:37]
	global_load_dword v43, v[36:37], off nt
	v_or_b32_e32 v36, 12, v144
	v_mov_b32_e32 v37, v145
	v_lshlrev_b64 v[36:37], 12, v[36:37]
	v_lshl_add_u64 v[36:37], v[34:35], 0, v[36:37]
	global_load_dword v44, v[36:37], off nt
	v_or_b32_e32 v36, 14, v144
	v_mov_b32_e32 v37, v145
	v_lshlrev_b64 v[36:37], 12, v[36:37]
	v_lshl_add_u64 v[36:37], v[34:35], 0, v[36:37]
	global_load_dword v45, v[36:37], off nt
	v_or_b32_e32 v36, 16, v144
	v_mov_b32_e32 v37, v145
	v_lshlrev_b64 v[36:37], 12, v[36:37]
	v_lshl_add_u64 v[36:37], v[34:35], 0, v[36:37]
	global_load_dword v46, v[36:37], off nt
	v_or_b32_e32 v36, 18, v144
	v_mov_b32_e32 v37, v145
	v_lshlrev_b64 v[36:37], 12, v[36:37]
	v_lshl_add_u64 v[36:37], v[34:35], 0, v[36:37]
	global_load_dword v47, v[36:37], off nt
	v_or_b32_e32 v36, 20, v144
	v_mov_b32_e32 v37, v145
	v_lshlrev_b64 v[36:37], 12, v[36:37]
	v_lshl_add_u64 v[36:37], v[34:35], 0, v[36:37]
	global_load_dword v48, v[36:37], off nt
	v_or_b32_e32 v36, 22, v144
	v_mov_b32_e32 v37, v145
	v_lshlrev_b64 v[36:37], 12, v[36:37]
	v_lshl_add_u64 v[36:37], v[34:35], 0, v[36:37]
	global_load_dword v49, v[36:37], off nt
	v_or_b32_e32 v36, 24, v144
	v_mov_b32_e32 v37, v145
	v_lshlrev_b64 v[36:37], 12, v[36:37]
	v_lshl_add_u64 v[36:37], v[34:35], 0, v[36:37]
	global_load_dword v50, v[36:37], off nt
	v_or_b32_e32 v36, 26, v144
	v_mov_b32_e32 v37, v145
	v_lshlrev_b64 v[36:37], 12, v[36:37]
	v_lshl_add_u64 v[36:37], v[34:35], 0, v[36:37]
	global_load_dword v51, v[36:37], off nt
	v_or_b32_e32 v36, 28, v144
	v_mov_b32_e32 v37, v145
	v_lshlrev_b64 v[36:37], 12, v[36:37]
	v_lshl_add_u64 v[36:37], v[34:35], 0, v[36:37]
	global_load_dword v69, v[36:37], off nt
	v_or_b32_e32 v36, 30, v144
	v_mov_b32_e32 v37, v145
	v_lshlrev_b64 v[36:37], 12, v[36:37]
	v_lshl_add_u64 v[36:37], v[34:35], 0, v[36:37]
	global_load_dword v70, v[36:37], off nt
	v_or_b32_e32 v36, 32, v144
	v_mov_b32_e32 v37, v145
	v_lshlrev_b64 v[36:37], 12, v[36:37]
	v_lshl_add_u64 v[36:37], v[34:35], 0, v[36:37]
	global_load_dword v71, v[36:37], off nt
	v_or_b32_e32 v36, 34, v144
	v_mov_b32_e32 v37, v145
	v_lshlrev_b64 v[36:37], 12, v[36:37]
	v_lshl_add_u64 v[36:37], v[34:35], 0, v[36:37]
	global_load_dword v72, v[36:37], off nt
	v_or_b32_e32 v36, 36, v144
	v_mov_b32_e32 v37, v145
	v_lshlrev_b64 v[36:37], 12, v[36:37]
	v_lshl_add_u64 v[36:37], v[34:35], 0, v[36:37]
	global_load_dword v73, v[36:37], off nt
	v_or_b32_e32 v36, 38, v144
	v_mov_b32_e32 v37, v145
	v_lshlrev_b64 v[36:37], 12, v[36:37]
	v_lshl_add_u64 v[36:37], v[34:35], 0, v[36:37]
	global_load_dword v74, v[36:37], off nt
	v_or_b32_e32 v36, 40, v144
	v_mov_b32_e32 v37, v145
	v_lshlrev_b64 v[36:37], 12, v[36:37]
	v_lshl_add_u64 v[36:37], v[34:35], 0, v[36:37]
	global_load_dword v75, v[36:37], off nt
	v_or_b32_e32 v36, 42, v144
	v_mov_b32_e32 v37, v145
	v_lshlrev_b64 v[36:37], 12, v[36:37]
	v_lshl_add_u64 v[36:37], v[34:35], 0, v[36:37]
	global_load_dword v76, v[36:37], off nt
	v_or_b32_e32 v36, 44, v144
	v_mov_b32_e32 v37, v145
	v_lshlrev_b64 v[36:37], 12, v[36:37]
	v_lshl_add_u64 v[36:37], v[34:35], 0, v[36:37]
	global_load_dword v77, v[36:37], off nt
	v_or_b32_e32 v36, 46, v144
	v_mov_b32_e32 v37, v145
	v_lshlrev_b64 v[36:37], 12, v[36:37]
	v_lshl_add_u64 v[36:37], v[34:35], 0, v[36:37]
	global_load_dword v78, v[36:37], off nt
	v_or_b32_e32 v36, 48, v144
	v_mov_b32_e32 v37, v145
	v_lshlrev_b64 v[36:37], 12, v[36:37]
	v_lshl_add_u64 v[36:37], v[34:35], 0, v[36:37]
	global_load_dword v79, v[36:37], off nt
	v_or_b32_e32 v36, 50, v144
	v_mov_b32_e32 v37, v145
	v_lshlrev_b64 v[36:37], 12, v[36:37]
	v_lshl_add_u64 v[36:37], v[34:35], 0, v[36:37]
	global_load_dword v80, v[36:37], off nt
	v_or_b32_e32 v36, 52, v144
	v_mov_b32_e32 v37, v145
	v_lshlrev_b64 v[36:37], 12, v[36:37]
	v_lshl_add_u64 v[36:37], v[34:35], 0, v[36:37]
	global_load_dword v81, v[36:37], off nt
	v_or_b32_e32 v36, 54, v144
	v_mov_b32_e32 v37, v145
	v_lshlrev_b64 v[36:37], 12, v[36:37]
	v_lshl_add_u64 v[36:37], v[34:35], 0, v[36:37]
	global_load_dword v82, v[36:37], off nt
	v_or_b32_e32 v36, 56, v144
	v_mov_b32_e32 v37, v145
	v_lshlrev_b64 v[36:37], 12, v[36:37]
	v_lshl_add_u64 v[36:37], v[34:35], 0, v[36:37]
	global_load_dword v83, v[36:37], off nt
	v_or_b32_e32 v36, 58, v144
	v_mov_b32_e32 v37, v145
	v_lshlrev_b64 v[36:37], 12, v[36:37]
	v_lshl_add_u64 v[36:37], v[34:35], 0, v[36:37]
	global_load_dword v84, v[36:37], off nt
	v_or_b32_e32 v36, 60, v144
	v_mov_b32_e32 v37, v145
	v_lshlrev_b64 v[36:37], 12, v[36:37]
	v_lshl_add_u64 v[36:37], v[34:35], 0, v[36:37]
	v_or_b32_e32 v144, 62, v144
	global_load_dword v85, v[36:37], off nt
	v_lshlrev_b64 v[36:37], 12, v[144:145]
	v_lshl_add_u64 v[34:35], v[34:35], 0, v[36:37]
	global_load_dword v34, v[34:35], off nt
	v_add_u32_e32 v35, 0x400, v3
	s_waitcnt vmcnt(0)
; #define LAS __attribute__((address_space(3)))
; __device__ __forceinline__ unsigned pk2(float lo, float hi) { return pg8::cvt_pk_bf16(lo, hi); }
; __device__ __forceinline__ void lds_wait() { asm volatile("s_waitcnt lgkmcnt(0)" ::: "memory"); }
; __device__ __forceinline__ void transpose_item(const float* W, int N, bf16* WT, int K, int k0, int n0, int drow0, const float* gk, LAS float* scr, int lane) {
;     ...
;     for (int i = 0; i < 32; ++i) { const int kk = 2 * i + (lane >> 5); float v = wv[i]; if (gk) v *= gk[kk]; scr[kk * 33 + (lane & 31)] = v; }
;     lds_wait();
;     const int c = lane & 7;
; #pragma unroll
;     for (int j = 0; j < 4; ++j) { const int n = (lane >> 3) + 8 * j; const LAS float* s = scr + (8 * c) * 33 + n;
;         u32x4 o; o.x = pk2(s[0 * 33], s[1 * 33]); o.y = pk2(s[2 * 33], s[3 * 33]); o.z = pk2(s[4 * 33], s[5 * 33]); o.w = pk2(s[6 * 33], s[7 * 33]);
;         *(u32x4*)(WT + (size_t)(drow0 + n) * K + k0 + 8 * c) = o; }
	ds_write2_b32 v3, v38, v39 offset1:66
	ds_write2_b32 v3, v40, v41 offset0:132 offset1:198
	ds_write2_b32 v35, v42, v43 offset0:8 offset1:74
	ds_write2_b32 v35, v44, v45 offset0:140 offset1:206
	v_add_u32_e32 v35, 0x800, v3
	ds_write2_b32 v35, v46, v47 offset0:16 offset1:82
	ds_write2_b32 v35, v48, v49 offset0:148 offset1:214
	v_add_u32_e32 v35, 0xc00, v3
	ds_write2_b32 v35, v50, v51 offset0:24 offset1:90
	ds_write2_b32 v35, v69, v70 offset0:156 offset1:222
	v_add_u32_e32 v35, 0x1000, v3
	ds_write2_b32 v35, v71, v72 offset0:32 offset1:98
	ds_write2_b32 v35, v73, v74 offset0:164 offset1:230
	v_add_u32_e32 v35, 0x1400, v3
	ds_write2_b32 v35, v75, v76 offset0:40 offset1:106
	ds_write2_b32 v35, v77, v78 offset0:172 offset1:238
	v_add_u32_e32 v35, 0x1800, v3
	ds_write2_b32 v35, v79, v80 offset0:48 offset1:114
	ds_write2_b32 v35, v81, v82 offset0:180 offset1:246
	v_add_u32_e32 v35, 0x1c00, v3
	ds_write2_b32 v35, v83, v84 offset0:56 offset1:122
	ds_write2_b32 v35, v85, v34 offset0:188 offset1:254
	s_waitcnt lgkmcnt(0)
	ds_read2_b32 v[34:35], v52 offset1:33
	ds_read2_b32 v[204:205], v52 offset0:66 offset1:99
	ds_read2_b32 v[206:207], v52 offset0:132 offset1:165
	ds_read2_b32 v[40:41], v52 offset0:198 offset1:231
	ds_read2_b32 v[208:209], v52 offset0:8 offset1:41
	ds_read2_b32 v[210:211], v52 offset0:74 offset1:107
	ds_read2_b32 v[212:213], v52 offset0:140 offset1:173
	ds_read2_b32 v[214:215], v52 offset0:16 offset1:49
	s_waitcnt lgkmcnt(7)
	v_cvt_pk_bf16_f32 v34, v34, v35
	ds_read2_b32 v[216:217], v52 offset0:82 offset1:115
	s_waitcnt lgkmcnt(7)
	v_cvt_pk_bf16_f32 v35, v204, v205
	ds_read2_b32 v[204:205], v52 offset0:148 offset1:181
	s_waitcnt lgkmcnt(7)
	v_cvt_pk_bf16_f32 v36, v206, v207
	ds_read2_b32 v[206:207], v52 offset0:24 offset1:57
	s_waitcnt lgkmcnt(7)
	v_cvt_pk_bf16_f32 v37, v40, v41
	v_or_b32_e32 v40, s0, v5
	s_lshl_b32 s82, s1, 1
	v_mul_u32_u24_e32 v40, 0xb00, v40
	v_lshl_add_u64 v[38:39], v[28:29], 0, s[82:83]
	v_lshlrev_b32_e32 v144, 1, v40
	ds_read2_b32 v[218:219], v52 offset0:90 offset1:123
	v_lshl_add_u64 v[40:41], v[38:39], 0, v[144:145]
	global_store_dwordx4 v[40:41], v[34:37], off sc1
	s_waitcnt lgkmcnt(7)
	v_cvt_pk_bf16_f32 v34, v208, v209
	ds_read2_b32 v[40:41], v52 offset0:206 offset1:239
	s_waitcnt lgkmcnt(7)
	v_cvt_pk_bf16_f32 v35, v210, v211
	ds_read2_b32 v[208:209], v52 offset0:156 offset1:189
	s_waitcnt lgkmcnt(7)
	v_cvt_pk_bf16_f32 v36, v212, v213
	s_waitcnt lgkmcnt(1)
	v_cvt_pk_bf16_f32 v37, v40, v41
	v_or_b32_e32 v40, s0, v53
	v_mul_u32_u24_e32 v40, 0xb00, v40
	v_lshlrev_b32_e32 v144, 1, v40
	v_lshl_add_u64 v[40:41], v[38:39], 0, v[144:145]
	global_store_dwordx4 v[40:41], v[34:37], off sc1
	ds_read2_b32 v[40:41], v52 offset0:214 offset1:247
	s_waitcnt lgkmcnt(2)
	v_cvt_pk_bf16_f32 v34, v214, v215
	s_waitcnt lgkmcnt(2)
	v_cvt_pk_bf16_f32 v35, v216, v217
	s_waitcnt lgkmcnt(2)
	v_cvt_pk_bf16_f32 v36, v204, v205
	s_waitcnt lgkmcnt(0)
	v_cvt_pk_bf16_f32 v37, v40, v41
	v_or_b32_e32 v40, s0, v54
	v_mul_u32_u24_e32 v40, 0xb00, v40
	v_lshlrev_b32_e32 v144, 1, v40
	v_lshl_add_u64 v[40:41], v[38:39], 0, v[144:145]
	global_store_dwordx4 v[40:41], v[34:37], off sc1
	ds_read2_b32 v[40:41], v52 offset0:222 offset1:255
	s_waitcnt lgkmcnt(1)
	v_cvt_pk_bf16_f32 v34, v206, v207
	s_waitcnt lgkmcnt(1)
	v_cvt_pk_bf16_f32 v35, v218, v219
	s_waitcnt lgkmcnt(1)
	v_cvt_pk_bf16_f32 v36, v208, v209
	s_waitcnt lgkmcnt(0)
	v_cvt_pk_bf16_f32 v37, v40, v41
	v_or_b32_e32 v40, s0, v55
	v_mul_u32_u24_e32 v40, 0xb00, v40
	v_lshlrev_b32_e32 v144, 1, v40
	v_lshl_add_u64 v[38:39], v[38:39], 0, v[144:145]
	global_store_dwordx4 v[38:39], v[34:37], off sc1
	s_waitcnt lgkmcnt(0)

; __device__ __forceinline__ void lds_wait() { asm volatile("s_waitcnt lgkmcnt(0)" ::: "memory"); }
; __device__ __forceinline__ void transpose_item(const float* W, int N, bf16* WT, int K, int k0, int n0, int drow0, const float* gk, LAS float* scr, int lane) {
;     ...
;     for (int i = 0; i < 32; ++i) wv[i] = W[(size_t)(k0 + 2 * i + (lane >> 5)) * N + n0 + (lane & 31)];
; #pragma unroll
;     for (int i = 0; i < 32; ++i) { const int kk = 2 * i + (lane >> 5); float v = wv[i]; if (gk) v *= gk[kk]; scr[kk * 33 + (lane & 31)] = v; }
;     lds_wait();
.LBB0_1771:
	s_andn2_b64 vcc, exec, s[0:1]
	s_cbranch_vccnz .LBB0_1773
	s_add_i32 s0, s26, 0x2100
	s_and_b32 s1, s0, 0x7fffffc0
	s_add_i32 s0, s35, 0xffff8000
	s_and_b32 s0, s0, 0x3e0
	v_or_b32_e32 v144, s1, v0
	s_lshl_b32 s82, s0, 2
	v_lshl_add_u64 v[34:35], v[32:33], 0, s[82:83]
	v_lshlrev_b64 v[36:37], 12, v[144:145]
	v_lshl_add_u64 v[36:37], v[34:35], 0, v[36:37]
	global_load_dword v38, v[36:37], off nt
	v_or_b32_e32 v36, 2, v144
	v_mov_b32_e32 v37, v145
	v_lshlrev_b64 v[36:37], 12, v[36:37]
	v_lshl_add_u64 v[36:37], v[34:35], 0, v[36:37]
	global_load_dword v39, v[36:37], off nt
	v_or_b32_e32 v36, 4, v144
	v_mov_b32_e32 v37, v145
	v_lshlrev_b64 v[36:37], 12, v[36:37]
	v_lshl_add_u64 v[36:37], v[34:35], 0, v[36:37]
	global_load_dword v40, v[36:37], off nt
	v_or_b32_e32 v36, 6, v144
	v_mov_b32_e32 v37, v145
	v_lshlrev_b64 v[36:37], 12, v[36:37]
	v_lshl_add_u64 v[36:37], v[34:35], 0, v[36:37]
	global_load_dword v41, v[36:37], off nt
	v_or_b32_e32 v36, 8, v144
	v_mov_b32_e32 v37, v145
	v_lshlrev_b64 v[36:37], 12, v[36:37]
	v_lshl_add_u64 v[36:37], v[34:35], 0, v[36:37]
	global_load_dword v42, v[36:37], off nt
	v_or_b32_e32 v36, 10, v144
	v_mov_b32_e32 v37, v145
	v_lshlrev_b64 v[36:37], 12, v[36:37]
	v_lshl_add_u64 v[36:37], v[34:35], 0, v[36:37]
	global_load_dword v43, v[36:37], off nt
	v_or_b32_e32 v36, 12, v144
	v_mov_b32_e32 v37, v145
	v_lshlrev_b64 v[36:37], 12, v[36:37]
	v_lshl_add_u64 v[36:37], v[34:35], 0, v[36:37]
	global_load_dword v44, v[36:37], off nt
	v_or_b32_e32 v36, 14, v144
	v_mov_b32_e32 v37, v145
	v_lshlrev_b64 v[36:37], 12, v[36:37]
	v_lshl_add_u64 v[36:37], v[34:35], 0, v[36:37]
	global_load_dword v45, v[36:37], off nt
	v_or_b32_e32 v36, 16, v144
	v_mov_b32_e32 v37, v145
	v_lshlrev_b64 v[36:37], 12, v[36:37]
	v_lshl_add_u64 v[36:37], v[34:35], 0, v[36:37]
	global_load_dword v46, v[36:37], off nt
	v_or_b32_e32 v36, 18, v144
	v_mov_b32_e32 v37, v145
	v_lshlrev_b64 v[36:37], 12, v[36:37]
	v_lshl_add_u64 v[36:37], v[34:35], 0, v[36:37]
	global_load_dword v47, v[36:37], off nt
	v_or_b32_e32 v36, 20, v144
	v_mov_b32_e32 v37, v145
	v_lshlrev_b64 v[36:37], 12, v[36:37]
	v_lshl_add_u64 v[36:37], v[34:35], 0, v[36:37]
	global_load_dword v48, v[36:37], off nt
	v_or_b32_e32 v36, 22, v144
	v_mov_b32_e32 v37, v145
	v_lshlrev_b64 v[36:37], 12, v[36:37]
	v_lshl_add_u64 v[36:37], v[34:35], 0, v[36:37]
	global_load_dword v49, v[36:37], off nt
	v_or_b32_e32 v36, 24, v144
	v_mov_b32_e32 v37, v145
	v_lshlrev_b64 v[36:37], 12, v[36:37]
	v_lshl_add_u64 v[36:37], v[34:35], 0, v[36:37]
	global_load_dword v50, v[36:37], off nt
	v_or_b32_e32 v36, 26, v144
	v_mov_b32_e32 v37, v145
	v_lshlrev_b64 v[36:37], 12, v[36:37]
	v_lshl_add_u64 v[36:37], v[34:35], 0, v[36:37]
	global_load_dword v51, v[36:37], off nt
	v_or_b32_e32 v36, 28, v144
	v_mov_b32_e32 v37, v145
	v_lshlrev_b64 v[36:37], 12, v[36:37]
	v_lshl_add_u64 v[36:37], v[34:35], 0, v[36:37]
	global_load_dword v69, v[36:37], off nt
	v_or_b32_e32 v36, 30, v144
	v_mov_b32_e32 v37, v145
	v_lshlrev_b64 v[36:37], 12, v[36:37]
	v_lshl_add_u64 v[36:37], v[34:35], 0, v[36:37]
	global_load_dword v70, v[36:37], off nt
	v_or_b32_e32 v36, 32, v144
	v_mov_b32_e32 v37, v145
	v_lshlrev_b64 v[36:37], 12, v[36:37]
	v_lshl_add_u64 v[36:37], v[34:35], 0, v[36:37]
	global_load_dword v71, v[36:37], off nt
	v_or_b32_e32 v36, 34, v144
	v_mov_b32_e32 v37, v145
	v_lshlrev_b64 v[36:37], 12, v[36:37]
	v_lshl_add_u64 v[36:37], v[34:35], 0, v[36:37]
	global_load_dword v72, v[36:37], off nt
	v_or_b32_e32 v36, 36, v144
	v_mov_b32_e32 v37, v145
	v_lshlrev_b64 v[36:37], 12, v[36:37]
	v_lshl_add_u64 v[36:37], v[34:35], 0, v[36:37]
	global_load_dword v73, v[36:37], off nt
	v_or_b32_e32 v36, 38, v144
	v_mov_b32_e32 v37, v145
	v_lshlrev_b64 v[36:37], 12, v[36:37]
	v_lshl_add_u64 v[36:37], v[34:35], 0, v[36:37]
	global_load_dword v74, v[36:37], off nt
	v_or_b32_e32 v36, 40, v144
	v_mov_b32_e32 v37, v145
	v_lshlrev_b64 v[36:37], 12, v[36:37]
	v_lshl_add_u64 v[36:37], v[34:35], 0, v[36:37]
	global_load_dword v75, v[36:37], off nt
	v_or_b32_e32 v36, 42, v144
	v_mov_b32_e32 v37, v145
	v_lshlrev_b64 v[36:37], 12, v[36:37]
	v_lshl_add_u64 v[36:37], v[34:35], 0, v[36:37]
	global_load_dword v76, v[36:37], off nt
	v_or_b32_e32 v36, 44, v144
	v_mov_b32_e32 v37, v145
	v_lshlrev_b64 v[36:37], 12, v[36:37]
	v_lshl_add_u64 v[36:37], v[34:35], 0, v[36:37]
	global_load_dword v77, v[36:37], off nt
	v_or_b32_e32 v36, 46, v144
	v_mov_b32_e32 v37, v145
	v_lshlrev_b64 v[36:37], 12, v[36:37]
	v_lshl_add_u64 v[36:37], v[34:35], 0, v[36:37]
	global_load_dword v78, v[36:37], off nt
	v_or_b32_e32 v36, 48, v144
	v_mov_b32_e32 v37, v145
	v_lshlrev_b64 v[36:37], 12, v[36:37]
	v_lshl_add_u64 v[36:37], v[34:35], 0, v[36:37]
	global_load_dword v79, v[36:37], off nt
	v_or_b32_e32 v36, 50, v144
	v_mov_b32_e32 v37, v145
	v_lshlrev_b64 v[36:37], 12, v[36:37]
	v_lshl_add_u64 v[36:37], v[34:35], 0, v[36:37]
	global_load_dword v80, v[36:37], off nt
	v_or_b32_e32 v36, 52, v144
	v_mov_b32_e32 v37, v145
	v_lshlrev_b64 v[36:37], 12, v[36:37]
	v_lshl_add_u64 v[36:37], v[34:35], 0, v[36:37]
	global_load_dword v81, v[36:37], off nt
	v_or_b32_e32 v36, 54, v144
	v_mov_b32_e32 v37, v145
	v_lshlrev_b64 v[36:37], 12, v[36:37]
	v_lshl_add_u64 v[36:37], v[34:35], 0, v[36:37]
	global_load_dword v82, v[36:37], off nt
	v_or_b32_e32 v36, 56, v144
	v_mov_b32_e32 v37, v145
	v_lshlrev_b64 v[36:37], 12, v[36:37]
	v_lshl_add_u64 v[36:37], v[34:35], 0, v[36:37]
	global_load_dword v83, v[36:37], off nt
	v_or_b32_e32 v36, 58, v144
	v_mov_b32_e32 v37, v145
	v_lshlrev_b64 v[36:37], 12, v[36:37]
	v_lshl_add_u64 v[36:37], v[34:35], 0, v[36:37]
	global_load_dword v84, v[36:37], off nt
	v_or_b32_e32 v36, 60, v144
	v_mov_b32_e32 v37, v145
	v_lshlrev_b64 v[36:37], 12, v[36:37]
	v_lshl_add_u64 v[36:37], v[34:35], 0, v[36:37]
	v_or_b32_e32 v144, 62, v144
	global_load_dword v85, v[36:37], off nt
	v_lshlrev_b64 v[36:37], 12, v[144:145]
	v_lshl_add_u64 v[34:35], v[34:35], 0, v[36:37]
	global_load_dword v34, v[34:35], off nt
	v_add_u32_e32 v35, 0x400, v3
	s_waitcnt vmcnt(0)
; #define LAS __attribute__((address_space(3)))
; __device__ __forceinline__ unsigned pk2(float lo, float hi) { return pg8::cvt_pk_bf16(lo, hi); }
; __device__ __forceinline__ void lds_wait() { asm volatile("s_waitcnt lgkmcnt(0)" ::: "memory"); }
; __device__ __forceinline__ void transpose_item(const float* W, int N, bf16* WT, int K, int k0, int n0, int drow0, const float* gk, LAS float* scr, int lane) {
;     ...
;     for (int i = 0; i < 32; ++i) { const int kk = 2 * i + (lane >> 5); float v = wv[i]; if (gk) v *= gk[kk]; scr[kk * 33 + (lane & 31)] = v; }
;     lds_wait();
;     const int c = lane & 7;
; #pragma unroll
;     for (int j = 0; j < 4; ++j) { const int n = (lane >> 3) + 8 * j; const LAS float* s = scr + (8 * c) * 33 + n;
;         u32x4 o; o.x = pk2(s[0 * 33], s[1 * 33]); o.y = pk2(s[2 * 33], s[3 * 33]); o.z = pk2(s[4 * 33], s[5 * 33]); o.w = pk2(s[6 * 33], s[7 * 33]);
;         *(u32x4*)(WT + (size_t)(drow0 + n) * K + k0 + 8 * c) = o; }
	ds_write2_b32 v3, v38, v39 offset1:66
	ds_write2_b32 v3, v40, v41 offset0:132 offset1:198
	ds_write2_b32 v35, v42, v43 offset0:8 offset1:74
	ds_write2_b32 v35, v44, v45 offset0:140 offset1:206
	v_add_u32_e32 v35, 0x800, v3
	ds_write2_b32 v35, v46, v47 offset0:16 offset1:82
	ds_write2_b32 v35, v48, v49 offset0:148 offset1:214
	v_add_u32_e32 v35, 0xc00, v3
	ds_write2_b32 v35, v50, v51 offset0:24 offset1:90
	ds_write2_b32 v35, v69, v70 offset0:156 offset1:222
	v_add_u32_e32 v35, 0x1000, v3
	ds_write2_b32 v35, v71, v72 offset0:32 offset1:98
	ds_write2_b32 v35, v73, v74 offset0:164 offset1:230
	v_add_u32_e32 v35, 0x1400, v3
	ds_write2_b32 v35, v75, v76 offset0:40 offset1:106
	ds_write2_b32 v35, v77, v78 offset0:172 offset1:238
	v_add_u32_e32 v35, 0x1800, v3
	ds_write2_b32 v35, v79, v80 offset0:48 offset1:114
	ds_write2_b32 v35, v81, v82 offset0:180 offset1:246
	v_add_u32_e32 v35, 0x1c00, v3
	ds_write2_b32 v35, v83, v84 offset0:56 offset1:122
	ds_write2_b32 v35, v85, v34 offset0:188 offset1:254
	s_waitcnt lgkmcnt(0)
	ds_read2_b32 v[34:35], v52 offset1:33
	ds_read2_b32 v[204:205], v52 offset0:66 offset1:99
	ds_read2_b32 v[206:207], v52 offset0:132 offset1:165
	ds_read2_b32 v[40:41], v52 offset0:198 offset1:231
	ds_read2_b32 v[208:209], v52 offset0:8 offset1:41
	ds_read2_b32 v[210:211], v52 offset0:74 offset1:107
	ds_read2_b32 v[212:213], v52 offset0:140 offset1:173
	ds_read2_b32 v[214:215], v52 offset0:16 offset1:49
	s_waitcnt lgkmcnt(7)
	v_cvt_pk_bf16_f32 v34, v34, v35
	ds_read2_b32 v[216:217], v52 offset0:82 offset1:115
	s_waitcnt lgkmcnt(7)
	v_cvt_pk_bf16_f32 v35, v204, v205
	ds_read2_b32 v[204:205], v52 offset0:148 offset1:181
	s_waitcnt lgkmcnt(7)
	v_cvt_pk_bf16_f32 v36, v206, v207
	ds_read2_b32 v[206:207], v52 offset0:24 offset1:57
	s_waitcnt lgkmcnt(7)
	v_cvt_pk_bf16_f32 v37, v40, v41
	v_or_b32_e32 v40, s0, v5
	s_lshl_b32 s82, s1, 1
	v_mul_u32_u24_e32 v40, 0xb00, v40
	v_lshl_add_u64 v[38:39], v[6:7], 0, s[82:83]
	v_lshlrev_b32_e32 v144, 1, v40
	ds_read2_b32 v[218:219], v52 offset0:90 offset1:123
	v_lshl_add_u64 v[40:41], v[38:39], 0, v[144:145]
	global_store_dwordx4 v[40:41], v[34:37], off sc1
	s_waitcnt lgkmcnt(7)
	v_cvt_pk_bf16_f32 v34, v208, v209
	ds_read2_b32 v[40:41], v52 offset0:206 offset1:239
	s_waitcnt lgkmcnt(7)
	v_cvt_pk_bf16_f32 v35, v210, v211
	ds_read2_b32 v[208:209], v52 offset0:156 offset1:189
	s_waitcnt lgkmcnt(7)
	v_cvt_pk_bf16_f32 v36, v212, v213
	s_waitcnt lgkmcnt(1)
	v_cvt_pk_bf16_f32 v37, v40, v41
	v_or_b32_e32 v40, s0, v53
	v_mul_u32_u24_e32 v40, 0xb00, v40
	v_lshlrev_b32_e32 v144, 1, v40
	v_lshl_add_u64 v[40:41], v[38:39], 0, v[144:145]
	global_store_dwordx4 v[40:41], v[34:37], off sc1
	ds_read2_b32 v[40:41], v52 offset0:214 offset1:247
	s_waitcnt lgkmcnt(2)
	v_cvt_pk_bf16_f32 v34, v214, v215
	s_waitcnt lgkmcnt(2)
	v_cvt_pk_bf16_f32 v35, v216, v217
	s_waitcnt lgkmcnt(2)
	v_cvt_pk_bf16_f32 v36, v204, v205
	s_waitcnt lgkmcnt(0)
	v_cvt_pk_bf16_f32 v37, v40, v41
	v_or_b32_e32 v40, s0, v54
	v_mul_u32_u24_e32 v40, 0xb00, v40
	v_lshlrev_b32_e32 v144, 1, v40
	v_lshl_add_u64 v[40:41], v[38:39], 0, v[144:145]
	global_store_dwordx4 v[40:41], v[34:37], off sc1
	ds_read2_b32 v[40:41], v52 offset0:222 offset1:255
	s_waitcnt lgkmcnt(1)
	v_cvt_pk_bf16_f32 v34, v206, v207
	s_waitcnt lgkmcnt(1)
	v_cvt_pk_bf16_f32 v35, v218, v219
	s_waitcnt lgkmcnt(1)
	v_cvt_pk_bf16_f32 v36, v208, v209
	s_waitcnt lgkmcnt(0)
	v_cvt_pk_bf16_f32 v37, v40, v41
	v_or_b32_e32 v40, s0, v55
	v_mul_u32_u24_e32 v40, 0xb00, v40
	v_lshlrev_b32_e32 v144, 1, v40
	v_lshl_add_u64 v[38:39], v[38:39], 0, v[144:145]
	global_store_dwordx4 v[38:39], v[34:37], off sc1
	s_waitcnt lgkmcnt(0)
